# P3 indexer: relu canonicalize folded, packed single wave-sum per bisection step, SALU bit countdown, counters initialised by first compare group
# speedup vs baseline: 1.0161x; 1.0161x over previous
.LBB0_585:
	s_barrier
	s_waitcnt vmcnt(1)
	ds_write_b128 v117, v[8:11]
	s_waitcnt lgkmcnt(0)
	s_barrier
	ds_read_b128 v[104:107], v214
	ds_read_b128 v[100:103], v214 offset:64
	ds_read_b128 v[96:99], v214 offset:128
	ds_read_b128 v[92:95], v214 offset:192
	ds_read_b128 v[88:91], v214 offset:256
	ds_read_b128 v[84:87], v214 offset:320
	ds_read_b128 v[80:83], v214 offset:384
	ds_read_b128 v[76:79], v214 offset:448
	s_lshl_b32 s79, s75, 4
	s_cmp_le_i32 s82, s75
	v_or_b32_e32 v108, s79, v133
	s_cbranch_scc0 .LBB0_587
	s_waitcnt vmcnt(0) lgkmcnt(7)
	v_mfma_f32_16x16x32_bf16 v[216:219], v[12:15], v[104:107], 0
	v_sub_u32_e32 v231, v108, v144
	v_cmp_lt_i32_e32 vcc, -1, v231
	s_nop 5
	v_max_f32_e32 v215, 0, v216
	v_max_f32_e32 v216, 0, v217
	v_fma_f32 v230, v4, v216, 0
	v_max_f32_e32 v220, 0, v218
	v_max_f32_e32 v221, 0, v219
	s_waitcnt lgkmcnt(6)
	v_mfma_f32_16x16x32_bf16 v[216:219], v[12:15], v[100:103], 0
	s_nop 0
	v_fma_f32 v215, v4, v215, 0
	s_nop 5
	v_max_f32_e32 v216, 0, v216
	v_fmac_f32_e32 v215, v5, v216
	v_max_f32_e32 v216, 0, v217
	v_fmac_f32_e32 v230, v5, v216
	v_max_f32_e32 v222, 0, v218
	v_max_f32_e32 v223, 0, v219
	s_waitcnt lgkmcnt(5)
	v_mfma_f32_16x16x32_bf16 v[216:219], v[12:15], v[96:99], 0
	s_nop 7
	v_max_f32_e32 v216, 0, v216
	v_fmac_f32_e32 v215, v6, v216
	v_max_f32_e32 v216, 0, v217
	v_fmac_f32_e32 v230, v6, v216
	v_max_f32_e32 v216, 0, v218
	v_max_f32_e32 v217, 0, v219
	v_pk_fma_f32 v[218:219], v[4:5], v[220:221], 0 op_sel_hi:[0,1,0]
	v_pk_fma_f32 v[218:219], v[4:5], v[222:223], v[218:219] op_sel:[1,0,0]
	s_nop 0
	v_pk_fma_f32 v[220:221], v[6:7], v[216:217], v[218:219] op_sel_hi:[0,1,1]
	s_waitcnt lgkmcnt(4)
	v_mfma_f32_16x16x32_bf16 v[216:219], v[12:15], v[92:95], 0
	s_nop 7
	v_max_f32_e32 v216, 0, v216
	v_fmac_f32_e32 v215, v7, v216
	v_max_f32_e32 v216, 0, v217
	v_fmac_f32_e32 v230, v7, v216
	v_max_f32_e32 v222, 0, v218
	v_max_f32_e32 v223, 0, v219
	s_waitcnt lgkmcnt(3)
	v_mfma_f32_16x16x32_bf16 v[216:219], v[12:15], v[88:91], 0
	v_fma_f32 v220, v7, v222, v220
	v_fma_f32 v221, v7, v223, v221
	s_nop 5
	v_max_f32_e32 v216, 0, v216
	v_fmac_f32_e32 v215, v0, v216
	v_max_f32_e32 v216, 0, v217
	v_fmac_f32_e32 v230, v0, v216
	v_max_f32_e32 v224, 0, v218
	v_max_f32_e32 v225, 0, v219
	s_waitcnt lgkmcnt(2)
	v_mfma_f32_16x16x32_bf16 v[216:219], v[12:15], v[84:87], 0
	v_fma_f32 v220, v0, v224, v220
	v_fma_f32 v221, v0, v225, v221
	s_nop 5
	v_max_f32_e32 v216, 0, v216
	v_fmac_f32_e32 v215, v1, v216
	v_max_f32_e32 v216, 0, v217
	v_fmac_f32_e32 v230, v1, v216
	v_max_f32_e32 v226, 0, v218
	v_max_f32_e32 v227, 0, v219
	s_waitcnt lgkmcnt(1)
	v_mfma_f32_16x16x32_bf16 v[216:219], v[12:15], v[80:83], 0
	v_fma_f32 v220, v1, v226, v220
	v_fma_f32 v221, v1, v227, v221
	s_nop 5
	v_max_f32_e32 v216, 0, v216
	v_fmac_f32_e32 v215, v2, v216
	v_max_f32_e32 v216, 0, v217
	v_fmac_f32_e32 v230, v2, v216
	v_max_f32_e32 v228, 0, v218
	v_max_f32_e32 v229, 0, v219
	s_waitcnt lgkmcnt(0)
	v_mfma_f32_16x16x32_bf16 v[216:219], v[12:15], v[76:79], 0
	v_fma_f32 v220, v2, v228, v220
	v_fma_f32 v221, v2, v229, v221
	s_nop 5
	v_max_f32_e32 v216, 0, v216
	v_fmac_f32_e32 v215, v3, v216
	v_max_f32_e32 v216, 0, v217
	v_fmac_f32_e32 v230, v3, v216
	v_max_f32_e32 v218, 0, v218
	v_max_f32_e32 v219, 0, v219
	v_add_f32_e32 v215, 0, v215
	v_ashrrev_i32_e32 v216, 31, v215
	v_bitop3_b32 v215, v216, v215, s33 bitop3:0x36
	v_cndmask_b32_e32 v216, 0, v215, vcc
	v_add_f32_e32 v215, 0, v230
	v_ashrrev_i32_e32 v217, 31, v215
	v_pk_fma_f32 v[218:219], v[2:3], v[218:219], v[220:221] op_sel:[1,0,0]
	v_bitop3_b32 v215, v217, v215, s33 bitop3:0x36
	v_cmp_lt_i32_e32 vcc, 0, v231
	v_pk_add_f32 v[218:219], v[218:219], 0 op_sel_hi:[1,0]
	s_nop 0
	v_cndmask_b32_e32 v217, 0, v215, vcc
	v_ashrrev_i32_e32 v215, 31, v219
	v_ashrrev_i32_e32 v220, 31, v218
	v_or_b32_e32 v215, 0x80000000, v215
	v_or_b32_e32 v220, 0x80000000, v220
	v_xor_b32_e32 v215, v215, v219
	v_cmp_lt_i32_e32 vcc, 2, v231
	v_xor_b32_e32 v218, v220, v218
	s_nop 0
	v_cndmask_b32_e32 v219, 0, v215, vcc
	v_cmp_lt_i32_e32 vcc, 1, v231
	s_nop 1
	v_cndmask_b32_e32 v218, 0, v218, vcc
	ds_write_b128 v145, v[216:219] offset:8448
.LBB0_587:
	s_cmp_ge_i32 s82, s75
	v_readlane_b32 s10, v254, 31
	v_readlane_b32 s11, v254, 33
	s_cbranch_scc1 .LBB0_608
	s_waitcnt vmcnt(0) lgkmcnt(7)
	v_mfma_f32_16x16x32_bf16 v[216:219], v[16:19], v[104:107], 0
	v_sub_u32_e32 v231, v108, v146
	v_cmp_lt_i32_e32 vcc, -1, v231
	s_nop 5
	v_max_f32_e32 v215, 0, v216
	v_max_f32_e32 v216, 0, v217
	v_fma_f32 v230, v4, v216, 0
	v_max_f32_e32 v220, 0, v218
	v_max_f32_e32 v221, 0, v219
	s_waitcnt lgkmcnt(6)
	v_mfma_f32_16x16x32_bf16 v[216:219], v[16:19], v[100:103], 0
	s_nop 0
	v_fma_f32 v215, v4, v215, 0
	s_nop 5
	v_max_f32_e32 v216, 0, v216
	v_fmac_f32_e32 v215, v5, v216
	v_max_f32_e32 v216, 0, v217
	v_fmac_f32_e32 v230, v5, v216
	v_max_f32_e32 v222, 0, v218
	v_max_f32_e32 v223, 0, v219
	s_waitcnt lgkmcnt(5)
	v_mfma_f32_16x16x32_bf16 v[216:219], v[16:19], v[96:99], 0
	s_nop 7
	v_max_f32_e32 v216, 0, v216
	v_fmac_f32_e32 v215, v6, v216
	v_max_f32_e32 v216, 0, v217
	v_fmac_f32_e32 v230, v6, v216
	v_max_f32_e32 v216, 0, v218
	v_max_f32_e32 v217, 0, v219
	v_pk_fma_f32 v[218:219], v[4:5], v[220:221], 0 op_sel_hi:[0,1,0]
	v_pk_fma_f32 v[218:219], v[4:5], v[222:223], v[218:219] op_sel:[1,0,0]
	s_nop 0
	v_pk_fma_f32 v[220:221], v[6:7], v[216:217], v[218:219] op_sel_hi:[0,1,1]
	s_waitcnt lgkmcnt(4)
	v_mfma_f32_16x16x32_bf16 v[216:219], v[16:19], v[92:95], 0
	s_nop 7
	v_max_f32_e32 v216, 0, v216
	v_fmac_f32_e32 v215, v7, v216
	v_max_f32_e32 v216, 0, v217
	v_fmac_f32_e32 v230, v7, v216
	v_max_f32_e32 v222, 0, v218
	v_max_f32_e32 v223, 0, v219
	s_waitcnt lgkmcnt(3)
	v_mfma_f32_16x16x32_bf16 v[216:219], v[16:19], v[88:91], 0
	v_fma_f32 v220, v7, v222, v220
	v_fma_f32 v221, v7, v223, v221
	s_nop 5
	v_max_f32_e32 v216, 0, v216
	v_fmac_f32_e32 v215, v0, v216
	v_max_f32_e32 v216, 0, v217
	v_fmac_f32_e32 v230, v0, v216
	v_max_f32_e32 v224, 0, v218
	v_max_f32_e32 v225, 0, v219
	s_waitcnt lgkmcnt(2)
	v_mfma_f32_16x16x32_bf16 v[216:219], v[16:19], v[84:87], 0
	v_fma_f32 v220, v0, v224, v220
	v_fma_f32 v221, v0, v225, v221
	s_nop 5
	v_max_f32_e32 v216, 0, v216
	v_fmac_f32_e32 v215, v1, v216
	v_max_f32_e32 v216, 0, v217
	v_fmac_f32_e32 v230, v1, v216
	v_max_f32_e32 v226, 0, v218
	v_max_f32_e32 v227, 0, v219
	s_waitcnt lgkmcnt(1)
	v_mfma_f32_16x16x32_bf16 v[216:219], v[16:19], v[80:83], 0
	v_fma_f32 v220, v1, v226, v220
	v_fma_f32 v221, v1, v227, v221
	s_nop 5
	v_max_f32_e32 v216, 0, v216
	v_fmac_f32_e32 v215, v2, v216
	v_max_f32_e32 v216, 0, v217
	v_fmac_f32_e32 v230, v2, v216
	v_max_f32_e32 v228, 0, v218
	v_max_f32_e32 v229, 0, v219
	s_waitcnt lgkmcnt(0)
	v_mfma_f32_16x16x32_bf16 v[216:219], v[16:19], v[76:79], 0
	v_fma_f32 v220, v2, v228, v220
	v_fma_f32 v221, v2, v229, v221
	s_nop 5
	v_max_f32_e32 v216, 0, v216
	v_fmac_f32_e32 v215, v3, v216
	v_max_f32_e32 v216, 0, v217
	v_fmac_f32_e32 v230, v3, v216
	v_max_f32_e32 v218, 0, v218
	v_max_f32_e32 v219, 0, v219
	v_add_f32_e32 v215, 0, v215
	v_ashrrev_i32_e32 v216, 31, v215
	v_bitop3_b32 v215, v216, v215, s33 bitop3:0x36
	v_cndmask_b32_e32 v216, 0, v215, vcc
	v_add_f32_e32 v215, 0, v230
	v_ashrrev_i32_e32 v217, 31, v215
	v_pk_fma_f32 v[218:219], v[2:3], v[218:219], v[220:221] op_sel:[1,0,0]
	v_bitop3_b32 v215, v217, v215, s33 bitop3:0x36
	v_cmp_lt_i32_e32 vcc, 0, v231
	v_pk_add_f32 v[218:219], v[218:219], 0 op_sel_hi:[1,0]
	s_nop 0
	v_cndmask_b32_e32 v217, 0, v215, vcc
	v_ashrrev_i32_e32 v215, 31, v219
	v_ashrrev_i32_e32 v220, 31, v218
	v_or_b32_e32 v215, 0x80000000, v215
	v_or_b32_e32 v220, 0x80000000, v220
	v_xor_b32_e32 v215, v215, v219
	v_cmp_lt_i32_e32 vcc, 2, v231
	v_xor_b32_e32 v218, v220, v218
	s_nop 0
	v_cndmask_b32_e32 v219, 0, v215, vcc
	v_cmp_lt_i32_e32 vcc, 1, v231
	s_nop 1
	v_cndmask_b32_e32 v218, 0, v218, vcc
	ds_write_b128 v145, v[216:219] offset:8512
	s_cmp_gt_i32 s83, s75
	s_cbranch_scc0 .LBB0_609

.LBB0_590:
	s_waitcnt vmcnt(0) lgkmcnt(7)
	v_mfma_f32_16x16x32_bf16 v[216:219], v[24:27], v[104:107], 0
	v_sub_u32_e32 v231, v108, v149
	v_cmp_lt_i32_e32 vcc, -1, v231
	s_nop 5
	v_max_f32_e32 v215, 0, v216
	v_max_f32_e32 v216, 0, v217
	v_fma_f32 v230, v4, v216, 0
	v_max_f32_e32 v220, 0, v218
	v_max_f32_e32 v221, 0, v219
	s_waitcnt lgkmcnt(6)
	v_mfma_f32_16x16x32_bf16 v[216:219], v[24:27], v[100:103], 0
	s_nop 0
	v_fma_f32 v215, v4, v215, 0
	s_nop 5
	v_max_f32_e32 v216, 0, v216
	v_fmac_f32_e32 v215, v5, v216
	v_max_f32_e32 v216, 0, v217
	v_fmac_f32_e32 v230, v5, v216
	v_max_f32_e32 v222, 0, v218
	v_max_f32_e32 v223, 0, v219
	s_waitcnt lgkmcnt(5)
	v_mfma_f32_16x16x32_bf16 v[216:219], v[24:27], v[96:99], 0
	s_nop 7
	v_max_f32_e32 v216, 0, v216
	v_fmac_f32_e32 v215, v6, v216
	v_max_f32_e32 v216, 0, v217
	v_fmac_f32_e32 v230, v6, v216
	v_max_f32_e32 v216, 0, v218
	v_max_f32_e32 v217, 0, v219
	v_pk_fma_f32 v[218:219], v[4:5], v[220:221], 0 op_sel_hi:[0,1,0]
	v_pk_fma_f32 v[218:219], v[4:5], v[222:223], v[218:219] op_sel:[1,0,0]
	s_nop 0
	v_pk_fma_f32 v[220:221], v[6:7], v[216:217], v[218:219] op_sel_hi:[0,1,1]
	s_waitcnt lgkmcnt(4)
	v_mfma_f32_16x16x32_bf16 v[216:219], v[24:27], v[92:95], 0
	s_nop 7
	v_max_f32_e32 v216, 0, v216
	v_fmac_f32_e32 v215, v7, v216
	v_max_f32_e32 v216, 0, v217
	v_fmac_f32_e32 v230, v7, v216
	v_max_f32_e32 v222, 0, v218
	v_max_f32_e32 v223, 0, v219
	s_waitcnt lgkmcnt(3)
	v_mfma_f32_16x16x32_bf16 v[216:219], v[24:27], v[88:91], 0
	v_fma_f32 v220, v7, v222, v220
	v_fma_f32 v221, v7, v223, v221
	s_nop 5
	v_max_f32_e32 v216, 0, v216
	v_fmac_f32_e32 v215, v0, v216
	v_max_f32_e32 v216, 0, v217
	v_fmac_f32_e32 v230, v0, v216
	v_max_f32_e32 v224, 0, v218
	v_max_f32_e32 v225, 0, v219
	s_waitcnt lgkmcnt(2)
	v_mfma_f32_16x16x32_bf16 v[216:219], v[24:27], v[84:87], 0
	v_fma_f32 v220, v0, v224, v220
	v_fma_f32 v221, v0, v225, v221
	s_nop 5
	v_max_f32_e32 v216, 0, v216
	v_fmac_f32_e32 v215, v1, v216
	v_max_f32_e32 v216, 0, v217
	v_fmac_f32_e32 v230, v1, v216
	v_max_f32_e32 v226, 0, v218
	v_max_f32_e32 v227, 0, v219
	s_waitcnt lgkmcnt(1)
	v_mfma_f32_16x16x32_bf16 v[216:219], v[24:27], v[80:83], 0
	v_fma_f32 v220, v1, v226, v220
	v_fma_f32 v221, v1, v227, v221
	s_nop 5
	v_max_f32_e32 v216, 0, v216
	v_fmac_f32_e32 v215, v2, v216
	v_max_f32_e32 v216, 0, v217
	v_fmac_f32_e32 v230, v2, v216
	v_max_f32_e32 v228, 0, v218
	v_max_f32_e32 v229, 0, v219
	s_waitcnt lgkmcnt(0)
	v_mfma_f32_16x16x32_bf16 v[216:219], v[24:27], v[76:79], 0
	v_fma_f32 v220, v2, v228, v220
	v_fma_f32 v221, v2, v229, v221
	s_nop 5
	v_max_f32_e32 v216, 0, v216
	v_fmac_f32_e32 v215, v3, v216
	v_max_f32_e32 v216, 0, v217
	v_fmac_f32_e32 v230, v3, v216
	v_max_f32_e32 v218, 0, v218
	v_max_f32_e32 v219, 0, v219
	v_add_f32_e32 v215, 0, v215
	v_ashrrev_i32_e32 v216, 31, v215
	v_bitop3_b32 v215, v216, v215, s33 bitop3:0x36
	v_cndmask_b32_e32 v216, 0, v215, vcc
	v_add_f32_e32 v215, 0, v230
	v_ashrrev_i32_e32 v217, 31, v215
	v_pk_fma_f32 v[218:219], v[2:3], v[218:219], v[220:221] op_sel:[1,0,0]
	v_bitop3_b32 v215, v217, v215, s33 bitop3:0x36
	v_cmp_lt_i32_e32 vcc, 0, v231
	v_pk_add_f32 v[218:219], v[218:219], 0 op_sel_hi:[1,0]
	s_nop 0
	v_cndmask_b32_e32 v217, 0, v215, vcc
	v_ashrrev_i32_e32 v215, 31, v219
	v_ashrrev_i32_e32 v220, 31, v218
	v_or_b32_e32 v215, 0x80000000, v215
	v_or_b32_e32 v220, 0x80000000, v220
	v_xor_b32_e32 v215, v215, v219
	v_cmp_lt_i32_e32 vcc, 2, v231
	v_xor_b32_e32 v218, v220, v218
	s_nop 0
	v_cndmask_b32_e32 v219, 0, v215, vcc
	v_cmp_lt_i32_e32 vcc, 1, v231
	s_nop 1
	v_cndmask_b32_e32 v218, 0, v218, vcc
	ds_write_b128 v148, v[216:219] offset:8512
	s_cmp_gt_i32 s84, s75
	s_cbranch_scc0 .LBB0_611

.LBB0_592:
	s_waitcnt vmcnt(0) lgkmcnt(7)
	v_mfma_f32_16x16x32_bf16 v[216:219], v[32:35], v[104:107], 0
	v_sub_u32_e32 v231, v108, v152
	v_cmp_lt_i32_e32 vcc, -1, v231
	s_nop 5
	v_max_f32_e32 v215, 0, v216
	v_max_f32_e32 v216, 0, v217
	v_fma_f32 v230, v4, v216, 0
	v_max_f32_e32 v220, 0, v218
	v_max_f32_e32 v221, 0, v219
	s_waitcnt lgkmcnt(6)
	v_mfma_f32_16x16x32_bf16 v[216:219], v[32:35], v[100:103], 0
	s_nop 0
	v_fma_f32 v215, v4, v215, 0
	s_nop 5
	v_max_f32_e32 v216, 0, v216
	v_fmac_f32_e32 v215, v5, v216
	v_max_f32_e32 v216, 0, v217
	v_fmac_f32_e32 v230, v5, v216
	v_max_f32_e32 v222, 0, v218
	v_max_f32_e32 v223, 0, v219
	s_waitcnt lgkmcnt(5)
	v_mfma_f32_16x16x32_bf16 v[216:219], v[32:35], v[96:99], 0
	s_nop 7
	v_max_f32_e32 v216, 0, v216
	v_fmac_f32_e32 v215, v6, v216
	v_max_f32_e32 v216, 0, v217
	v_fmac_f32_e32 v230, v6, v216
	v_max_f32_e32 v216, 0, v218
	v_max_f32_e32 v217, 0, v219
	v_pk_fma_f32 v[218:219], v[4:5], v[220:221], 0 op_sel_hi:[0,1,0]
	v_pk_fma_f32 v[218:219], v[4:5], v[222:223], v[218:219] op_sel:[1,0,0]
	s_nop 0
	v_pk_fma_f32 v[220:221], v[6:7], v[216:217], v[218:219] op_sel_hi:[0,1,1]
	s_waitcnt lgkmcnt(4)
	v_mfma_f32_16x16x32_bf16 v[216:219], v[32:35], v[92:95], 0
	s_nop 7
	v_max_f32_e32 v216, 0, v216
	v_fmac_f32_e32 v215, v7, v216
	v_max_f32_e32 v216, 0, v217
	v_fmac_f32_e32 v230, v7, v216
	v_max_f32_e32 v222, 0, v218
	v_max_f32_e32 v223, 0, v219
	s_waitcnt lgkmcnt(3)
	v_mfma_f32_16x16x32_bf16 v[216:219], v[32:35], v[88:91], 0
	v_fma_f32 v220, v7, v222, v220
	v_fma_f32 v221, v7, v223, v221
	s_nop 5
	v_max_f32_e32 v216, 0, v216
	v_fmac_f32_e32 v215, v0, v216
	v_max_f32_e32 v216, 0, v217
	v_fmac_f32_e32 v230, v0, v216
	v_max_f32_e32 v224, 0, v218
	v_max_f32_e32 v225, 0, v219
	s_waitcnt lgkmcnt(2)
	v_mfma_f32_16x16x32_bf16 v[216:219], v[32:35], v[84:87], 0
	v_fma_f32 v220, v0, v224, v220
	v_fma_f32 v221, v0, v225, v221
	s_nop 5
	v_max_f32_e32 v216, 0, v216
	v_fmac_f32_e32 v215, v1, v216
	v_max_f32_e32 v216, 0, v217
	v_fmac_f32_e32 v230, v1, v216
	v_max_f32_e32 v226, 0, v218
	v_max_f32_e32 v227, 0, v219
	s_waitcnt lgkmcnt(1)
	v_mfma_f32_16x16x32_bf16 v[216:219], v[32:35], v[80:83], 0
	v_fma_f32 v220, v1, v226, v220
	v_fma_f32 v221, v1, v227, v221
	s_nop 5
	v_max_f32_e32 v216, 0, v216
	v_fmac_f32_e32 v215, v2, v216
	v_max_f32_e32 v216, 0, v217
	v_fmac_f32_e32 v230, v2, v216
	v_max_f32_e32 v228, 0, v218
	v_max_f32_e32 v229, 0, v219
	s_waitcnt lgkmcnt(0)
	v_mfma_f32_16x16x32_bf16 v[216:219], v[32:35], v[76:79], 0
	v_fma_f32 v220, v2, v228, v220
	v_fma_f32 v221, v2, v229, v221
	s_nop 5
	v_max_f32_e32 v216, 0, v216
	v_fmac_f32_e32 v215, v3, v216
	v_max_f32_e32 v216, 0, v217
	v_fmac_f32_e32 v230, v3, v216
	v_max_f32_e32 v218, 0, v218
	v_max_f32_e32 v219, 0, v219
	v_add_f32_e32 v215, 0, v215
	v_ashrrev_i32_e32 v216, 31, v215
	v_bitop3_b32 v215, v216, v215, s33 bitop3:0x36
	v_cndmask_b32_e32 v216, 0, v215, vcc
	v_add_f32_e32 v215, 0, v230
	v_ashrrev_i32_e32 v217, 31, v215
	v_pk_fma_f32 v[218:219], v[2:3], v[218:219], v[220:221] op_sel:[1,0,0]
	v_bitop3_b32 v215, v217, v215, s33 bitop3:0x36
	v_cmp_lt_i32_e32 vcc, 0, v231
	v_pk_add_f32 v[218:219], v[218:219], 0 op_sel_hi:[1,0]
	s_nop 0
	v_cndmask_b32_e32 v217, 0, v215, vcc
	v_ashrrev_i32_e32 v215, 31, v219
	v_ashrrev_i32_e32 v220, 31, v218
	v_or_b32_e32 v215, 0x80000000, v215
	v_or_b32_e32 v220, 0x80000000, v220
	v_xor_b32_e32 v215, v215, v219
	v_cmp_lt_i32_e32 vcc, 2, v231
	v_xor_b32_e32 v218, v220, v218
	s_nop 0
	v_cndmask_b32_e32 v219, 0, v215, vcc
	v_cmp_lt_i32_e32 vcc, 1, v231
	s_nop 1
	v_cndmask_b32_e32 v218, 0, v218, vcc
	ds_write_b128 v151, v[216:219] offset:8512
	s_cmp_gt_i32 s10, s75
	s_cbranch_scc0 .LBB0_613

.LBB0_594:
	s_waitcnt vmcnt(0) lgkmcnt(7)
	v_mfma_f32_16x16x32_bf16 v[216:219], v[40:43], v[104:107], 0
	v_sub_u32_e32 v231, v108, v155
	v_cmp_lt_i32_e32 vcc, -1, v231
	s_nop 5
	v_max_f32_e32 v215, 0, v216
	v_max_f32_e32 v216, 0, v217
	v_fma_f32 v230, v4, v216, 0
	v_max_f32_e32 v220, 0, v218
	v_max_f32_e32 v221, 0, v219
	s_waitcnt lgkmcnt(6)
	v_mfma_f32_16x16x32_bf16 v[216:219], v[40:43], v[100:103], 0
	s_nop 0
	v_fma_f32 v215, v4, v215, 0
	s_nop 5
	v_max_f32_e32 v216, 0, v216
	v_fmac_f32_e32 v215, v5, v216
	v_max_f32_e32 v216, 0, v217
	v_fmac_f32_e32 v230, v5, v216
	v_max_f32_e32 v222, 0, v218
	v_max_f32_e32 v223, 0, v219
	s_waitcnt lgkmcnt(5)
	v_mfma_f32_16x16x32_bf16 v[216:219], v[40:43], v[96:99], 0
	s_nop 7
	v_max_f32_e32 v216, 0, v216
	v_fmac_f32_e32 v215, v6, v216
	v_max_f32_e32 v216, 0, v217
	v_fmac_f32_e32 v230, v6, v216
	v_max_f32_e32 v216, 0, v218
	v_max_f32_e32 v217, 0, v219
	v_pk_fma_f32 v[218:219], v[4:5], v[220:221], 0 op_sel_hi:[0,1,0]
	v_pk_fma_f32 v[218:219], v[4:5], v[222:223], v[218:219] op_sel:[1,0,0]
	s_nop 0
	v_pk_fma_f32 v[220:221], v[6:7], v[216:217], v[218:219] op_sel_hi:[0,1,1]
	s_waitcnt lgkmcnt(4)
	v_mfma_f32_16x16x32_bf16 v[216:219], v[40:43], v[92:95], 0
	s_nop 7
	v_max_f32_e32 v216, 0, v216
	v_fmac_f32_e32 v215, v7, v216
	v_max_f32_e32 v216, 0, v217
	v_fmac_f32_e32 v230, v7, v216
	v_max_f32_e32 v222, 0, v218
	v_max_f32_e32 v223, 0, v219
	s_waitcnt lgkmcnt(3)
	v_mfma_f32_16x16x32_bf16 v[216:219], v[40:43], v[88:91], 0
	v_fma_f32 v220, v7, v222, v220
	v_fma_f32 v221, v7, v223, v221
	s_nop 5
	v_max_f32_e32 v216, 0, v216
	v_fmac_f32_e32 v215, v0, v216
	v_max_f32_e32 v216, 0, v217
	v_fmac_f32_e32 v230, v0, v216
	v_max_f32_e32 v224, 0, v218
	v_max_f32_e32 v225, 0, v219
	s_waitcnt lgkmcnt(2)
	v_mfma_f32_16x16x32_bf16 v[216:219], v[40:43], v[84:87], 0
	v_fma_f32 v220, v0, v224, v220
	v_fma_f32 v221, v0, v225, v221
	s_nop 5
	v_max_f32_e32 v216, 0, v216
	v_fmac_f32_e32 v215, v1, v216
	v_max_f32_e32 v216, 0, v217
	v_fmac_f32_e32 v230, v1, v216
	v_max_f32_e32 v226, 0, v218
	v_max_f32_e32 v227, 0, v219
	s_waitcnt lgkmcnt(1)
	v_mfma_f32_16x16x32_bf16 v[216:219], v[40:43], v[80:83], 0
	v_fma_f32 v220, v1, v226, v220
	v_fma_f32 v221, v1, v227, v221
	s_nop 5
	v_max_f32_e32 v216, 0, v216
	v_fmac_f32_e32 v215, v2, v216
	v_max_f32_e32 v216, 0, v217
	v_fmac_f32_e32 v230, v2, v216
	v_max_f32_e32 v228, 0, v218
	v_max_f32_e32 v229, 0, v219
	s_waitcnt lgkmcnt(0)
	v_mfma_f32_16x16x32_bf16 v[216:219], v[40:43], v[76:79], 0
	v_fma_f32 v220, v2, v228, v220
	v_fma_f32 v221, v2, v229, v221
	s_nop 5
	v_max_f32_e32 v216, 0, v216
	v_fmac_f32_e32 v215, v3, v216
	v_max_f32_e32 v216, 0, v217
	v_fmac_f32_e32 v230, v3, v216
	v_max_f32_e32 v218, 0, v218
	v_max_f32_e32 v219, 0, v219
	v_add_f32_e32 v215, 0, v215
	v_ashrrev_i32_e32 v216, 31, v215
	v_bitop3_b32 v215, v216, v215, s33 bitop3:0x36
	v_cndmask_b32_e32 v216, 0, v215, vcc
	v_add_f32_e32 v215, 0, v230
	v_ashrrev_i32_e32 v217, 31, v215
	v_pk_fma_f32 v[218:219], v[2:3], v[218:219], v[220:221] op_sel:[1,0,0]
	v_bitop3_b32 v215, v217, v215, s33 bitop3:0x36
	v_cmp_lt_i32_e32 vcc, 0, v231
	v_pk_add_f32 v[218:219], v[218:219], 0 op_sel_hi:[1,0]
	s_nop 0
	v_cndmask_b32_e32 v217, 0, v215, vcc
	v_ashrrev_i32_e32 v215, 31, v219
	v_ashrrev_i32_e32 v220, 31, v218
	v_or_b32_e32 v215, 0x80000000, v215
	v_or_b32_e32 v220, 0x80000000, v220
	v_xor_b32_e32 v215, v215, v219
	v_cmp_lt_i32_e32 vcc, 2, v231
	v_xor_b32_e32 v218, v220, v218
	s_nop 0
	v_cndmask_b32_e32 v219, 0, v215, vcc
	v_cmp_lt_i32_e32 vcc, 1, v231
	s_nop 1
	v_cndmask_b32_e32 v218, 0, v218, vcc
	ds_write_b128 v154, v[216:219] offset:8512
	s_cmp_gt_i32 s12, s75
	s_cbranch_scc0 .LBB0_615

.LBB0_596:
	s_waitcnt vmcnt(0) lgkmcnt(7)
	v_mfma_f32_16x16x32_bf16 v[216:219], v[48:51], v[104:107], 0
	v_sub_u32_e32 v231, v108, v158
	v_cmp_lt_i32_e32 vcc, -1, v231
	s_nop 5
	v_max_f32_e32 v215, 0, v216
	v_max_f32_e32 v216, 0, v217
	v_fma_f32 v230, v4, v216, 0
	v_max_f32_e32 v220, 0, v218
	v_max_f32_e32 v221, 0, v219
	s_waitcnt lgkmcnt(6)
	v_mfma_f32_16x16x32_bf16 v[216:219], v[48:51], v[100:103], 0
	s_nop 0
	v_fma_f32 v215, v4, v215, 0
	s_nop 5
	v_max_f32_e32 v216, 0, v216
	v_fmac_f32_e32 v215, v5, v216
	v_max_f32_e32 v216, 0, v217
	v_fmac_f32_e32 v230, v5, v216
	v_max_f32_e32 v222, 0, v218
	v_max_f32_e32 v223, 0, v219
	s_waitcnt lgkmcnt(5)
	v_mfma_f32_16x16x32_bf16 v[216:219], v[48:51], v[96:99], 0
	s_nop 7
	v_max_f32_e32 v216, 0, v216
	v_fmac_f32_e32 v215, v6, v216
	v_max_f32_e32 v216, 0, v217
	v_fmac_f32_e32 v230, v6, v216
	v_max_f32_e32 v216, 0, v218
	v_max_f32_e32 v217, 0, v219
	v_pk_fma_f32 v[218:219], v[4:5], v[220:221], 0 op_sel_hi:[0,1,0]
	v_pk_fma_f32 v[218:219], v[4:5], v[222:223], v[218:219] op_sel:[1,0,0]
	s_nop 0
	v_pk_fma_f32 v[220:221], v[6:7], v[216:217], v[218:219] op_sel_hi:[0,1,1]
	s_waitcnt lgkmcnt(4)
	v_mfma_f32_16x16x32_bf16 v[216:219], v[48:51], v[92:95], 0
	s_nop 7
	v_max_f32_e32 v216, 0, v216
	v_fmac_f32_e32 v215, v7, v216
	v_max_f32_e32 v216, 0, v217
	v_fmac_f32_e32 v230, v7, v216
	v_max_f32_e32 v222, 0, v218
	v_max_f32_e32 v223, 0, v219
	s_waitcnt lgkmcnt(3)
	v_mfma_f32_16x16x32_bf16 v[216:219], v[48:51], v[88:91], 0
	v_fma_f32 v220, v7, v222, v220
	v_fma_f32 v221, v7, v223, v221
	s_nop 5
	v_max_f32_e32 v216, 0, v216
	v_fmac_f32_e32 v215, v0, v216
	v_max_f32_e32 v216, 0, v217
	v_fmac_f32_e32 v230, v0, v216
	v_max_f32_e32 v224, 0, v218
	v_max_f32_e32 v225, 0, v219
	s_waitcnt lgkmcnt(2)
	v_mfma_f32_16x16x32_bf16 v[216:219], v[48:51], v[84:87], 0
	v_fma_f32 v220, v0, v224, v220
	v_fma_f32 v221, v0, v225, v221
	s_nop 5
	v_max_f32_e32 v216, 0, v216
	v_fmac_f32_e32 v215, v1, v216
	v_max_f32_e32 v216, 0, v217
	v_fmac_f32_e32 v230, v1, v216
	v_max_f32_e32 v226, 0, v218
	v_max_f32_e32 v227, 0, v219
	s_waitcnt lgkmcnt(1)
	v_mfma_f32_16x16x32_bf16 v[216:219], v[48:51], v[80:83], 0
	v_fma_f32 v220, v1, v226, v220
	v_fma_f32 v221, v1, v227, v221
	s_nop 5
	v_max_f32_e32 v216, 0, v216
	v_fmac_f32_e32 v215, v2, v216
	v_max_f32_e32 v216, 0, v217
	v_fmac_f32_e32 v230, v2, v216
	v_max_f32_e32 v228, 0, v218
	v_max_f32_e32 v229, 0, v219
	s_waitcnt lgkmcnt(0)
	v_mfma_f32_16x16x32_bf16 v[216:219], v[48:51], v[76:79], 0
	v_fma_f32 v220, v2, v228, v220
	v_fma_f32 v221, v2, v229, v221
	s_nop 5
	v_max_f32_e32 v216, 0, v216
	v_fmac_f32_e32 v215, v3, v216
	v_max_f32_e32 v216, 0, v217
	v_fmac_f32_e32 v230, v3, v216
	v_max_f32_e32 v218, 0, v218
	v_max_f32_e32 v219, 0, v219
	v_add_f32_e32 v215, 0, v215
	v_ashrrev_i32_e32 v216, 31, v215
	v_bitop3_b32 v215, v216, v215, s33 bitop3:0x36
	v_cndmask_b32_e32 v216, 0, v215, vcc
	v_add_f32_e32 v215, 0, v230
	v_ashrrev_i32_e32 v217, 31, v215
	v_pk_fma_f32 v[218:219], v[2:3], v[218:219], v[220:221] op_sel:[1,0,0]
	v_bitop3_b32 v215, v217, v215, s33 bitop3:0x36
	v_cmp_lt_i32_e32 vcc, 0, v231
	v_pk_add_f32 v[218:219], v[218:219], 0 op_sel_hi:[1,0]
	s_nop 0
	v_cndmask_b32_e32 v217, 0, v215, vcc
	v_ashrrev_i32_e32 v215, 31, v219
	v_ashrrev_i32_e32 v220, 31, v218
	v_or_b32_e32 v215, 0x80000000, v215
	v_or_b32_e32 v220, 0x80000000, v220
	v_xor_b32_e32 v215, v215, v219
	v_cmp_lt_i32_e32 vcc, 2, v231
	v_xor_b32_e32 v218, v220, v218
	s_nop 0
	v_cndmask_b32_e32 v219, 0, v215, vcc
	v_cmp_lt_i32_e32 vcc, 1, v231
	s_nop 1
	v_cndmask_b32_e32 v218, 0, v218, vcc
	ds_write_b128 v157, v[216:219] offset:8512
	s_cmp_gt_i32 s13, s75
	s_cbranch_scc0 .LBB0_617

.LBB0_598:
	s_waitcnt vmcnt(0) lgkmcnt(7)
	v_mfma_f32_16x16x32_bf16 v[216:219], v[56:59], v[104:107], 0
	v_sub_u32_e32 v231, v108, v161
	v_cmp_lt_i32_e32 vcc, -1, v231
	s_nop 5
	v_max_f32_e32 v215, 0, v216
	v_max_f32_e32 v216, 0, v217
	v_fma_f32 v230, v4, v216, 0
	v_max_f32_e32 v220, 0, v218
	v_max_f32_e32 v221, 0, v219
	s_waitcnt lgkmcnt(6)
	v_mfma_f32_16x16x32_bf16 v[216:219], v[56:59], v[100:103], 0
	s_nop 0
	v_fma_f32 v215, v4, v215, 0
	s_nop 5
	v_max_f32_e32 v216, 0, v216
	v_fmac_f32_e32 v215, v5, v216
	v_max_f32_e32 v216, 0, v217
	v_fmac_f32_e32 v230, v5, v216
	v_max_f32_e32 v222, 0, v218
	v_max_f32_e32 v223, 0, v219
	s_waitcnt lgkmcnt(5)
	v_mfma_f32_16x16x32_bf16 v[216:219], v[56:59], v[96:99], 0
	s_nop 7
	v_max_f32_e32 v216, 0, v216
	v_fmac_f32_e32 v215, v6, v216
	v_max_f32_e32 v216, 0, v217
	v_fmac_f32_e32 v230, v6, v216
	v_max_f32_e32 v216, 0, v218
	v_max_f32_e32 v217, 0, v219
	v_pk_fma_f32 v[218:219], v[4:5], v[220:221], 0 op_sel_hi:[0,1,0]
	v_pk_fma_f32 v[218:219], v[4:5], v[222:223], v[218:219] op_sel:[1,0,0]
	s_nop 0
	v_pk_fma_f32 v[220:221], v[6:7], v[216:217], v[218:219] op_sel_hi:[0,1,1]
	s_waitcnt lgkmcnt(4)
	v_mfma_f32_16x16x32_bf16 v[216:219], v[56:59], v[92:95], 0
	s_nop 7
	v_max_f32_e32 v216, 0, v216
	v_fmac_f32_e32 v215, v7, v216
	v_max_f32_e32 v216, 0, v217
	v_fmac_f32_e32 v230, v7, v216
	v_max_f32_e32 v222, 0, v218
	v_max_f32_e32 v223, 0, v219
	s_waitcnt lgkmcnt(3)
	v_mfma_f32_16x16x32_bf16 v[216:219], v[56:59], v[88:91], 0
	v_fma_f32 v220, v7, v222, v220
	v_fma_f32 v221, v7, v223, v221
	s_nop 5
	v_max_f32_e32 v216, 0, v216
	v_fmac_f32_e32 v215, v0, v216
	v_max_f32_e32 v216, 0, v217
	v_fmac_f32_e32 v230, v0, v216
	v_max_f32_e32 v224, 0, v218
	v_max_f32_e32 v225, 0, v219
	s_waitcnt lgkmcnt(2)
	v_mfma_f32_16x16x32_bf16 v[216:219], v[56:59], v[84:87], 0
	v_fma_f32 v220, v0, v224, v220
	v_fma_f32 v221, v0, v225, v221
	s_nop 5
	v_max_f32_e32 v216, 0, v216
	v_fmac_f32_e32 v215, v1, v216
	v_max_f32_e32 v216, 0, v217
	v_fmac_f32_e32 v230, v1, v216
	v_max_f32_e32 v226, 0, v218
	v_max_f32_e32 v227, 0, v219
	s_waitcnt lgkmcnt(1)
	v_mfma_f32_16x16x32_bf16 v[216:219], v[56:59], v[80:83], 0
	v_fma_f32 v220, v1, v226, v220
	v_fma_f32 v221, v1, v227, v221
	s_nop 5
	v_max_f32_e32 v216, 0, v216
	v_fmac_f32_e32 v215, v2, v216
	v_max_f32_e32 v216, 0, v217
	v_fmac_f32_e32 v230, v2, v216
	v_max_f32_e32 v228, 0, v218
	v_max_f32_e32 v229, 0, v219
	s_waitcnt lgkmcnt(0)
	v_mfma_f32_16x16x32_bf16 v[216:219], v[56:59], v[76:79], 0
	v_fma_f32 v220, v2, v228, v220
	v_fma_f32 v221, v2, v229, v221
	s_nop 5
	v_max_f32_e32 v216, 0, v216
	v_fmac_f32_e32 v215, v3, v216
	v_max_f32_e32 v216, 0, v217
	v_fmac_f32_e32 v230, v3, v216
	v_max_f32_e32 v218, 0, v218
	v_max_f32_e32 v219, 0, v219
	v_add_f32_e32 v215, 0, v215
	v_ashrrev_i32_e32 v216, 31, v215
	v_bitop3_b32 v215, v216, v215, s33 bitop3:0x36
	v_cndmask_b32_e32 v216, 0, v215, vcc
	v_add_f32_e32 v215, 0, v230
	v_ashrrev_i32_e32 v217, 31, v215
	v_pk_fma_f32 v[218:219], v[2:3], v[218:219], v[220:221] op_sel:[1,0,0]
	v_bitop3_b32 v215, v217, v215, s33 bitop3:0x36
	v_cmp_lt_i32_e32 vcc, 0, v231
	v_pk_add_f32 v[218:219], v[218:219], 0 op_sel_hi:[1,0]
	s_nop 0
	v_cndmask_b32_e32 v217, 0, v215, vcc
	v_ashrrev_i32_e32 v215, 31, v219
	v_ashrrev_i32_e32 v220, 31, v218
	v_or_b32_e32 v215, 0x80000000, v215
	v_or_b32_e32 v220, 0x80000000, v220
	v_xor_b32_e32 v215, v215, v219
	v_cmp_lt_i32_e32 vcc, 2, v231
	v_xor_b32_e32 v218, v220, v218
	s_nop 0
	v_cndmask_b32_e32 v219, 0, v215, vcc
	v_cmp_lt_i32_e32 vcc, 1, v231
	s_nop 1
	v_cndmask_b32_e32 v218, 0, v218, vcc
	ds_write_b128 v160, v[216:219] offset:8512
	s_cmp_gt_i32 s11, s75
	s_cbranch_scc0 .LBB0_619

.LBB0_600:
	s_waitcnt vmcnt(0) lgkmcnt(7)
	v_mfma_f32_16x16x32_bf16 v[216:219], v[64:67], v[104:107], 0
	v_sub_u32_e32 v231, v108, v164
	v_cmp_lt_i32_e32 vcc, -1, v231
	s_nop 5
	v_max_f32_e32 v215, 0, v216
	v_max_f32_e32 v216, 0, v217
	v_fma_f32 v230, v4, v216, 0
	v_max_f32_e32 v220, 0, v218
	v_max_f32_e32 v221, 0, v219
	s_waitcnt lgkmcnt(6)
	v_mfma_f32_16x16x32_bf16 v[216:219], v[64:67], v[100:103], 0
	s_nop 0
	v_fma_f32 v215, v4, v215, 0
	s_nop 5
	v_max_f32_e32 v216, 0, v216
	v_fmac_f32_e32 v215, v5, v216
	v_max_f32_e32 v216, 0, v217
	v_fmac_f32_e32 v230, v5, v216
	v_max_f32_e32 v222, 0, v218
	v_max_f32_e32 v223, 0, v219
	s_waitcnt lgkmcnt(5)
	v_mfma_f32_16x16x32_bf16 v[216:219], v[64:67], v[96:99], 0
	s_nop 7
	v_max_f32_e32 v216, 0, v216
	v_fmac_f32_e32 v215, v6, v216
	v_max_f32_e32 v216, 0, v217
	v_fmac_f32_e32 v230, v6, v216
	v_max_f32_e32 v216, 0, v218
	v_max_f32_e32 v217, 0, v219
	v_pk_fma_f32 v[218:219], v[4:5], v[220:221], 0 op_sel_hi:[0,1,0]
	v_pk_fma_f32 v[218:219], v[4:5], v[222:223], v[218:219] op_sel:[1,0,0]
	s_nop 0
	v_pk_fma_f32 v[220:221], v[6:7], v[216:217], v[218:219] op_sel_hi:[0,1,1]
	s_waitcnt lgkmcnt(4)
	v_mfma_f32_16x16x32_bf16 v[216:219], v[64:67], v[92:95], 0
	s_nop 7
	v_max_f32_e32 v216, 0, v216
	v_fmac_f32_e32 v215, v7, v216
	v_max_f32_e32 v216, 0, v217
	v_fmac_f32_e32 v230, v7, v216
	v_max_f32_e32 v222, 0, v218
	v_max_f32_e32 v223, 0, v219
	s_waitcnt lgkmcnt(3)
	v_mfma_f32_16x16x32_bf16 v[216:219], v[64:67], v[88:91], 0
	v_fma_f32 v220, v7, v222, v220
	v_fma_f32 v221, v7, v223, v221
	s_nop 5
	v_max_f32_e32 v216, 0, v216
	v_fmac_f32_e32 v215, v0, v216
	v_max_f32_e32 v216, 0, v217
	v_fmac_f32_e32 v230, v0, v216
	v_max_f32_e32 v224, 0, v218
	v_max_f32_e32 v225, 0, v219
	s_waitcnt lgkmcnt(2)
	v_mfma_f32_16x16x32_bf16 v[216:219], v[64:67], v[84:87], 0
	v_fma_f32 v220, v0, v224, v220
	v_fma_f32 v221, v0, v225, v221
	s_nop 5
	v_max_f32_e32 v216, 0, v216
	v_fmac_f32_e32 v215, v1, v216
	v_max_f32_e32 v216, 0, v217
	v_fmac_f32_e32 v230, v1, v216
	v_max_f32_e32 v226, 0, v218
	v_max_f32_e32 v227, 0, v219
	s_waitcnt lgkmcnt(1)
	v_mfma_f32_16x16x32_bf16 v[216:219], v[64:67], v[80:83], 0
	v_fma_f32 v220, v1, v226, v220
	v_fma_f32 v221, v1, v227, v221
	s_nop 5
	v_max_f32_e32 v216, 0, v216
	v_fmac_f32_e32 v215, v2, v216
	v_max_f32_e32 v216, 0, v217
	v_fmac_f32_e32 v230, v2, v216
	v_max_f32_e32 v228, 0, v218
	v_max_f32_e32 v229, 0, v219
	s_waitcnt lgkmcnt(0)
	v_mfma_f32_16x16x32_bf16 v[216:219], v[64:67], v[76:79], 0
	v_fma_f32 v220, v2, v228, v220
	v_fma_f32 v221, v2, v229, v221
	s_nop 5
	v_max_f32_e32 v216, 0, v216
	v_fmac_f32_e32 v215, v3, v216
	v_max_f32_e32 v216, 0, v217
	v_fmac_f32_e32 v230, v3, v216
	v_max_f32_e32 v218, 0, v218
	v_max_f32_e32 v219, 0, v219
	v_add_f32_e32 v215, 0, v215
	v_ashrrev_i32_e32 v216, 31, v215
	v_bitop3_b32 v215, v216, v215, s33 bitop3:0x36
	v_cndmask_b32_e32 v216, 0, v215, vcc
	v_add_f32_e32 v215, 0, v230
	v_ashrrev_i32_e32 v217, 31, v215
	v_pk_fma_f32 v[218:219], v[2:3], v[218:219], v[220:221] op_sel:[1,0,0]
	v_bitop3_b32 v215, v217, v215, s33 bitop3:0x36
	v_cmp_lt_i32_e32 vcc, 0, v231
	v_pk_add_f32 v[218:219], v[218:219], 0 op_sel_hi:[1,0]
	s_nop 0
	v_cndmask_b32_e32 v217, 0, v215, vcc
	v_ashrrev_i32_e32 v215, 31, v219
	v_ashrrev_i32_e32 v220, 31, v218
	v_or_b32_e32 v215, 0x80000000, v215
	v_or_b32_e32 v220, 0x80000000, v220
	v_xor_b32_e32 v215, v215, v219
	v_cmp_lt_i32_e32 vcc, 2, v231
	v_xor_b32_e32 v218, v220, v218
	s_nop 0
	v_cndmask_b32_e32 v219, 0, v215, vcc
	v_cmp_lt_i32_e32 vcc, 1, v231
	s_nop 1
	v_cndmask_b32_e32 v218, 0, v218, vcc
	ds_write_b128 v163, v[216:219] offset:8512
.LBB0_601:
	v_readlane_b32 s0, v254, 34
	s_cmp_gt_i32 s0, s75
	s_cbranch_scc1 .LBB0_603
	s_waitcnt vmcnt(0) lgkmcnt(7)
	v_mfma_f32_16x16x32_bf16 v[216:219], v[68:71], v[104:107], 0
	v_sub_u32_e32 v231, v108, v165
	v_cmp_lt_i32_e32 vcc, -1, v231
	s_nop 5
	v_max_f32_e32 v215, 0, v216
	v_max_f32_e32 v216, 0, v217
	v_fma_f32 v230, v4, v216, 0
	v_max_f32_e32 v220, 0, v218
	v_max_f32_e32 v221, 0, v219
	s_waitcnt lgkmcnt(6)
	v_mfma_f32_16x16x32_bf16 v[216:219], v[68:71], v[100:103], 0
	s_nop 0
	v_fma_f32 v215, v4, v215, 0
	s_nop 5
	v_max_f32_e32 v216, 0, v216
	v_fmac_f32_e32 v215, v5, v216
	v_max_f32_e32 v216, 0, v217
	v_fmac_f32_e32 v230, v5, v216
	v_max_f32_e32 v222, 0, v218
	v_max_f32_e32 v223, 0, v219
	s_waitcnt lgkmcnt(5)
	v_mfma_f32_16x16x32_bf16 v[216:219], v[68:71], v[96:99], 0
	s_nop 7
	v_max_f32_e32 v216, 0, v216
	v_fmac_f32_e32 v215, v6, v216
	v_max_f32_e32 v216, 0, v217
	v_fmac_f32_e32 v230, v6, v216
	v_max_f32_e32 v216, 0, v218
	v_max_f32_e32 v217, 0, v219
	v_pk_fma_f32 v[218:219], v[4:5], v[220:221], 0 op_sel_hi:[0,1,0]
	v_pk_fma_f32 v[218:219], v[4:5], v[222:223], v[218:219] op_sel:[1,0,0]
	s_nop 0
	v_pk_fma_f32 v[220:221], v[6:7], v[216:217], v[218:219] op_sel_hi:[0,1,1]
	s_waitcnt lgkmcnt(4)
	v_mfma_f32_16x16x32_bf16 v[216:219], v[68:71], v[92:95], 0
	s_nop 7
	v_max_f32_e32 v216, 0, v216
	v_fmac_f32_e32 v215, v7, v216
	v_max_f32_e32 v216, 0, v217
	v_fmac_f32_e32 v230, v7, v216
	v_max_f32_e32 v222, 0, v218
	v_max_f32_e32 v223, 0, v219
	s_waitcnt lgkmcnt(3)
	v_mfma_f32_16x16x32_bf16 v[216:219], v[68:71], v[88:91], 0
	v_fma_f32 v220, v7, v222, v220
	v_fma_f32 v221, v7, v223, v221
	s_nop 5
	v_max_f32_e32 v216, 0, v216
	v_fmac_f32_e32 v215, v0, v216
	v_max_f32_e32 v216, 0, v217
	v_fmac_f32_e32 v230, v0, v216
	v_max_f32_e32 v224, 0, v218
	v_max_f32_e32 v225, 0, v219
	s_waitcnt lgkmcnt(2)
	v_mfma_f32_16x16x32_bf16 v[216:219], v[68:71], v[84:87], 0
	v_fma_f32 v220, v0, v224, v220
	v_fma_f32 v221, v0, v225, v221
	s_nop 5
	v_max_f32_e32 v216, 0, v216
	v_fmac_f32_e32 v215, v1, v216
	v_max_f32_e32 v216, 0, v217
	v_fmac_f32_e32 v230, v1, v216
	v_max_f32_e32 v226, 0, v218
	v_max_f32_e32 v227, 0, v219
	s_waitcnt lgkmcnt(1)
	v_mfma_f32_16x16x32_bf16 v[216:219], v[68:71], v[80:83], 0
	v_fma_f32 v220, v1, v226, v220
	v_fma_f32 v221, v1, v227, v221
	s_nop 5
	v_max_f32_e32 v216, 0, v216
	v_fmac_f32_e32 v215, v2, v216
	v_max_f32_e32 v216, 0, v217
	v_fmac_f32_e32 v230, v2, v216
	v_max_f32_e32 v228, 0, v218
	v_max_f32_e32 v229, 0, v219
	s_waitcnt lgkmcnt(0)
	v_mfma_f32_16x16x32_bf16 v[216:219], v[68:71], v[76:79], 0
	v_fma_f32 v220, v2, v228, v220
	v_fma_f32 v221, v2, v229, v221
	s_nop 5
	v_max_f32_e32 v216, 0, v216
	v_fmac_f32_e32 v215, v3, v216
	v_max_f32_e32 v216, 0, v217
	v_fmac_f32_e32 v230, v3, v216
	v_max_f32_e32 v218, 0, v218
	v_max_f32_e32 v219, 0, v219
	v_add_f32_e32 v215, 0, v215
	v_ashrrev_i32_e32 v216, 31, v215
	v_bitop3_b32 v215, v216, v215, s33 bitop3:0x36
	v_cndmask_b32_e32 v216, 0, v215, vcc
	v_add_f32_e32 v215, 0, v230
	v_ashrrev_i32_e32 v217, 31, v215
	v_pk_fma_f32 v[218:219], v[2:3], v[218:219], v[220:221] op_sel:[1,0,0]
	v_bitop3_b32 v215, v217, v215, s33 bitop3:0x36
	v_cmp_lt_i32_e32 vcc, 0, v231
	v_pk_add_f32 v[218:219], v[218:219], 0 op_sel_hi:[1,0]
	s_nop 0
	v_cndmask_b32_e32 v217, 0, v215, vcc
	v_ashrrev_i32_e32 v215, 31, v219
	v_ashrrev_i32_e32 v220, 31, v218
	v_or_b32_e32 v215, 0x80000000, v215
	v_or_b32_e32 v220, 0x80000000, v220
	v_xor_b32_e32 v215, v215, v219
	v_cmp_lt_i32_e32 vcc, 2, v231
	v_xor_b32_e32 v218, v220, v218
	s_nop 0
	v_cndmask_b32_e32 v219, 0, v215, vcc
	v_cmp_lt_i32_e32 vcc, 1, v231
	s_nop 1
	v_cndmask_b32_e32 v218, 0, v218, vcc
	ds_write_b128 v166, v[216:219] offset:8448
.LBB0_603:
	v_readlane_b32 s0, v254, 34
	s_cmp_ge_i32 s0, s75
	s_cbranch_scc1 .LBB0_605
	s_waitcnt vmcnt(0) lgkmcnt(7)
	v_mfma_f32_16x16x32_bf16 v[104:107], v[72:75], v[104:107], 0
	s_waitcnt lgkmcnt(6)
	v_mfma_f32_16x16x32_bf16 v[100:103], v[72:75], v[100:103], 0
	s_waitcnt lgkmcnt(5)
	v_mfma_f32_16x16x32_bf16 v[96:99], v[72:75], v[96:99], 0
	s_nop 3
	v_max_f32_e32 v104, 0, v104
	s_nop 0
	v_max_f32_e32 v100, 0, v100
	s_waitcnt lgkmcnt(4)
	v_mfma_f32_16x16x32_bf16 v[92:95], v[72:75], v[92:95], 0
	v_max_f32_e32 v105, 0, v105
	v_fma_f32 v215, v4, v104, 0
	s_nop 0
	s_waitcnt lgkmcnt(3)
	v_mfma_f32_16x16x32_bf16 v[88:91], v[72:75], v[88:91], 0
	v_max_f32_e32 v96, 0, v96
	s_nop 0
	v_fmac_f32_e32 v215, v5, v100
	s_waitcnt lgkmcnt(2)
	v_mfma_f32_16x16x32_bf16 v[84:87], v[72:75], v[84:87], 0
	v_max_f32_e32 v100, 0, v101
	s_nop 0
	v_max_f32_e32 v92, 0, v92
	s_waitcnt lgkmcnt(1)
	v_mfma_f32_16x16x32_bf16 v[80:83], v[72:75], v[80:83], 0
	v_fma_f32 v216, v4, v105, 0
	s_nop 0
	v_fmac_f32_e32 v215, v6, v96
	s_waitcnt lgkmcnt(0)
	v_mfma_f32_16x16x32_bf16 v[76:79], v[72:75], v[76:79], 0
	v_max_f32_e32 v96, 0, v97
	s_nop 0
	v_max_f32_e32 v88, 0, v88
	v_fmac_f32_e32 v216, v5, v100
	s_nop 0
	v_fmac_f32_e32 v215, v7, v92
	v_max_f32_e32 v92, 0, v93
	s_nop 0
	v_max_f32_e32 v84, 0, v84
	v_fmac_f32_e32 v216, v6, v96
	s_nop 0
	v_fmac_f32_e32 v215, v0, v88
	v_max_f32_e32 v88, 0, v89
	s_nop 0
	v_max_f32_e32 v80, 0, v80
	v_fmac_f32_e32 v216, v7, v92
	s_nop 0
	v_fmac_f32_e32 v215, v1, v84
	v_max_f32_e32 v84, 0, v85
	s_nop 0
	v_max_f32_e32 v76, 0, v76
	v_fmac_f32_e32 v216, v0, v88
	v_fmac_f32_e32 v215, v2, v80
	v_max_f32_e32 v80, 0, v81
	v_fmac_f32_e32 v216, v1, v84
	v_fmac_f32_e32 v215, v3, v76
	v_max_f32_e32 v76, 0, v77
	v_fmac_f32_e32 v216, v2, v80
	v_fmac_f32_e32 v216, v3, v76
	v_max_f32_e32 v78, 0, v78
	v_max_f32_e32 v104, 0, v106
	v_max_f32_e32 v105, 0, v107
	v_max_f32_e32 v79, 0, v79
	v_max_f32_e32 v100, 0, v102
	v_max_f32_e32 v101, 0, v103
	v_add_f32_e32 v76, 0, v215
	v_max_f32_e32 v96, 0, v98
	v_max_f32_e32 v97, 0, v99
	v_pk_fma_f32 v[98:99], v[4:5], v[104:105], 0 op_sel_hi:[0,1,0]
	v_ashrrev_i32_e32 v77, 31, v76
	v_pk_fma_f32 v[98:99], v[4:5], v[100:101], v[98:99] op_sel:[1,0,0]
	v_max_f32_e32 v92, 0, v94
	v_max_f32_e32 v93, 0, v95
	v_bitop3_b32 v76, v77, v76, s33 bitop3:0x36
	v_add_f32_e32 v77, 0, v216
	v_pk_fma_f32 v[96:97], v[6:7], v[96:97], v[98:99] op_sel_hi:[0,1,1]
	v_max_f32_e32 v88, 0, v90
	v_max_f32_e32 v89, 0, v91
	v_max_f32_e32 v80, 0, v82
	v_ashrrev_i32_e32 v82, 31, v77
	v_max_f32_e32 v84, 0, v86
	v_max_f32_e32 v85, 0, v87
	v_max_f32_e32 v81, 0, v83
	v_bitop3_b32 v77, v82, v77, s33 bitop3:0x36
	v_pk_fma_f32 v[82:83], v[6:7], v[92:93], v[96:97] op_sel:[1,0,0]
	v_pk_fma_f32 v[82:83], v[0:1], v[88:89], v[82:83] op_sel_hi:[0,1,1]
	v_pk_fma_f32 v[82:83], v[0:1], v[84:85], v[82:83] op_sel:[1,0,0]
	v_sub_u32_e32 v86, v108, v167
	v_pk_fma_f32 v[80:81], v[2:3], v[80:81], v[82:83] op_sel_hi:[0,1,1]
	v_pk_fma_f32 v[78:79], v[2:3], v[78:79], v[80:81] op_sel:[1,0,0]
	v_cmp_lt_i32_e32 vcc, -1, v86
	v_pk_add_f32 v[78:79], v[78:79], 0 op_sel_hi:[1,0]
	s_nop 0
	v_ashrrev_i32_e32 v80, 31, v79
	v_cndmask_b32_e32 v76, 0, v76, vcc
	v_cmp_lt_i32_e32 vcc, 0, v86
	v_ashrrev_i32_e32 v81, 31, v78
	v_or_b32_e32 v80, 0x80000000, v80
	v_cndmask_b32_e32 v77, 0, v77, vcc
	v_or_b32_e32 v81, 0x80000000, v81
	v_xor_b32_e32 v79, v80, v79
	v_cmp_lt_i32_e32 vcc, 2, v86
	v_xor_b32_e32 v78, v81, v78
	s_nop 0
	v_cndmask_b32_e32 v79, 0, v79, vcc
	v_cmp_lt_i32_e32 vcc, 1, v86
	s_nop 1
	v_cndmask_b32_e32 v78, 0, v78, vcc
	ds_write_b128 v166, v[76:79] offset:8512

.LBB0_609:
	s_waitcnt vmcnt(0) lgkmcnt(7)
	v_mfma_f32_16x16x32_bf16 v[216:219], v[20:23], v[104:107], 0
	v_sub_u32_e32 v231, v108, v147
	v_cmp_lt_i32_e32 vcc, -1, v231
	s_nop 5
	v_max_f32_e32 v215, 0, v216
	v_max_f32_e32 v216, 0, v217
	v_fma_f32 v230, v4, v216, 0
	v_max_f32_e32 v220, 0, v218
	v_max_f32_e32 v221, 0, v219
	s_waitcnt lgkmcnt(6)
	v_mfma_f32_16x16x32_bf16 v[216:219], v[20:23], v[100:103], 0
	s_nop 0
	v_fma_f32 v215, v4, v215, 0
	s_nop 5
	v_max_f32_e32 v216, 0, v216
	v_fmac_f32_e32 v215, v5, v216
	v_max_f32_e32 v216, 0, v217
	v_fmac_f32_e32 v230, v5, v216
	v_max_f32_e32 v222, 0, v218
	v_max_f32_e32 v223, 0, v219
	s_waitcnt lgkmcnt(5)
	v_mfma_f32_16x16x32_bf16 v[216:219], v[20:23], v[96:99], 0
	s_nop 7
	v_max_f32_e32 v216, 0, v216
	v_fmac_f32_e32 v215, v6, v216
	v_max_f32_e32 v216, 0, v217
	v_fmac_f32_e32 v230, v6, v216
	v_max_f32_e32 v216, 0, v218
	v_max_f32_e32 v217, 0, v219
	v_pk_fma_f32 v[218:219], v[4:5], v[220:221], 0 op_sel_hi:[0,1,0]
	v_pk_fma_f32 v[218:219], v[4:5], v[222:223], v[218:219] op_sel:[1,0,0]
	s_nop 0
	v_pk_fma_f32 v[220:221], v[6:7], v[216:217], v[218:219] op_sel_hi:[0,1,1]
	s_waitcnt lgkmcnt(4)
	v_mfma_f32_16x16x32_bf16 v[216:219], v[20:23], v[92:95], 0
	s_nop 7
	v_max_f32_e32 v216, 0, v216
	v_fmac_f32_e32 v215, v7, v216
	v_max_f32_e32 v216, 0, v217
	v_fmac_f32_e32 v230, v7, v216
	v_max_f32_e32 v222, 0, v218
	v_max_f32_e32 v223, 0, v219
	s_waitcnt lgkmcnt(3)
	v_mfma_f32_16x16x32_bf16 v[216:219], v[20:23], v[88:91], 0
	v_fma_f32 v220, v7, v222, v220
	v_fma_f32 v221, v7, v223, v221
	s_nop 5
	v_max_f32_e32 v216, 0, v216
	v_fmac_f32_e32 v215, v0, v216
	v_max_f32_e32 v216, 0, v217
	v_fmac_f32_e32 v230, v0, v216
	v_max_f32_e32 v224, 0, v218
	v_max_f32_e32 v225, 0, v219
	s_waitcnt lgkmcnt(2)
	v_mfma_f32_16x16x32_bf16 v[216:219], v[20:23], v[84:87], 0
	v_fma_f32 v220, v0, v224, v220
	v_fma_f32 v221, v0, v225, v221
	s_nop 5
	v_max_f32_e32 v216, 0, v216
	v_fmac_f32_e32 v215, v1, v216
	v_max_f32_e32 v216, 0, v217
	v_fmac_f32_e32 v230, v1, v216
	v_max_f32_e32 v226, 0, v218
	v_max_f32_e32 v227, 0, v219
	s_waitcnt lgkmcnt(1)
	v_mfma_f32_16x16x32_bf16 v[216:219], v[20:23], v[80:83], 0
	v_fma_f32 v220, v1, v226, v220
	v_fma_f32 v221, v1, v227, v221
	s_nop 5
	v_max_f32_e32 v216, 0, v216
	v_fmac_f32_e32 v215, v2, v216
	v_max_f32_e32 v216, 0, v217
	v_fmac_f32_e32 v230, v2, v216
	v_max_f32_e32 v228, 0, v218
	v_max_f32_e32 v229, 0, v219
	s_waitcnt lgkmcnt(0)
	v_mfma_f32_16x16x32_bf16 v[216:219], v[20:23], v[76:79], 0
	v_fma_f32 v220, v2, v228, v220
	v_fma_f32 v221, v2, v229, v221
	s_nop 5
	v_max_f32_e32 v216, 0, v216
	v_fmac_f32_e32 v215, v3, v216
	v_max_f32_e32 v216, 0, v217
	v_fmac_f32_e32 v230, v3, v216
	v_max_f32_e32 v218, 0, v218
	v_max_f32_e32 v219, 0, v219
	v_add_f32_e32 v215, 0, v215
	v_ashrrev_i32_e32 v216, 31, v215
	v_bitop3_b32 v215, v216, v215, s33 bitop3:0x36
	v_cndmask_b32_e32 v216, 0, v215, vcc
	v_add_f32_e32 v215, 0, v230
	v_ashrrev_i32_e32 v217, 31, v215
	v_pk_fma_f32 v[218:219], v[2:3], v[218:219], v[220:221] op_sel:[1,0,0]
	v_bitop3_b32 v215, v217, v215, s33 bitop3:0x36
	v_cmp_lt_i32_e32 vcc, 0, v231
	v_pk_add_f32 v[218:219], v[218:219], 0 op_sel_hi:[1,0]
	s_nop 0
	v_cndmask_b32_e32 v217, 0, v215, vcc
	v_ashrrev_i32_e32 v215, 31, v219
	v_ashrrev_i32_e32 v220, 31, v218
	v_or_b32_e32 v215, 0x80000000, v215
	v_or_b32_e32 v220, 0x80000000, v220
	v_xor_b32_e32 v215, v215, v219
	v_cmp_lt_i32_e32 vcc, 2, v231
	v_xor_b32_e32 v218, v220, v218
	s_nop 0
	v_cndmask_b32_e32 v219, 0, v215, vcc
	v_cmp_lt_i32_e32 vcc, 1, v231
	s_nop 1
	v_cndmask_b32_e32 v218, 0, v218, vcc
	ds_write_b128 v148, v[216:219] offset:8448
	s_cmp_ge_i32 s83, s75
	s_cbranch_scc0 .LBB0_590

.LBB0_611:
	s_waitcnt vmcnt(0) lgkmcnt(7)
	v_mfma_f32_16x16x32_bf16 v[216:219], v[28:31], v[104:107], 0
	v_sub_u32_e32 v231, v108, v150
	v_cmp_lt_i32_e32 vcc, -1, v231
	s_nop 5
	v_max_f32_e32 v215, 0, v216
	v_max_f32_e32 v216, 0, v217
	v_fma_f32 v230, v4, v216, 0
	v_max_f32_e32 v220, 0, v218
	v_max_f32_e32 v221, 0, v219
	s_waitcnt lgkmcnt(6)
	v_mfma_f32_16x16x32_bf16 v[216:219], v[28:31], v[100:103], 0
	s_nop 0
	v_fma_f32 v215, v4, v215, 0
	s_nop 5
	v_max_f32_e32 v216, 0, v216
	v_fmac_f32_e32 v215, v5, v216
	v_max_f32_e32 v216, 0, v217
	v_fmac_f32_e32 v230, v5, v216
	v_max_f32_e32 v222, 0, v218
	v_max_f32_e32 v223, 0, v219
	s_waitcnt lgkmcnt(5)
	v_mfma_f32_16x16x32_bf16 v[216:219], v[28:31], v[96:99], 0
	s_nop 7
	v_max_f32_e32 v216, 0, v216
	v_fmac_f32_e32 v215, v6, v216
	v_max_f32_e32 v216, 0, v217
	v_fmac_f32_e32 v230, v6, v216
	v_max_f32_e32 v216, 0, v218
	v_max_f32_e32 v217, 0, v219
	v_pk_fma_f32 v[218:219], v[4:5], v[220:221], 0 op_sel_hi:[0,1,0]
	v_pk_fma_f32 v[218:219], v[4:5], v[222:223], v[218:219] op_sel:[1,0,0]
	s_nop 0
	v_pk_fma_f32 v[220:221], v[6:7], v[216:217], v[218:219] op_sel_hi:[0,1,1]
	s_waitcnt lgkmcnt(4)
	v_mfma_f32_16x16x32_bf16 v[216:219], v[28:31], v[92:95], 0
	s_nop 7
	v_max_f32_e32 v216, 0, v216
	v_fmac_f32_e32 v215, v7, v216
	v_max_f32_e32 v216, 0, v217
	v_fmac_f32_e32 v230, v7, v216
	v_max_f32_e32 v222, 0, v218
	v_max_f32_e32 v223, 0, v219
	s_waitcnt lgkmcnt(3)
	v_mfma_f32_16x16x32_bf16 v[216:219], v[28:31], v[88:91], 0
	v_fma_f32 v220, v7, v222, v220
	v_fma_f32 v221, v7, v223, v221
	s_nop 5
	v_max_f32_e32 v216, 0, v216
	v_fmac_f32_e32 v215, v0, v216
	v_max_f32_e32 v216, 0, v217
	v_fmac_f32_e32 v230, v0, v216
	v_max_f32_e32 v224, 0, v218
	v_max_f32_e32 v225, 0, v219
	s_waitcnt lgkmcnt(2)
	v_mfma_f32_16x16x32_bf16 v[216:219], v[28:31], v[84:87], 0
	v_fma_f32 v220, v0, v224, v220
	v_fma_f32 v221, v0, v225, v221
	s_nop 5
	v_max_f32_e32 v216, 0, v216
	v_fmac_f32_e32 v215, v1, v216
	v_max_f32_e32 v216, 0, v217
	v_fmac_f32_e32 v230, v1, v216
	v_max_f32_e32 v226, 0, v218
	v_max_f32_e32 v227, 0, v219
	s_waitcnt lgkmcnt(1)
	v_mfma_f32_16x16x32_bf16 v[216:219], v[28:31], v[80:83], 0
	v_fma_f32 v220, v1, v226, v220
	v_fma_f32 v221, v1, v227, v221
	s_nop 5
	v_max_f32_e32 v216, 0, v216
	v_fmac_f32_e32 v215, v2, v216
	v_max_f32_e32 v216, 0, v217
	v_fmac_f32_e32 v230, v2, v216
	v_max_f32_e32 v228, 0, v218
	v_max_f32_e32 v229, 0, v219
	s_waitcnt lgkmcnt(0)
	v_mfma_f32_16x16x32_bf16 v[216:219], v[28:31], v[76:79], 0
	v_fma_f32 v220, v2, v228, v220
	v_fma_f32 v221, v2, v229, v221
	s_nop 5
	v_max_f32_e32 v216, 0, v216
	v_fmac_f32_e32 v215, v3, v216
	v_max_f32_e32 v216, 0, v217
	v_fmac_f32_e32 v230, v3, v216
	v_max_f32_e32 v218, 0, v218
	v_max_f32_e32 v219, 0, v219
	v_add_f32_e32 v215, 0, v215
	v_ashrrev_i32_e32 v216, 31, v215
	v_bitop3_b32 v215, v216, v215, s33 bitop3:0x36
	v_cndmask_b32_e32 v216, 0, v215, vcc
	v_add_f32_e32 v215, 0, v230
	v_ashrrev_i32_e32 v217, 31, v215
	v_pk_fma_f32 v[218:219], v[2:3], v[218:219], v[220:221] op_sel:[1,0,0]
	v_bitop3_b32 v215, v217, v215, s33 bitop3:0x36
	v_cmp_lt_i32_e32 vcc, 0, v231
	v_pk_add_f32 v[218:219], v[218:219], 0 op_sel_hi:[1,0]
	s_nop 0
	v_cndmask_b32_e32 v217, 0, v215, vcc
	v_ashrrev_i32_e32 v215, 31, v219
	v_ashrrev_i32_e32 v220, 31, v218
	v_or_b32_e32 v215, 0x80000000, v215
	v_or_b32_e32 v220, 0x80000000, v220
	v_xor_b32_e32 v215, v215, v219
	v_cmp_lt_i32_e32 vcc, 2, v231
	v_xor_b32_e32 v218, v220, v218
	s_nop 0
	v_cndmask_b32_e32 v219, 0, v215, vcc
	v_cmp_lt_i32_e32 vcc, 1, v231
	s_nop 1
	v_cndmask_b32_e32 v218, 0, v218, vcc
	ds_write_b128 v151, v[216:219] offset:8448
	s_cmp_ge_i32 s84, s75
	s_cbranch_scc0 .LBB0_592

.LBB0_613:
	s_waitcnt vmcnt(0) lgkmcnt(7)
	v_mfma_f32_16x16x32_bf16 v[216:219], v[36:39], v[104:107], 0
	v_sub_u32_e32 v231, v108, v153
	v_cmp_lt_i32_e32 vcc, -1, v231
	s_nop 5
	v_max_f32_e32 v215, 0, v216
	v_max_f32_e32 v216, 0, v217
	v_fma_f32 v230, v4, v216, 0
	v_max_f32_e32 v220, 0, v218
	v_max_f32_e32 v221, 0, v219
	s_waitcnt lgkmcnt(6)
	v_mfma_f32_16x16x32_bf16 v[216:219], v[36:39], v[100:103], 0
	s_nop 0
	v_fma_f32 v215, v4, v215, 0
	s_nop 5
	v_max_f32_e32 v216, 0, v216
	v_fmac_f32_e32 v215, v5, v216
	v_max_f32_e32 v216, 0, v217
	v_fmac_f32_e32 v230, v5, v216
	v_max_f32_e32 v222, 0, v218
	v_max_f32_e32 v223, 0, v219
	s_waitcnt lgkmcnt(5)
	v_mfma_f32_16x16x32_bf16 v[216:219], v[36:39], v[96:99], 0
	s_nop 7
	v_max_f32_e32 v216, 0, v216
	v_fmac_f32_e32 v215, v6, v216
	v_max_f32_e32 v216, 0, v217
	v_fmac_f32_e32 v230, v6, v216
	v_max_f32_e32 v216, 0, v218
	v_max_f32_e32 v217, 0, v219
	v_pk_fma_f32 v[218:219], v[4:5], v[220:221], 0 op_sel_hi:[0,1,0]
	v_pk_fma_f32 v[218:219], v[4:5], v[222:223], v[218:219] op_sel:[1,0,0]
	s_nop 0
	v_pk_fma_f32 v[220:221], v[6:7], v[216:217], v[218:219] op_sel_hi:[0,1,1]
	s_waitcnt lgkmcnt(4)
	v_mfma_f32_16x16x32_bf16 v[216:219], v[36:39], v[92:95], 0
	s_nop 7
	v_max_f32_e32 v216, 0, v216
	v_fmac_f32_e32 v215, v7, v216
	v_max_f32_e32 v216, 0, v217
	v_fmac_f32_e32 v230, v7, v216
	v_max_f32_e32 v222, 0, v218
	v_max_f32_e32 v223, 0, v219
	s_waitcnt lgkmcnt(3)
	v_mfma_f32_16x16x32_bf16 v[216:219], v[36:39], v[88:91], 0
	v_fma_f32 v220, v7, v222, v220
	v_fma_f32 v221, v7, v223, v221
	s_nop 5
	v_max_f32_e32 v216, 0, v216
	v_fmac_f32_e32 v215, v0, v216
	v_max_f32_e32 v216, 0, v217
	v_fmac_f32_e32 v230, v0, v216
	v_max_f32_e32 v224, 0, v218
	v_max_f32_e32 v225, 0, v219
	s_waitcnt lgkmcnt(2)
	v_mfma_f32_16x16x32_bf16 v[216:219], v[36:39], v[84:87], 0
	v_fma_f32 v220, v0, v224, v220
	v_fma_f32 v221, v0, v225, v221
	s_nop 5
	v_max_f32_e32 v216, 0, v216
	v_fmac_f32_e32 v215, v1, v216
	v_max_f32_e32 v216, 0, v217
	v_fmac_f32_e32 v230, v1, v216
	v_max_f32_e32 v226, 0, v218
	v_max_f32_e32 v227, 0, v219
	s_waitcnt lgkmcnt(1)
	v_mfma_f32_16x16x32_bf16 v[216:219], v[36:39], v[80:83], 0
	v_fma_f32 v220, v1, v226, v220
	v_fma_f32 v221, v1, v227, v221
	s_nop 5
	v_max_f32_e32 v216, 0, v216
	v_fmac_f32_e32 v215, v2, v216
	v_max_f32_e32 v216, 0, v217
	v_fmac_f32_e32 v230, v2, v216
	v_max_f32_e32 v228, 0, v218
	v_max_f32_e32 v229, 0, v219
	s_waitcnt lgkmcnt(0)
	v_mfma_f32_16x16x32_bf16 v[216:219], v[36:39], v[76:79], 0
	v_fma_f32 v220, v2, v228, v220
	v_fma_f32 v221, v2, v229, v221
	s_nop 5
	v_max_f32_e32 v216, 0, v216
	v_fmac_f32_e32 v215, v3, v216
	v_max_f32_e32 v216, 0, v217
	v_fmac_f32_e32 v230, v3, v216
	v_max_f32_e32 v218, 0, v218
	v_max_f32_e32 v219, 0, v219
	v_add_f32_e32 v215, 0, v215
	v_ashrrev_i32_e32 v216, 31, v215
	v_bitop3_b32 v215, v216, v215, s33 bitop3:0x36
	v_cndmask_b32_e32 v216, 0, v215, vcc
	v_add_f32_e32 v215, 0, v230
	v_ashrrev_i32_e32 v217, 31, v215
	v_pk_fma_f32 v[218:219], v[2:3], v[218:219], v[220:221] op_sel:[1,0,0]
	v_bitop3_b32 v215, v217, v215, s33 bitop3:0x36
	v_cmp_lt_i32_e32 vcc, 0, v231
	v_pk_add_f32 v[218:219], v[218:219], 0 op_sel_hi:[1,0]
	s_nop 0
	v_cndmask_b32_e32 v217, 0, v215, vcc
	v_ashrrev_i32_e32 v215, 31, v219
	v_ashrrev_i32_e32 v220, 31, v218
	v_or_b32_e32 v215, 0x80000000, v215
	v_or_b32_e32 v220, 0x80000000, v220
	v_xor_b32_e32 v215, v215, v219
	v_cmp_lt_i32_e32 vcc, 2, v231
	v_xor_b32_e32 v218, v220, v218
	s_nop 0
	v_cndmask_b32_e32 v219, 0, v215, vcc
	v_cmp_lt_i32_e32 vcc, 1, v231
	s_nop 1
	v_cndmask_b32_e32 v218, 0, v218, vcc
	ds_write_b128 v154, v[216:219] offset:8448
	s_cmp_ge_i32 s10, s75
	s_cbranch_scc0 .LBB0_594

.LBB0_615:
	s_waitcnt vmcnt(0) lgkmcnt(7)
	v_mfma_f32_16x16x32_bf16 v[216:219], v[44:47], v[104:107], 0
	v_sub_u32_e32 v231, v108, v156
	v_cmp_lt_i32_e32 vcc, -1, v231
	s_nop 5
	v_max_f32_e32 v215, 0, v216
	v_max_f32_e32 v216, 0, v217
	v_fma_f32 v230, v4, v216, 0
	v_max_f32_e32 v220, 0, v218
	v_max_f32_e32 v221, 0, v219
	s_waitcnt lgkmcnt(6)
	v_mfma_f32_16x16x32_bf16 v[216:219], v[44:47], v[100:103], 0
	s_nop 0
	v_fma_f32 v215, v4, v215, 0
	s_nop 5
	v_max_f32_e32 v216, 0, v216
	v_fmac_f32_e32 v215, v5, v216
	v_max_f32_e32 v216, 0, v217
	v_fmac_f32_e32 v230, v5, v216
	v_max_f32_e32 v222, 0, v218
	v_max_f32_e32 v223, 0, v219
	s_waitcnt lgkmcnt(5)
	v_mfma_f32_16x16x32_bf16 v[216:219], v[44:47], v[96:99], 0
	s_nop 7
	v_max_f32_e32 v216, 0, v216
	v_fmac_f32_e32 v215, v6, v216
	v_max_f32_e32 v216, 0, v217
	v_fmac_f32_e32 v230, v6, v216
	v_max_f32_e32 v216, 0, v218
	v_max_f32_e32 v217, 0, v219
	v_pk_fma_f32 v[218:219], v[4:5], v[220:221], 0 op_sel_hi:[0,1,0]
	v_pk_fma_f32 v[218:219], v[4:5], v[222:223], v[218:219] op_sel:[1,0,0]
	s_nop 0
	v_pk_fma_f32 v[220:221], v[6:7], v[216:217], v[218:219] op_sel_hi:[0,1,1]
	s_waitcnt lgkmcnt(4)
	v_mfma_f32_16x16x32_bf16 v[216:219], v[44:47], v[92:95], 0
	s_nop 7
	v_max_f32_e32 v216, 0, v216
	v_fmac_f32_e32 v215, v7, v216
	v_max_f32_e32 v216, 0, v217
	v_fmac_f32_e32 v230, v7, v216
	v_max_f32_e32 v222, 0, v218
	v_max_f32_e32 v223, 0, v219
	s_waitcnt lgkmcnt(3)
	v_mfma_f32_16x16x32_bf16 v[216:219], v[44:47], v[88:91], 0
	v_fma_f32 v220, v7, v222, v220
	v_fma_f32 v221, v7, v223, v221
	s_nop 5
	v_max_f32_e32 v216, 0, v216
	v_fmac_f32_e32 v215, v0, v216
	v_max_f32_e32 v216, 0, v217
	v_fmac_f32_e32 v230, v0, v216
	v_max_f32_e32 v224, 0, v218
	v_max_f32_e32 v225, 0, v219
	s_waitcnt lgkmcnt(2)
	v_mfma_f32_16x16x32_bf16 v[216:219], v[44:47], v[84:87], 0
	v_fma_f32 v220, v0, v224, v220
	v_fma_f32 v221, v0, v225, v221
	s_nop 5
	v_max_f32_e32 v216, 0, v216
	v_fmac_f32_e32 v215, v1, v216
	v_max_f32_e32 v216, 0, v217
	v_fmac_f32_e32 v230, v1, v216
	v_max_f32_e32 v226, 0, v218
	v_max_f32_e32 v227, 0, v219
	s_waitcnt lgkmcnt(1)
	v_mfma_f32_16x16x32_bf16 v[216:219], v[44:47], v[80:83], 0
	v_fma_f32 v220, v1, v226, v220
	v_fma_f32 v221, v1, v227, v221
	s_nop 5
	v_max_f32_e32 v216, 0, v216
	v_fmac_f32_e32 v215, v2, v216
	v_max_f32_e32 v216, 0, v217
	v_fmac_f32_e32 v230, v2, v216
	v_max_f32_e32 v228, 0, v218
	v_max_f32_e32 v229, 0, v219
	s_waitcnt lgkmcnt(0)
	v_mfma_f32_16x16x32_bf16 v[216:219], v[44:47], v[76:79], 0
	v_fma_f32 v220, v2, v228, v220
	v_fma_f32 v221, v2, v229, v221
	s_nop 5
	v_max_f32_e32 v216, 0, v216
	v_fmac_f32_e32 v215, v3, v216
	v_max_f32_e32 v216, 0, v217
	v_fmac_f32_e32 v230, v3, v216
	v_max_f32_e32 v218, 0, v218
	v_max_f32_e32 v219, 0, v219
	v_add_f32_e32 v215, 0, v215
	v_ashrrev_i32_e32 v216, 31, v215
	v_bitop3_b32 v215, v216, v215, s33 bitop3:0x36
	v_cndmask_b32_e32 v216, 0, v215, vcc
	v_add_f32_e32 v215, 0, v230
	v_ashrrev_i32_e32 v217, 31, v215
	v_pk_fma_f32 v[218:219], v[2:3], v[218:219], v[220:221] op_sel:[1,0,0]
	v_bitop3_b32 v215, v217, v215, s33 bitop3:0x36
	v_cmp_lt_i32_e32 vcc, 0, v231
	v_pk_add_f32 v[218:219], v[218:219], 0 op_sel_hi:[1,0]
	s_nop 0
	v_cndmask_b32_e32 v217, 0, v215, vcc
	v_ashrrev_i32_e32 v215, 31, v219
	v_ashrrev_i32_e32 v220, 31, v218
	v_or_b32_e32 v215, 0x80000000, v215
	v_or_b32_e32 v220, 0x80000000, v220
	v_xor_b32_e32 v215, v215, v219
	v_cmp_lt_i32_e32 vcc, 2, v231
	v_xor_b32_e32 v218, v220, v218
	s_nop 0
	v_cndmask_b32_e32 v219, 0, v215, vcc
	v_cmp_lt_i32_e32 vcc, 1, v231
	s_nop 1
	v_cndmask_b32_e32 v218, 0, v218, vcc
	ds_write_b128 v157, v[216:219] offset:8448
	s_cmp_ge_i32 s12, s75
	s_cbranch_scc0 .LBB0_596

.LBB0_617:
	s_waitcnt vmcnt(0) lgkmcnt(7)
	v_mfma_f32_16x16x32_bf16 v[216:219], v[52:55], v[104:107], 0
	v_sub_u32_e32 v231, v108, v159
	v_cmp_lt_i32_e32 vcc, -1, v231
	s_nop 5
	v_max_f32_e32 v215, 0, v216
	v_max_f32_e32 v216, 0, v217
	v_fma_f32 v230, v4, v216, 0
	v_max_f32_e32 v220, 0, v218
	v_max_f32_e32 v221, 0, v219
	s_waitcnt lgkmcnt(6)
	v_mfma_f32_16x16x32_bf16 v[216:219], v[52:55], v[100:103], 0
	s_nop 0
	v_fma_f32 v215, v4, v215, 0
	s_nop 5
	v_max_f32_e32 v216, 0, v216
	v_fmac_f32_e32 v215, v5, v216
	v_max_f32_e32 v216, 0, v217
	v_fmac_f32_e32 v230, v5, v216
	v_max_f32_e32 v222, 0, v218
	v_max_f32_e32 v223, 0, v219
	s_waitcnt lgkmcnt(5)
	v_mfma_f32_16x16x32_bf16 v[216:219], v[52:55], v[96:99], 0
	s_nop 7
	v_max_f32_e32 v216, 0, v216
	v_fmac_f32_e32 v215, v6, v216
	v_max_f32_e32 v216, 0, v217
	v_fmac_f32_e32 v230, v6, v216
	v_max_f32_e32 v216, 0, v218
	v_max_f32_e32 v217, 0, v219
	v_pk_fma_f32 v[218:219], v[4:5], v[220:221], 0 op_sel_hi:[0,1,0]
	v_pk_fma_f32 v[218:219], v[4:5], v[222:223], v[218:219] op_sel:[1,0,0]
	s_nop 0
	v_pk_fma_f32 v[220:221], v[6:7], v[216:217], v[218:219] op_sel_hi:[0,1,1]
	s_waitcnt lgkmcnt(4)
	v_mfma_f32_16x16x32_bf16 v[216:219], v[52:55], v[92:95], 0
	s_nop 7
	v_max_f32_e32 v216, 0, v216
	v_fmac_f32_e32 v215, v7, v216
	v_max_f32_e32 v216, 0, v217
	v_fmac_f32_e32 v230, v7, v216
	v_max_f32_e32 v222, 0, v218
	v_max_f32_e32 v223, 0, v219
	s_waitcnt lgkmcnt(3)
	v_mfma_f32_16x16x32_bf16 v[216:219], v[52:55], v[88:91], 0
	v_fma_f32 v220, v7, v222, v220
	v_fma_f32 v221, v7, v223, v221
	s_nop 5
	v_max_f32_e32 v216, 0, v216
	v_fmac_f32_e32 v215, v0, v216
	v_max_f32_e32 v216, 0, v217
	v_fmac_f32_e32 v230, v0, v216
	v_max_f32_e32 v224, 0, v218
	v_max_f32_e32 v225, 0, v219
	s_waitcnt lgkmcnt(2)
	v_mfma_f32_16x16x32_bf16 v[216:219], v[52:55], v[84:87], 0
	v_fma_f32 v220, v0, v224, v220
	v_fma_f32 v221, v0, v225, v221
	s_nop 5
	v_max_f32_e32 v216, 0, v216
	v_fmac_f32_e32 v215, v1, v216
	v_max_f32_e32 v216, 0, v217
	v_fmac_f32_e32 v230, v1, v216
	v_max_f32_e32 v226, 0, v218
	v_max_f32_e32 v227, 0, v219
	s_waitcnt lgkmcnt(1)
	v_mfma_f32_16x16x32_bf16 v[216:219], v[52:55], v[80:83], 0
	v_fma_f32 v220, v1, v226, v220
	v_fma_f32 v221, v1, v227, v221
	s_nop 5
	v_max_f32_e32 v216, 0, v216
	v_fmac_f32_e32 v215, v2, v216
	v_max_f32_e32 v216, 0, v217
	v_fmac_f32_e32 v230, v2, v216
	v_max_f32_e32 v228, 0, v218
	v_max_f32_e32 v229, 0, v219
	s_waitcnt lgkmcnt(0)
	v_mfma_f32_16x16x32_bf16 v[216:219], v[52:55], v[76:79], 0
	v_fma_f32 v220, v2, v228, v220
	v_fma_f32 v221, v2, v229, v221
	s_nop 5
	v_max_f32_e32 v216, 0, v216
	v_fmac_f32_e32 v215, v3, v216
	v_max_f32_e32 v216, 0, v217
	v_fmac_f32_e32 v230, v3, v216
	v_max_f32_e32 v218, 0, v218
	v_max_f32_e32 v219, 0, v219
	v_add_f32_e32 v215, 0, v215
	v_ashrrev_i32_e32 v216, 31, v215
	v_bitop3_b32 v215, v216, v215, s33 bitop3:0x36
	v_cndmask_b32_e32 v216, 0, v215, vcc
	v_add_f32_e32 v215, 0, v230
	v_ashrrev_i32_e32 v217, 31, v215
	v_pk_fma_f32 v[218:219], v[2:3], v[218:219], v[220:221] op_sel:[1,0,0]
	v_bitop3_b32 v215, v217, v215, s33 bitop3:0x36
	v_cmp_lt_i32_e32 vcc, 0, v231
	v_pk_add_f32 v[218:219], v[218:219], 0 op_sel_hi:[1,0]
	s_nop 0
	v_cndmask_b32_e32 v217, 0, v215, vcc
	v_ashrrev_i32_e32 v215, 31, v219
	v_ashrrev_i32_e32 v220, 31, v218
	v_or_b32_e32 v215, 0x80000000, v215
	v_or_b32_e32 v220, 0x80000000, v220
	v_xor_b32_e32 v215, v215, v219
	v_cmp_lt_i32_e32 vcc, 2, v231
	v_xor_b32_e32 v218, v220, v218
	s_nop 0
	v_cndmask_b32_e32 v219, 0, v215, vcc
	v_cmp_lt_i32_e32 vcc, 1, v231
	s_nop 1
	v_cndmask_b32_e32 v218, 0, v218, vcc
	ds_write_b128 v160, v[216:219] offset:8448
	s_cmp_ge_i32 s13, s75
	s_cbranch_scc0 .LBB0_598

.LBB0_619:
	s_waitcnt vmcnt(0) lgkmcnt(7)
	v_mfma_f32_16x16x32_bf16 v[216:219], v[60:63], v[104:107], 0
	v_sub_u32_e32 v231, v108, v162
	v_cmp_lt_i32_e32 vcc, -1, v231
	s_nop 5
	v_max_f32_e32 v215, 0, v216
	v_max_f32_e32 v216, 0, v217
	v_fma_f32 v230, v4, v216, 0
	v_max_f32_e32 v220, 0, v218
	v_max_f32_e32 v221, 0, v219
	s_waitcnt lgkmcnt(6)
	v_mfma_f32_16x16x32_bf16 v[216:219], v[60:63], v[100:103], 0
	s_nop 0
	v_fma_f32 v215, v4, v215, 0
	s_nop 5
	v_max_f32_e32 v216, 0, v216
	v_fmac_f32_e32 v215, v5, v216
	v_max_f32_e32 v216, 0, v217
	v_fmac_f32_e32 v230, v5, v216
	v_max_f32_e32 v222, 0, v218
	v_max_f32_e32 v223, 0, v219
	s_waitcnt lgkmcnt(5)
	v_mfma_f32_16x16x32_bf16 v[216:219], v[60:63], v[96:99], 0
	s_nop 7
	v_max_f32_e32 v216, 0, v216
	v_fmac_f32_e32 v215, v6, v216
	v_max_f32_e32 v216, 0, v217
	v_fmac_f32_e32 v230, v6, v216
	v_max_f32_e32 v216, 0, v218
	v_max_f32_e32 v217, 0, v219
	v_pk_fma_f32 v[218:219], v[4:5], v[220:221], 0 op_sel_hi:[0,1,0]
	v_pk_fma_f32 v[218:219], v[4:5], v[222:223], v[218:219] op_sel:[1,0,0]
	s_nop 0
	v_pk_fma_f32 v[220:221], v[6:7], v[216:217], v[218:219] op_sel_hi:[0,1,1]
	s_waitcnt lgkmcnt(4)
	v_mfma_f32_16x16x32_bf16 v[216:219], v[60:63], v[92:95], 0
	s_nop 7
	v_max_f32_e32 v216, 0, v216
	v_fmac_f32_e32 v215, v7, v216
	v_max_f32_e32 v216, 0, v217
	v_fmac_f32_e32 v230, v7, v216
	v_max_f32_e32 v222, 0, v218
	v_max_f32_e32 v223, 0, v219
	s_waitcnt lgkmcnt(3)
	v_mfma_f32_16x16x32_bf16 v[216:219], v[60:63], v[88:91], 0
	v_fma_f32 v220, v7, v222, v220
	v_fma_f32 v221, v7, v223, v221
	s_nop 5
	v_max_f32_e32 v216, 0, v216
	v_fmac_f32_e32 v215, v0, v216
	v_max_f32_e32 v216, 0, v217
	v_fmac_f32_e32 v230, v0, v216
	v_max_f32_e32 v224, 0, v218
	v_max_f32_e32 v225, 0, v219
	s_waitcnt lgkmcnt(2)
	v_mfma_f32_16x16x32_bf16 v[216:219], v[60:63], v[84:87], 0
	v_fma_f32 v220, v0, v224, v220
	v_fma_f32 v221, v0, v225, v221
	s_nop 5
	v_max_f32_e32 v216, 0, v216
	v_fmac_f32_e32 v215, v1, v216
	v_max_f32_e32 v216, 0, v217
	v_fmac_f32_e32 v230, v1, v216
	v_max_f32_e32 v226, 0, v218
	v_max_f32_e32 v227, 0, v219
	s_waitcnt lgkmcnt(1)
	v_mfma_f32_16x16x32_bf16 v[216:219], v[60:63], v[80:83], 0
	v_fma_f32 v220, v1, v226, v220
	v_fma_f32 v221, v1, v227, v221
	s_nop 5
	v_max_f32_e32 v216, 0, v216
	v_fmac_f32_e32 v215, v2, v216
	v_max_f32_e32 v216, 0, v217
	v_fmac_f32_e32 v230, v2, v216
	v_max_f32_e32 v228, 0, v218
	v_max_f32_e32 v229, 0, v219
	s_waitcnt lgkmcnt(0)
	v_mfma_f32_16x16x32_bf16 v[216:219], v[60:63], v[76:79], 0
	v_fma_f32 v220, v2, v228, v220
	v_fma_f32 v221, v2, v229, v221
	s_nop 5
	v_max_f32_e32 v216, 0, v216
	v_fmac_f32_e32 v215, v3, v216
	v_max_f32_e32 v216, 0, v217
	v_fmac_f32_e32 v230, v3, v216
	v_max_f32_e32 v218, 0, v218
	v_max_f32_e32 v219, 0, v219
	v_add_f32_e32 v215, 0, v215
	v_ashrrev_i32_e32 v216, 31, v215
	v_bitop3_b32 v215, v216, v215, s33 bitop3:0x36
	v_cndmask_b32_e32 v216, 0, v215, vcc
	v_add_f32_e32 v215, 0, v230
	v_ashrrev_i32_e32 v217, 31, v215
	v_pk_fma_f32 v[218:219], v[2:3], v[218:219], v[220:221] op_sel:[1,0,0]
	v_bitop3_b32 v215, v217, v215, s33 bitop3:0x36
	v_cmp_lt_i32_e32 vcc, 0, v231
	v_pk_add_f32 v[218:219], v[218:219], 0 op_sel_hi:[1,0]
	s_nop 0
	v_cndmask_b32_e32 v217, 0, v215, vcc
	v_ashrrev_i32_e32 v215, 31, v219
	v_ashrrev_i32_e32 v220, 31, v218
	v_or_b32_e32 v215, 0x80000000, v215
	v_or_b32_e32 v220, 0x80000000, v220
	v_xor_b32_e32 v215, v215, v219
	v_cmp_lt_i32_e32 vcc, 2, v231
	v_xor_b32_e32 v218, v220, v218
	s_nop 0
	v_cndmask_b32_e32 v219, 0, v215, vcc
	v_cmp_lt_i32_e32 vcc, 1, v231
	s_nop 1
	v_cndmask_b32_e32 v218, 0, v218, vcc
	ds_write_b128 v163, v[216:219] offset:8448
	s_cmp_ge_i32 s11, s75
	s_cbranch_scc0 .LBB0_600
	s_branch .LBB0_601

.LBB0_719:
	s_sub_u32 s2, s2, 1
	s_cselect_b64 s[22:23], -1, 0
	s_and_b64 s[24:25], s[16:17], s[18:19]
	s_or_b64 s[22:23], s[22:23], s[24:25]
	s_andn2_b64 vcc, exec, s[22:23]
	s_cbranch_vccz .LBB0_735
.LBB0_720:
	s_lshl_b32 s21, 1, s2
	s_or_b32 s22, s21, s1
	s_andn2_b64 vcc, exec, s[8:9]
	s_or_b32 s21, s21, s0
	s_cbranch_vccnz .LBB0_731
	v_cmp_le_u32_e64 s[24:25], s22, v245
	v_cmp_le_u32_e64 s[26:27], s22, v244
	v_cmp_le_u32_e64 s[28:29], s22, v243
	v_cmp_le_u32_e64 s[30:31], s22, v242
	v_cndmask_b32_e64 v251, 0, 1, s[24:25]
	v_cndmask_b32_e64 v250, 0, 1, s[26:27]
	v_cndmask_b32_e64 v253, 0, 1, s[28:29]
	v_cndmask_b32_e64 v252, 0, 1, s[30:31]
	s_nop 0
	v_cmp_le_u32_e64 s[24:25], s21, v215
	v_cmp_le_u32_e64 s[26:27], s21, v108
	v_cmp_le_u32_e64 s[28:29], s21, v107
	v_cmp_le_u32_e64 s[30:31], s21, v106
	v_cndmask_b32_e64 v247, 0, 1, s[24:25]
	v_cndmask_b32_e64 v246, 0, 1, s[26:27]
	v_cndmask_b32_e64 v248, 0, 1, s[28:29]
	v_cndmask_b32_e64 v249, 0, 1, s[30:31]
	s_nop 0
	v_cmp_le_u32_e64 s[24:25], s22, v241
	v_cmp_le_u32_e64 s[26:27], s22, v240
	v_cmp_le_u32_e64 s[28:29], s22, v239
	v_cmp_le_u32_e64 s[30:31], s22, v238
	v_addc_co_u32_e64 v251, s[24:25], v251, 0, s[24:25]
	v_addc_co_u32_e64 v250, s[26:27], v250, 0, s[26:27]
	v_addc_co_u32_e64 v253, s[28:29], v253, 0, s[28:29]
	v_addc_co_u32_e64 v252, s[30:31], v252, 0, s[30:31]
	s_nop 0
	v_cmp_le_u32_e64 s[24:25], s21, v105
	v_cmp_le_u32_e64 s[26:27], s21, v104
	v_cmp_le_u32_e64 s[28:29], s21, v103
	v_cmp_le_u32_e64 s[30:31], s21, v102
	v_addc_co_u32_e64 v247, s[24:25], v247, 0, s[24:25]
	v_addc_co_u32_e64 v246, s[26:27], v246, 0, s[26:27]
	v_addc_co_u32_e64 v248, s[28:29], v248, 0, s[28:29]
	v_addc_co_u32_e64 v249, s[30:31], v249, 0, s[30:31]
	s_andn2_b64 vcc, exec, s[10:11]
	s_cbranch_vccnz .LBB0_723

.LBB0_727:
	v_add_u32_e32 v252, v253, v252
	v_add3_u32 v250, v252, v250, v251
	v_add_u32_e32 v246, v248, v246
	v_add3_u32 v246, v246, v249, v247
	v_lshl_add_u32 v250, v246, 16, v250
	s_nop 1
	v_add_u32_dpp v250, v250, v250 quad_perm:[1,0,3,2] row_mask:0xf bank_mask:0xf bound_ctrl:1
	s_nop 1
	v_add_u32_dpp v250, v250, v250 quad_perm:[2,3,0,1] row_mask:0xf bank_mask:0xf bound_ctrl:1
	s_nop 1
	v_add_u32_dpp v250, v250, v250 row_half_mirror row_mask:0xf bank_mask:0xf bound_ctrl:1
	s_nop 1
	v_add_u32_dpp v250, v250, v250 row_mirror row_mask:0xf bank_mask:0xf bound_ctrl:1
	v_mov_b32_e32 v251, v250
	s_nop 1
	v_permlane16_swap_b32_e32 v250, v251
	v_add_u32_e32 v250, v250, v251
	v_mov_b32_e32 v251, v250
	s_nop 1
	v_permlane32_swap_b32_e32 v250, v251
	v_add_u32_e32 v250, v250, v251
	s_nop 0
	v_readfirstlane_b32 s24, v250
	s_lshr_b32 s23, s24, 16
	s_and_b32 s24, s24, 0xffff
	s_cmpk_lt_i32 s24, 0x100
	s_cselect_b64 s[26:27], -1, 0
	s_or_b64 s[26:27], s[16:17], s[26:27]
	s_and_b64 vcc, exec, s[26:27]
	s_cbranch_vccnz .LBB0_729
	s_cmpk_eq_i32 s24, 0x100
	s_cselect_b64 s[16:17], -1, 0
	s_mov_b32 s3, s24
	s_mov_b32 s1, s22

.LBB0_1592:
	s_waitcnt lgkmcnt(0)
	s_barrier
	s_waitcnt vmcnt(1)
	ds_write_b128 v117, v[8:11]
	s_waitcnt lgkmcnt(0)
	s_barrier
	ds_read_b128 v[104:107], v210
	ds_read_b128 v[100:103], v210 offset:64
	ds_read_b128 v[96:99], v210 offset:128
	ds_read_b128 v[92:95], v210 offset:192
	ds_read_b128 v[88:91], v210 offset:256
	ds_read_b128 v[84:87], v210 offset:320
	ds_read_b128 v[80:83], v210 offset:384
	ds_read_b128 v[76:79], v210 offset:448
	s_lshl_b32 s93, s91, 4
	s_cmp_le_i32 s75, s91
	v_or_b32_e32 v108, s93, v133
	s_cbranch_scc0 .LBB0_1611
	s_waitcnt vmcnt(0) lgkmcnt(7)
	v_mfma_f32_16x16x32_bf16 v[212:215], v[12:15], v[104:107], 0
	v_sub_u32_e32 v227, v108, v143
	v_cmp_lt_i32_e32 vcc, -1, v227
	s_nop 5
	v_max_f32_e32 v211, 0, v212
	v_max_f32_e32 v212, 0, v213
	v_fma_f32 v226, v4, v212, 0
	v_max_f32_e32 v216, 0, v214
	v_max_f32_e32 v217, 0, v215
	s_waitcnt lgkmcnt(6)
	v_mfma_f32_16x16x32_bf16 v[212:215], v[12:15], v[100:103], 0
	s_nop 0
	v_fma_f32 v211, v4, v211, 0
	s_nop 5
	v_max_f32_e32 v212, 0, v212
	v_fmac_f32_e32 v211, v5, v212
	v_max_f32_e32 v212, 0, v213
	v_fmac_f32_e32 v226, v5, v212
	v_max_f32_e32 v218, 0, v214
	v_max_f32_e32 v219, 0, v215
	s_waitcnt lgkmcnt(5)
	v_mfma_f32_16x16x32_bf16 v[212:215], v[12:15], v[96:99], 0
	s_nop 7
	v_max_f32_e32 v212, 0, v212
	v_fmac_f32_e32 v211, v6, v212
	v_max_f32_e32 v212, 0, v213
	v_fmac_f32_e32 v226, v6, v212
	v_max_f32_e32 v212, 0, v214
	v_max_f32_e32 v213, 0, v215
	v_pk_fma_f32 v[214:215], v[4:5], v[216:217], 0 op_sel_hi:[0,1,0]
	v_pk_fma_f32 v[214:215], v[4:5], v[218:219], v[214:215] op_sel:[1,0,0]
	s_nop 0
	v_pk_fma_f32 v[216:217], v[6:7], v[212:213], v[214:215] op_sel_hi:[0,1,1]
	s_waitcnt lgkmcnt(4)
	v_mfma_f32_16x16x32_bf16 v[212:215], v[12:15], v[92:95], 0
	s_nop 7
	v_max_f32_e32 v212, 0, v212
	v_fmac_f32_e32 v211, v7, v212
	v_max_f32_e32 v212, 0, v213
	v_fmac_f32_e32 v226, v7, v212
	v_max_f32_e32 v218, 0, v214
	v_max_f32_e32 v219, 0, v215
	s_waitcnt lgkmcnt(3)
	v_mfma_f32_16x16x32_bf16 v[212:215], v[12:15], v[88:91], 0
	v_fma_f32 v216, v7, v218, v216
	v_fma_f32 v217, v7, v219, v217
	s_nop 5
	v_max_f32_e32 v212, 0, v212
	v_fmac_f32_e32 v211, v0, v212
	v_max_f32_e32 v212, 0, v213
	v_fmac_f32_e32 v226, v0, v212
	v_max_f32_e32 v220, 0, v214
	v_max_f32_e32 v221, 0, v215
	s_waitcnt lgkmcnt(2)
	v_mfma_f32_16x16x32_bf16 v[212:215], v[12:15], v[84:87], 0
	v_fma_f32 v216, v0, v220, v216
	v_fma_f32 v217, v0, v221, v217
	s_nop 5
	v_max_f32_e32 v212, 0, v212
	v_fmac_f32_e32 v211, v1, v212
	v_max_f32_e32 v212, 0, v213
	v_fmac_f32_e32 v226, v1, v212
	v_max_f32_e32 v222, 0, v214
	v_max_f32_e32 v223, 0, v215
	s_waitcnt lgkmcnt(1)
	v_mfma_f32_16x16x32_bf16 v[212:215], v[12:15], v[80:83], 0
	v_fma_f32 v216, v1, v222, v216
	v_fma_f32 v217, v1, v223, v217
	s_nop 5
	v_max_f32_e32 v212, 0, v212
	v_fmac_f32_e32 v211, v2, v212
	v_max_f32_e32 v212, 0, v213
	v_fmac_f32_e32 v226, v2, v212
	v_max_f32_e32 v224, 0, v214
	v_max_f32_e32 v225, 0, v215
	s_waitcnt lgkmcnt(0)
	v_mfma_f32_16x16x32_bf16 v[212:215], v[12:15], v[76:79], 0
	v_fma_f32 v216, v2, v224, v216
	v_fma_f32 v217, v2, v225, v217
	s_nop 5
	v_max_f32_e32 v212, 0, v212
	v_fmac_f32_e32 v211, v3, v212
	v_max_f32_e32 v212, 0, v213
	v_fmac_f32_e32 v226, v3, v212
	v_max_f32_e32 v214, 0, v214
	v_max_f32_e32 v215, 0, v215
	v_add_f32_e32 v211, 0, v211
	v_ashrrev_i32_e32 v212, 31, v211
	v_bitop3_b32 v211, v212, v211, s7 bitop3:0x36
	v_cndmask_b32_e32 v212, 0, v211, vcc
	v_add_f32_e32 v211, 0, v226
	v_ashrrev_i32_e32 v213, 31, v211
	v_pk_fma_f32 v[214:215], v[2:3], v[214:215], v[216:217] op_sel:[1,0,0]
	v_bitop3_b32 v211, v213, v211, s7 bitop3:0x36
	v_cmp_lt_i32_e32 vcc, 0, v227
	v_pk_add_f32 v[214:215], v[214:215], 0 op_sel_hi:[1,0]
	s_nop 0
	v_cndmask_b32_e32 v213, 0, v211, vcc
	v_ashrrev_i32_e32 v211, 31, v215
	v_ashrrev_i32_e32 v216, 31, v214
	v_or_b32_e32 v211, 0x80000000, v211
	v_or_b32_e32 v216, 0x80000000, v216
	v_xor_b32_e32 v211, v211, v215
	v_cmp_lt_i32_e32 vcc, 2, v227
	v_xor_b32_e32 v214, v216, v214
	s_nop 0
	v_cndmask_b32_e32 v215, 0, v211, vcc
	v_cmp_lt_i32_e32 vcc, 1, v227
	s_nop 1
	v_cndmask_b32_e32 v214, 0, v214, vcc
	ds_write_b128 v144, v[212:215] offset:8448
	s_cmp_ge_i32 s75, s91
	s_cbranch_scc0 .LBB0_1612

.LBB0_1595:
	s_waitcnt vmcnt(0) lgkmcnt(7)
	v_mfma_f32_16x16x32_bf16 v[212:215], v[20:23], v[104:107], 0
	v_sub_u32_e32 v227, v108, v146
	v_cmp_lt_i32_e32 vcc, -1, v227
	s_nop 5
	v_max_f32_e32 v211, 0, v212
	v_max_f32_e32 v212, 0, v213
	v_fma_f32 v226, v4, v212, 0
	v_max_f32_e32 v216, 0, v214
	v_max_f32_e32 v217, 0, v215
	s_waitcnt lgkmcnt(6)
	v_mfma_f32_16x16x32_bf16 v[212:215], v[20:23], v[100:103], 0
	s_nop 0
	v_fma_f32 v211, v4, v211, 0
	s_nop 5
	v_max_f32_e32 v212, 0, v212
	v_fmac_f32_e32 v211, v5, v212
	v_max_f32_e32 v212, 0, v213
	v_fmac_f32_e32 v226, v5, v212
	v_max_f32_e32 v218, 0, v214
	v_max_f32_e32 v219, 0, v215
	s_waitcnt lgkmcnt(5)
	v_mfma_f32_16x16x32_bf16 v[212:215], v[20:23], v[96:99], 0
	s_nop 7
	v_max_f32_e32 v212, 0, v212
	v_fmac_f32_e32 v211, v6, v212
	v_max_f32_e32 v212, 0, v213
	v_fmac_f32_e32 v226, v6, v212
	v_max_f32_e32 v212, 0, v214
	v_max_f32_e32 v213, 0, v215
	v_pk_fma_f32 v[214:215], v[4:5], v[216:217], 0 op_sel_hi:[0,1,0]
	v_pk_fma_f32 v[214:215], v[4:5], v[218:219], v[214:215] op_sel:[1,0,0]
	s_nop 0
	v_pk_fma_f32 v[216:217], v[6:7], v[212:213], v[214:215] op_sel_hi:[0,1,1]
	s_waitcnt lgkmcnt(4)
	v_mfma_f32_16x16x32_bf16 v[212:215], v[20:23], v[92:95], 0
	s_nop 7
	v_max_f32_e32 v212, 0, v212
	v_fmac_f32_e32 v211, v7, v212
	v_max_f32_e32 v212, 0, v213
	v_fmac_f32_e32 v226, v7, v212
	v_max_f32_e32 v218, 0, v214
	v_max_f32_e32 v219, 0, v215
	s_waitcnt lgkmcnt(3)
	v_mfma_f32_16x16x32_bf16 v[212:215], v[20:23], v[88:91], 0
	v_fma_f32 v216, v7, v218, v216
	v_fma_f32 v217, v7, v219, v217
	s_nop 5
	v_max_f32_e32 v212, 0, v212
	v_fmac_f32_e32 v211, v0, v212
	v_max_f32_e32 v212, 0, v213
	v_fmac_f32_e32 v226, v0, v212
	v_max_f32_e32 v220, 0, v214
	v_max_f32_e32 v221, 0, v215
	s_waitcnt lgkmcnt(2)
	v_mfma_f32_16x16x32_bf16 v[212:215], v[20:23], v[84:87], 0
	v_fma_f32 v216, v0, v220, v216
	v_fma_f32 v217, v0, v221, v217
	s_nop 5
	v_max_f32_e32 v212, 0, v212
	v_fmac_f32_e32 v211, v1, v212
	v_max_f32_e32 v212, 0, v213
	v_fmac_f32_e32 v226, v1, v212
	v_max_f32_e32 v222, 0, v214
	v_max_f32_e32 v223, 0, v215
	s_waitcnt lgkmcnt(1)
	v_mfma_f32_16x16x32_bf16 v[212:215], v[20:23], v[80:83], 0
	v_fma_f32 v216, v1, v222, v216
	v_fma_f32 v217, v1, v223, v217
	s_nop 5
	v_max_f32_e32 v212, 0, v212
	v_fmac_f32_e32 v211, v2, v212
	v_max_f32_e32 v212, 0, v213
	v_fmac_f32_e32 v226, v2, v212
	v_max_f32_e32 v224, 0, v214
	v_max_f32_e32 v225, 0, v215
	s_waitcnt lgkmcnt(0)
	v_mfma_f32_16x16x32_bf16 v[212:215], v[20:23], v[76:79], 0
	v_fma_f32 v216, v2, v224, v216
	v_fma_f32 v217, v2, v225, v217
	s_nop 5
	v_max_f32_e32 v212, 0, v212
	v_fmac_f32_e32 v211, v3, v212
	v_max_f32_e32 v212, 0, v213
	v_fmac_f32_e32 v226, v3, v212
	v_max_f32_e32 v214, 0, v214
	v_max_f32_e32 v215, 0, v215
	v_add_f32_e32 v211, 0, v211
	v_ashrrev_i32_e32 v212, 31, v211
	v_bitop3_b32 v211, v212, v211, s7 bitop3:0x36
	v_cndmask_b32_e32 v212, 0, v211, vcc
	v_add_f32_e32 v211, 0, v226
	v_ashrrev_i32_e32 v213, 31, v211
	v_pk_fma_f32 v[214:215], v[2:3], v[214:215], v[216:217] op_sel:[1,0,0]
	v_bitop3_b32 v211, v213, v211, s7 bitop3:0x36
	v_cmp_lt_i32_e32 vcc, 0, v227
	v_pk_add_f32 v[214:215], v[214:215], 0 op_sel_hi:[1,0]
	s_nop 0
	v_cndmask_b32_e32 v213, 0, v211, vcc
	v_ashrrev_i32_e32 v211, 31, v215
	v_ashrrev_i32_e32 v216, 31, v214
	v_or_b32_e32 v211, 0x80000000, v211
	v_or_b32_e32 v216, 0x80000000, v216
	v_xor_b32_e32 v211, v211, v215
	v_cmp_lt_i32_e32 vcc, 2, v227
	v_xor_b32_e32 v214, v216, v214
	s_nop 0
	v_cndmask_b32_e32 v215, 0, v211, vcc
	v_cmp_lt_i32_e32 vcc, 1, v227
	s_nop 1
	v_cndmask_b32_e32 v214, 0, v214, vcc
	ds_write_b128 v147, v[212:215] offset:8448
	s_cmp_ge_i32 s84, s91
	s_cbranch_scc0 .LBB0_1614

.LBB0_1597:
	s_waitcnt vmcnt(0) lgkmcnt(7)
	v_mfma_f32_16x16x32_bf16 v[212:215], v[28:31], v[104:107], 0
	v_sub_u32_e32 v227, v108, v149
	v_cmp_lt_i32_e32 vcc, -1, v227
	s_nop 5
	v_max_f32_e32 v211, 0, v212
	v_max_f32_e32 v212, 0, v213
	v_fma_f32 v226, v4, v212, 0
	v_max_f32_e32 v216, 0, v214
	v_max_f32_e32 v217, 0, v215
	s_waitcnt lgkmcnt(6)
	v_mfma_f32_16x16x32_bf16 v[212:215], v[28:31], v[100:103], 0
	s_nop 0
	v_fma_f32 v211, v4, v211, 0
	s_nop 5
	v_max_f32_e32 v212, 0, v212
	v_fmac_f32_e32 v211, v5, v212
	v_max_f32_e32 v212, 0, v213
	v_fmac_f32_e32 v226, v5, v212
	v_max_f32_e32 v218, 0, v214
	v_max_f32_e32 v219, 0, v215
	s_waitcnt lgkmcnt(5)
	v_mfma_f32_16x16x32_bf16 v[212:215], v[28:31], v[96:99], 0
	s_nop 7
	v_max_f32_e32 v212, 0, v212
	v_fmac_f32_e32 v211, v6, v212
	v_max_f32_e32 v212, 0, v213
	v_fmac_f32_e32 v226, v6, v212
	v_max_f32_e32 v212, 0, v214
	v_max_f32_e32 v213, 0, v215
	v_pk_fma_f32 v[214:215], v[4:5], v[216:217], 0 op_sel_hi:[0,1,0]
	v_pk_fma_f32 v[214:215], v[4:5], v[218:219], v[214:215] op_sel:[1,0,0]
	s_nop 0
	v_pk_fma_f32 v[216:217], v[6:7], v[212:213], v[214:215] op_sel_hi:[0,1,1]
	s_waitcnt lgkmcnt(4)
	v_mfma_f32_16x16x32_bf16 v[212:215], v[28:31], v[92:95], 0
	s_nop 7
	v_max_f32_e32 v212, 0, v212
	v_fmac_f32_e32 v211, v7, v212
	v_max_f32_e32 v212, 0, v213
	v_fmac_f32_e32 v226, v7, v212
	v_max_f32_e32 v218, 0, v214
	v_max_f32_e32 v219, 0, v215
	s_waitcnt lgkmcnt(3)
	v_mfma_f32_16x16x32_bf16 v[212:215], v[28:31], v[88:91], 0
	v_fma_f32 v216, v7, v218, v216
	v_fma_f32 v217, v7, v219, v217
	s_nop 5
	v_max_f32_e32 v212, 0, v212
	v_fmac_f32_e32 v211, v0, v212
	v_max_f32_e32 v212, 0, v213
	v_fmac_f32_e32 v226, v0, v212
	v_max_f32_e32 v220, 0, v214
	v_max_f32_e32 v221, 0, v215
	s_waitcnt lgkmcnt(2)
	v_mfma_f32_16x16x32_bf16 v[212:215], v[28:31], v[84:87], 0
	v_fma_f32 v216, v0, v220, v216
	v_fma_f32 v217, v0, v221, v217
	s_nop 5
	v_max_f32_e32 v212, 0, v212
	v_fmac_f32_e32 v211, v1, v212
	v_max_f32_e32 v212, 0, v213
	v_fmac_f32_e32 v226, v1, v212
	v_max_f32_e32 v222, 0, v214
	v_max_f32_e32 v223, 0, v215
	s_waitcnt lgkmcnt(1)
	v_mfma_f32_16x16x32_bf16 v[212:215], v[28:31], v[80:83], 0
	v_fma_f32 v216, v1, v222, v216
	v_fma_f32 v217, v1, v223, v217
	s_nop 5
	v_max_f32_e32 v212, 0, v212
	v_fmac_f32_e32 v211, v2, v212
	v_max_f32_e32 v212, 0, v213
	v_fmac_f32_e32 v226, v2, v212
	v_max_f32_e32 v224, 0, v214
	v_max_f32_e32 v225, 0, v215
	s_waitcnt lgkmcnt(0)
	v_mfma_f32_16x16x32_bf16 v[212:215], v[28:31], v[76:79], 0
	v_fma_f32 v216, v2, v224, v216
	v_fma_f32 v217, v2, v225, v217
	s_nop 5
	v_max_f32_e32 v212, 0, v212
	v_fmac_f32_e32 v211, v3, v212
	v_max_f32_e32 v212, 0, v213
	v_fmac_f32_e32 v226, v3, v212
	v_max_f32_e32 v214, 0, v214
	v_max_f32_e32 v215, 0, v215
	v_add_f32_e32 v211, 0, v211
	v_ashrrev_i32_e32 v212, 31, v211
	v_bitop3_b32 v211, v212, v211, s7 bitop3:0x36
	v_cndmask_b32_e32 v212, 0, v211, vcc
	v_add_f32_e32 v211, 0, v226
	v_ashrrev_i32_e32 v213, 31, v211
	v_pk_fma_f32 v[214:215], v[2:3], v[214:215], v[216:217] op_sel:[1,0,0]
	v_bitop3_b32 v211, v213, v211, s7 bitop3:0x36
	v_cmp_lt_i32_e32 vcc, 0, v227
	v_pk_add_f32 v[214:215], v[214:215], 0 op_sel_hi:[1,0]
	s_nop 0
	v_cndmask_b32_e32 v213, 0, v211, vcc
	v_ashrrev_i32_e32 v211, 31, v215
	v_ashrrev_i32_e32 v216, 31, v214
	v_or_b32_e32 v211, 0x80000000, v211
	v_or_b32_e32 v216, 0x80000000, v216
	v_xor_b32_e32 v211, v211, v215
	v_cmp_lt_i32_e32 vcc, 2, v227
	v_xor_b32_e32 v214, v216, v214
	s_nop 0
	v_cndmask_b32_e32 v215, 0, v211, vcc
	v_cmp_lt_i32_e32 vcc, 1, v227
	s_nop 1
	v_cndmask_b32_e32 v214, 0, v214, vcc
	ds_write_b128 v150, v[212:215] offset:8448
	s_cmp_ge_i32 s83, s91
	s_cbranch_scc0 .LBB0_1616

.LBB0_1599:
	s_waitcnt vmcnt(0) lgkmcnt(7)
	v_mfma_f32_16x16x32_bf16 v[212:215], v[36:39], v[104:107], 0
	v_sub_u32_e32 v227, v108, v152
	v_cmp_lt_i32_e32 vcc, -1, v227
	s_nop 5
	v_max_f32_e32 v211, 0, v212
	v_max_f32_e32 v212, 0, v213
	v_fma_f32 v226, v4, v212, 0
	v_max_f32_e32 v216, 0, v214
	v_max_f32_e32 v217, 0, v215
	s_waitcnt lgkmcnt(6)
	v_mfma_f32_16x16x32_bf16 v[212:215], v[36:39], v[100:103], 0
	s_nop 0
	v_fma_f32 v211, v4, v211, 0
	s_nop 5
	v_max_f32_e32 v212, 0, v212
	v_fmac_f32_e32 v211, v5, v212
	v_max_f32_e32 v212, 0, v213
	v_fmac_f32_e32 v226, v5, v212
	v_max_f32_e32 v218, 0, v214
	v_max_f32_e32 v219, 0, v215
	s_waitcnt lgkmcnt(5)
	v_mfma_f32_16x16x32_bf16 v[212:215], v[36:39], v[96:99], 0
	s_nop 7
	v_max_f32_e32 v212, 0, v212
	v_fmac_f32_e32 v211, v6, v212
	v_max_f32_e32 v212, 0, v213
	v_fmac_f32_e32 v226, v6, v212
	v_max_f32_e32 v212, 0, v214
	v_max_f32_e32 v213, 0, v215
	v_pk_fma_f32 v[214:215], v[4:5], v[216:217], 0 op_sel_hi:[0,1,0]
	v_pk_fma_f32 v[214:215], v[4:5], v[218:219], v[214:215] op_sel:[1,0,0]
	s_nop 0
	v_pk_fma_f32 v[216:217], v[6:7], v[212:213], v[214:215] op_sel_hi:[0,1,1]
	s_waitcnt lgkmcnt(4)
	v_mfma_f32_16x16x32_bf16 v[212:215], v[36:39], v[92:95], 0
	s_nop 7
	v_max_f32_e32 v212, 0, v212
	v_fmac_f32_e32 v211, v7, v212
	v_max_f32_e32 v212, 0, v213
	v_fmac_f32_e32 v226, v7, v212
	v_max_f32_e32 v218, 0, v214
	v_max_f32_e32 v219, 0, v215
	s_waitcnt lgkmcnt(3)
	v_mfma_f32_16x16x32_bf16 v[212:215], v[36:39], v[88:91], 0
	v_fma_f32 v216, v7, v218, v216
	v_fma_f32 v217, v7, v219, v217
	s_nop 5
	v_max_f32_e32 v212, 0, v212
	v_fmac_f32_e32 v211, v0, v212
	v_max_f32_e32 v212, 0, v213
	v_fmac_f32_e32 v226, v0, v212
	v_max_f32_e32 v220, 0, v214
	v_max_f32_e32 v221, 0, v215
	s_waitcnt lgkmcnt(2)
	v_mfma_f32_16x16x32_bf16 v[212:215], v[36:39], v[84:87], 0
	v_fma_f32 v216, v0, v220, v216
	v_fma_f32 v217, v0, v221, v217
	s_nop 5
	v_max_f32_e32 v212, 0, v212
	v_fmac_f32_e32 v211, v1, v212
	v_max_f32_e32 v212, 0, v213
	v_fmac_f32_e32 v226, v1, v212
	v_max_f32_e32 v222, 0, v214
	v_max_f32_e32 v223, 0, v215
	s_waitcnt lgkmcnt(1)
	v_mfma_f32_16x16x32_bf16 v[212:215], v[36:39], v[80:83], 0
	v_fma_f32 v216, v1, v222, v216
	v_fma_f32 v217, v1, v223, v217
	s_nop 5
	v_max_f32_e32 v212, 0, v212
	v_fmac_f32_e32 v211, v2, v212
	v_max_f32_e32 v212, 0, v213
	v_fmac_f32_e32 v226, v2, v212
	v_max_f32_e32 v224, 0, v214
	v_max_f32_e32 v225, 0, v215
	s_waitcnt lgkmcnt(0)
	v_mfma_f32_16x16x32_bf16 v[212:215], v[36:39], v[76:79], 0
	v_fma_f32 v216, v2, v224, v216
	v_fma_f32 v217, v2, v225, v217
	s_nop 5
	v_max_f32_e32 v212, 0, v212
	v_fmac_f32_e32 v211, v3, v212
	v_max_f32_e32 v212, 0, v213
	v_fmac_f32_e32 v226, v3, v212
	v_max_f32_e32 v214, 0, v214
	v_max_f32_e32 v215, 0, v215
	v_add_f32_e32 v211, 0, v211
	v_ashrrev_i32_e32 v212, 31, v211
	v_bitop3_b32 v211, v212, v211, s7 bitop3:0x36
	v_cndmask_b32_e32 v212, 0, v211, vcc
	v_add_f32_e32 v211, 0, v226
	v_ashrrev_i32_e32 v213, 31, v211
	v_pk_fma_f32 v[214:215], v[2:3], v[214:215], v[216:217] op_sel:[1,0,0]
	v_bitop3_b32 v211, v213, v211, s7 bitop3:0x36
	v_cmp_lt_i32_e32 vcc, 0, v227
	v_pk_add_f32 v[214:215], v[214:215], 0 op_sel_hi:[1,0]
	s_nop 0
	v_cndmask_b32_e32 v213, 0, v211, vcc
	v_ashrrev_i32_e32 v211, 31, v215
	v_ashrrev_i32_e32 v216, 31, v214
	v_or_b32_e32 v211, 0x80000000, v211
	v_or_b32_e32 v216, 0x80000000, v216
	v_xor_b32_e32 v211, v211, v215
	v_cmp_lt_i32_e32 vcc, 2, v227
	v_xor_b32_e32 v214, v216, v214
	s_nop 0
	v_cndmask_b32_e32 v215, 0, v211, vcc
	v_cmp_lt_i32_e32 vcc, 1, v227
	s_nop 1
	v_cndmask_b32_e32 v214, 0, v214, vcc
	ds_write_b128 v153, v[212:215] offset:8448
	s_cmp_ge_i32 s82, s91
	s_cbranch_scc0 .LBB0_1618

.LBB0_1601:
	s_waitcnt vmcnt(0) lgkmcnt(7)
	v_mfma_f32_16x16x32_bf16 v[212:215], v[44:47], v[104:107], 0
	v_sub_u32_e32 v227, v108, v155
	v_cmp_lt_i32_e32 vcc, -1, v227
	s_nop 5
	v_max_f32_e32 v211, 0, v212
	v_max_f32_e32 v212, 0, v213
	v_fma_f32 v226, v4, v212, 0
	v_max_f32_e32 v216, 0, v214
	v_max_f32_e32 v217, 0, v215
	s_waitcnt lgkmcnt(6)
	v_mfma_f32_16x16x32_bf16 v[212:215], v[44:47], v[100:103], 0
	s_nop 0
	v_fma_f32 v211, v4, v211, 0
	s_nop 5
	v_max_f32_e32 v212, 0, v212
	v_fmac_f32_e32 v211, v5, v212
	v_max_f32_e32 v212, 0, v213
	v_fmac_f32_e32 v226, v5, v212
	v_max_f32_e32 v218, 0, v214
	v_max_f32_e32 v219, 0, v215
	s_waitcnt lgkmcnt(5)
	v_mfma_f32_16x16x32_bf16 v[212:215], v[44:47], v[96:99], 0
	s_nop 7
	v_max_f32_e32 v212, 0, v212
	v_fmac_f32_e32 v211, v6, v212
	v_max_f32_e32 v212, 0, v213
	v_fmac_f32_e32 v226, v6, v212
	v_max_f32_e32 v212, 0, v214
	v_max_f32_e32 v213, 0, v215
	v_pk_fma_f32 v[214:215], v[4:5], v[216:217], 0 op_sel_hi:[0,1,0]
	v_pk_fma_f32 v[214:215], v[4:5], v[218:219], v[214:215] op_sel:[1,0,0]
	s_nop 0
	v_pk_fma_f32 v[216:217], v[6:7], v[212:213], v[214:215] op_sel_hi:[0,1,1]
	s_waitcnt lgkmcnt(4)
	v_mfma_f32_16x16x32_bf16 v[212:215], v[44:47], v[92:95], 0
	s_nop 7
	v_max_f32_e32 v212, 0, v212
	v_fmac_f32_e32 v211, v7, v212
	v_max_f32_e32 v212, 0, v213
	v_fmac_f32_e32 v226, v7, v212
	v_max_f32_e32 v218, 0, v214
	v_max_f32_e32 v219, 0, v215
	s_waitcnt lgkmcnt(3)
	v_mfma_f32_16x16x32_bf16 v[212:215], v[44:47], v[88:91], 0
	v_fma_f32 v216, v7, v218, v216
	v_fma_f32 v217, v7, v219, v217
	s_nop 5
	v_max_f32_e32 v212, 0, v212
	v_fmac_f32_e32 v211, v0, v212
	v_max_f32_e32 v212, 0, v213
	v_fmac_f32_e32 v226, v0, v212
	v_max_f32_e32 v220, 0, v214
	v_max_f32_e32 v221, 0, v215
	s_waitcnt lgkmcnt(2)
	v_mfma_f32_16x16x32_bf16 v[212:215], v[44:47], v[84:87], 0
	v_fma_f32 v216, v0, v220, v216
	v_fma_f32 v217, v0, v221, v217
	s_nop 5
	v_max_f32_e32 v212, 0, v212
	v_fmac_f32_e32 v211, v1, v212
	v_max_f32_e32 v212, 0, v213
	v_fmac_f32_e32 v226, v1, v212
	v_max_f32_e32 v222, 0, v214
	v_max_f32_e32 v223, 0, v215
	s_waitcnt lgkmcnt(1)
	v_mfma_f32_16x16x32_bf16 v[212:215], v[44:47], v[80:83], 0
	v_fma_f32 v216, v1, v222, v216
	v_fma_f32 v217, v1, v223, v217
	s_nop 5
	v_max_f32_e32 v212, 0, v212
	v_fmac_f32_e32 v211, v2, v212
	v_max_f32_e32 v212, 0, v213
	v_fmac_f32_e32 v226, v2, v212
	v_max_f32_e32 v224, 0, v214
	v_max_f32_e32 v225, 0, v215
	s_waitcnt lgkmcnt(0)
	v_mfma_f32_16x16x32_bf16 v[212:215], v[44:47], v[76:79], 0
	v_fma_f32 v216, v2, v224, v216
	v_fma_f32 v217, v2, v225, v217
	s_nop 5
	v_max_f32_e32 v212, 0, v212
	v_fmac_f32_e32 v211, v3, v212
	v_max_f32_e32 v212, 0, v213
	v_fmac_f32_e32 v226, v3, v212
	v_max_f32_e32 v214, 0, v214
	v_max_f32_e32 v215, 0, v215
	v_add_f32_e32 v211, 0, v211
	v_ashrrev_i32_e32 v212, 31, v211
	v_bitop3_b32 v211, v212, v211, s7 bitop3:0x36
	v_cndmask_b32_e32 v212, 0, v211, vcc
	v_add_f32_e32 v211, 0, v226
	v_ashrrev_i32_e32 v213, 31, v211
	v_pk_fma_f32 v[214:215], v[2:3], v[214:215], v[216:217] op_sel:[1,0,0]
	v_bitop3_b32 v211, v213, v211, s7 bitop3:0x36
	v_cmp_lt_i32_e32 vcc, 0, v227
	v_pk_add_f32 v[214:215], v[214:215], 0 op_sel_hi:[1,0]
	s_nop 0
	v_cndmask_b32_e32 v213, 0, v211, vcc
	v_ashrrev_i32_e32 v211, 31, v215
	v_ashrrev_i32_e32 v216, 31, v214
	v_or_b32_e32 v211, 0x80000000, v211
	v_or_b32_e32 v216, 0x80000000, v216
	v_xor_b32_e32 v211, v211, v215
	v_cmp_lt_i32_e32 vcc, 2, v227
	v_xor_b32_e32 v214, v216, v214
	s_nop 0
	v_cndmask_b32_e32 v215, 0, v211, vcc
	v_cmp_lt_i32_e32 vcc, 1, v227
	s_nop 1
	v_cndmask_b32_e32 v214, 0, v214, vcc
	ds_write_b128 v156, v[212:215] offset:8448
	s_cmp_ge_i32 s94, s91
	s_cbranch_scc0 .LBB0_1620

.LBB0_1603:
	s_waitcnt vmcnt(0) lgkmcnt(7)
	v_mfma_f32_16x16x32_bf16 v[212:215], v[52:55], v[104:107], 0
	v_sub_u32_e32 v227, v108, v158
	v_cmp_lt_i32_e32 vcc, -1, v227
	s_nop 5
	v_max_f32_e32 v211, 0, v212
	v_max_f32_e32 v212, 0, v213
	v_fma_f32 v226, v4, v212, 0
	v_max_f32_e32 v216, 0, v214
	v_max_f32_e32 v217, 0, v215
	s_waitcnt lgkmcnt(6)
	v_mfma_f32_16x16x32_bf16 v[212:215], v[52:55], v[100:103], 0
	s_nop 0
	v_fma_f32 v211, v4, v211, 0
	s_nop 5
	v_max_f32_e32 v212, 0, v212
	v_fmac_f32_e32 v211, v5, v212
	v_max_f32_e32 v212, 0, v213
	v_fmac_f32_e32 v226, v5, v212
	v_max_f32_e32 v218, 0, v214
	v_max_f32_e32 v219, 0, v215
	s_waitcnt lgkmcnt(5)
	v_mfma_f32_16x16x32_bf16 v[212:215], v[52:55], v[96:99], 0
	s_nop 7
	v_max_f32_e32 v212, 0, v212
	v_fmac_f32_e32 v211, v6, v212
	v_max_f32_e32 v212, 0, v213
	v_fmac_f32_e32 v226, v6, v212
	v_max_f32_e32 v212, 0, v214
	v_max_f32_e32 v213, 0, v215
	v_pk_fma_f32 v[214:215], v[4:5], v[216:217], 0 op_sel_hi:[0,1,0]
	v_pk_fma_f32 v[214:215], v[4:5], v[218:219], v[214:215] op_sel:[1,0,0]
	s_nop 0
	v_pk_fma_f32 v[216:217], v[6:7], v[212:213], v[214:215] op_sel_hi:[0,1,1]
	s_waitcnt lgkmcnt(4)
	v_mfma_f32_16x16x32_bf16 v[212:215], v[52:55], v[92:95], 0
	s_nop 7
	v_max_f32_e32 v212, 0, v212
	v_fmac_f32_e32 v211, v7, v212
	v_max_f32_e32 v212, 0, v213
	v_fmac_f32_e32 v226, v7, v212
	v_max_f32_e32 v218, 0, v214
	v_max_f32_e32 v219, 0, v215
	s_waitcnt lgkmcnt(3)
	v_mfma_f32_16x16x32_bf16 v[212:215], v[52:55], v[88:91], 0
	v_fma_f32 v216, v7, v218, v216
	v_fma_f32 v217, v7, v219, v217
	s_nop 5
	v_max_f32_e32 v212, 0, v212
	v_fmac_f32_e32 v211, v0, v212
	v_max_f32_e32 v212, 0, v213
	v_fmac_f32_e32 v226, v0, v212
	v_max_f32_e32 v220, 0, v214
	v_max_f32_e32 v221, 0, v215
	s_waitcnt lgkmcnt(2)
	v_mfma_f32_16x16x32_bf16 v[212:215], v[52:55], v[84:87], 0
	v_fma_f32 v216, v0, v220, v216
	v_fma_f32 v217, v0, v221, v217
	s_nop 5
	v_max_f32_e32 v212, 0, v212
	v_fmac_f32_e32 v211, v1, v212
	v_max_f32_e32 v212, 0, v213
	v_fmac_f32_e32 v226, v1, v212
	v_max_f32_e32 v222, 0, v214
	v_max_f32_e32 v223, 0, v215
	s_waitcnt lgkmcnt(1)
	v_mfma_f32_16x16x32_bf16 v[212:215], v[52:55], v[80:83], 0
	v_fma_f32 v216, v1, v222, v216
	v_fma_f32 v217, v1, v223, v217
	s_nop 5
	v_max_f32_e32 v212, 0, v212
	v_fmac_f32_e32 v211, v2, v212
	v_max_f32_e32 v212, 0, v213
	v_fmac_f32_e32 v226, v2, v212
	v_max_f32_e32 v224, 0, v214
	v_max_f32_e32 v225, 0, v215
	s_waitcnt lgkmcnt(0)
	v_mfma_f32_16x16x32_bf16 v[212:215], v[52:55], v[76:79], 0
	v_fma_f32 v216, v2, v224, v216
	v_fma_f32 v217, v2, v225, v217
	s_nop 5
	v_max_f32_e32 v212, 0, v212
	v_fmac_f32_e32 v211, v3, v212
	v_max_f32_e32 v212, 0, v213
	v_fmac_f32_e32 v226, v3, v212
	v_max_f32_e32 v214, 0, v214
	v_max_f32_e32 v215, 0, v215
	v_add_f32_e32 v211, 0, v211
	v_ashrrev_i32_e32 v212, 31, v211
	v_bitop3_b32 v211, v212, v211, s7 bitop3:0x36
	v_cndmask_b32_e32 v212, 0, v211, vcc
	v_add_f32_e32 v211, 0, v226
	v_ashrrev_i32_e32 v213, 31, v211
	v_pk_fma_f32 v[214:215], v[2:3], v[214:215], v[216:217] op_sel:[1,0,0]
	v_bitop3_b32 v211, v213, v211, s7 bitop3:0x36
	v_cmp_lt_i32_e32 vcc, 0, v227
	v_pk_add_f32 v[214:215], v[214:215], 0 op_sel_hi:[1,0]
	s_nop 0
	v_cndmask_b32_e32 v213, 0, v211, vcc
	v_ashrrev_i32_e32 v211, 31, v215
	v_ashrrev_i32_e32 v216, 31, v214
	v_or_b32_e32 v211, 0x80000000, v211
	v_or_b32_e32 v216, 0x80000000, v216
	v_xor_b32_e32 v211, v211, v215
	v_cmp_lt_i32_e32 vcc, 2, v227
	v_xor_b32_e32 v214, v216, v214
	s_nop 0
	v_cndmask_b32_e32 v215, 0, v211, vcc
	v_cmp_lt_i32_e32 vcc, 1, v227
	s_nop 1
	v_cndmask_b32_e32 v214, 0, v214, vcc
	ds_write_b128 v159, v[212:215] offset:8448
	s_cmp_ge_i32 s96, s91
	s_cbranch_scc0 .LBB0_1622

.LBB0_1605:
	s_waitcnt vmcnt(0) lgkmcnt(7)
	v_mfma_f32_16x16x32_bf16 v[212:215], v[60:63], v[104:107], 0
	v_sub_u32_e32 v227, v108, v161
	v_cmp_lt_i32_e32 vcc, -1, v227
	s_nop 5
	v_max_f32_e32 v211, 0, v212
	v_max_f32_e32 v212, 0, v213
	v_fma_f32 v226, v4, v212, 0
	v_max_f32_e32 v216, 0, v214
	v_max_f32_e32 v217, 0, v215
	s_waitcnt lgkmcnt(6)
	v_mfma_f32_16x16x32_bf16 v[212:215], v[60:63], v[100:103], 0
	s_nop 0
	v_fma_f32 v211, v4, v211, 0
	s_nop 5
	v_max_f32_e32 v212, 0, v212
	v_fmac_f32_e32 v211, v5, v212
	v_max_f32_e32 v212, 0, v213
	v_fmac_f32_e32 v226, v5, v212
	v_max_f32_e32 v218, 0, v214
	v_max_f32_e32 v219, 0, v215
	s_waitcnt lgkmcnt(5)
	v_mfma_f32_16x16x32_bf16 v[212:215], v[60:63], v[96:99], 0
	s_nop 7
	v_max_f32_e32 v212, 0, v212
	v_fmac_f32_e32 v211, v6, v212
	v_max_f32_e32 v212, 0, v213
	v_fmac_f32_e32 v226, v6, v212
	v_max_f32_e32 v212, 0, v214
	v_max_f32_e32 v213, 0, v215
	v_pk_fma_f32 v[214:215], v[4:5], v[216:217], 0 op_sel_hi:[0,1,0]
	v_pk_fma_f32 v[214:215], v[4:5], v[218:219], v[214:215] op_sel:[1,0,0]
	s_nop 0
	v_pk_fma_f32 v[216:217], v[6:7], v[212:213], v[214:215] op_sel_hi:[0,1,1]
	s_waitcnt lgkmcnt(4)
	v_mfma_f32_16x16x32_bf16 v[212:215], v[60:63], v[92:95], 0
	s_nop 7
	v_max_f32_e32 v212, 0, v212
	v_fmac_f32_e32 v211, v7, v212
	v_max_f32_e32 v212, 0, v213
	v_fmac_f32_e32 v226, v7, v212
	v_max_f32_e32 v218, 0, v214
	v_max_f32_e32 v219, 0, v215
	s_waitcnt lgkmcnt(3)
	v_mfma_f32_16x16x32_bf16 v[212:215], v[60:63], v[88:91], 0
	v_fma_f32 v216, v7, v218, v216
	v_fma_f32 v217, v7, v219, v217
	s_nop 5
	v_max_f32_e32 v212, 0, v212
	v_fmac_f32_e32 v211, v0, v212
	v_max_f32_e32 v212, 0, v213
	v_fmac_f32_e32 v226, v0, v212
	v_max_f32_e32 v220, 0, v214
	v_max_f32_e32 v221, 0, v215
	s_waitcnt lgkmcnt(2)
	v_mfma_f32_16x16x32_bf16 v[212:215], v[60:63], v[84:87], 0
	v_fma_f32 v216, v0, v220, v216
	v_fma_f32 v217, v0, v221, v217
	s_nop 5
	v_max_f32_e32 v212, 0, v212
	v_fmac_f32_e32 v211, v1, v212
	v_max_f32_e32 v212, 0, v213
	v_fmac_f32_e32 v226, v1, v212
	v_max_f32_e32 v222, 0, v214
	v_max_f32_e32 v223, 0, v215
	s_waitcnt lgkmcnt(1)
	v_mfma_f32_16x16x32_bf16 v[212:215], v[60:63], v[80:83], 0
	v_fma_f32 v216, v1, v222, v216
	v_fma_f32 v217, v1, v223, v217
	s_nop 5
	v_max_f32_e32 v212, 0, v212
	v_fmac_f32_e32 v211, v2, v212
	v_max_f32_e32 v212, 0, v213
	v_fmac_f32_e32 v226, v2, v212
	v_max_f32_e32 v224, 0, v214
	v_max_f32_e32 v225, 0, v215
	s_waitcnt lgkmcnt(0)
	v_mfma_f32_16x16x32_bf16 v[212:215], v[60:63], v[76:79], 0
	v_fma_f32 v216, v2, v224, v216
	v_fma_f32 v217, v2, v225, v217
	s_nop 5
	v_max_f32_e32 v212, 0, v212
	v_fmac_f32_e32 v211, v3, v212
	v_max_f32_e32 v212, 0, v213
	v_fmac_f32_e32 v226, v3, v212
	v_max_f32_e32 v214, 0, v214
	v_max_f32_e32 v215, 0, v215
	v_add_f32_e32 v211, 0, v211
	v_ashrrev_i32_e32 v212, 31, v211
	v_bitop3_b32 v211, v212, v211, s7 bitop3:0x36
	v_cndmask_b32_e32 v212, 0, v211, vcc
	v_add_f32_e32 v211, 0, v226
	v_ashrrev_i32_e32 v213, 31, v211
	v_pk_fma_f32 v[214:215], v[2:3], v[214:215], v[216:217] op_sel:[1,0,0]
	v_bitop3_b32 v211, v213, v211, s7 bitop3:0x36
	v_cmp_lt_i32_e32 vcc, 0, v227
	v_pk_add_f32 v[214:215], v[214:215], 0 op_sel_hi:[1,0]
	s_nop 0
	v_cndmask_b32_e32 v213, 0, v211, vcc
	v_ashrrev_i32_e32 v211, 31, v215
	v_ashrrev_i32_e32 v216, 31, v214
	v_or_b32_e32 v211, 0x80000000, v211
	v_or_b32_e32 v216, 0x80000000, v216
	v_xor_b32_e32 v211, v211, v215
	v_cmp_lt_i32_e32 vcc, 2, v227
	v_xor_b32_e32 v214, v216, v214
	s_nop 0
	v_cndmask_b32_e32 v215, 0, v211, vcc
	v_cmp_lt_i32_e32 vcc, 1, v227
	s_nop 1
	v_cndmask_b32_e32 v214, 0, v214, vcc
	ds_write_b128 v162, v[212:215] offset:8448
	s_cmp_ge_i32 s74, s91
	s_cbranch_scc0 .LBB0_1624

.LBB0_1607:
	s_waitcnt vmcnt(0) lgkmcnt(7)
	v_mfma_f32_16x16x32_bf16 v[212:215], v[68:71], v[104:107], 0
	v_sub_u32_e32 v227, v108, v164
	v_cmp_lt_i32_e32 vcc, -1, v227
	s_nop 5
	v_max_f32_e32 v211, 0, v212
	v_max_f32_e32 v212, 0, v213
	v_fma_f32 v226, v4, v212, 0
	v_max_f32_e32 v216, 0, v214
	v_max_f32_e32 v217, 0, v215
	s_waitcnt lgkmcnt(6)
	v_mfma_f32_16x16x32_bf16 v[212:215], v[68:71], v[100:103], 0
	s_nop 0
	v_fma_f32 v211, v4, v211, 0
	s_nop 5
	v_max_f32_e32 v212, 0, v212
	v_fmac_f32_e32 v211, v5, v212
	v_max_f32_e32 v212, 0, v213
	v_fmac_f32_e32 v226, v5, v212
	v_max_f32_e32 v218, 0, v214
	v_max_f32_e32 v219, 0, v215
	s_waitcnt lgkmcnt(5)
	v_mfma_f32_16x16x32_bf16 v[212:215], v[68:71], v[96:99], 0
	s_nop 7
	v_max_f32_e32 v212, 0, v212
	v_fmac_f32_e32 v211, v6, v212
	v_max_f32_e32 v212, 0, v213
	v_fmac_f32_e32 v226, v6, v212
	v_max_f32_e32 v212, 0, v214
	v_max_f32_e32 v213, 0, v215
	v_pk_fma_f32 v[214:215], v[4:5], v[216:217], 0 op_sel_hi:[0,1,0]
	v_pk_fma_f32 v[214:215], v[4:5], v[218:219], v[214:215] op_sel:[1,0,0]
	s_nop 0
	v_pk_fma_f32 v[216:217], v[6:7], v[212:213], v[214:215] op_sel_hi:[0,1,1]
	s_waitcnt lgkmcnt(4)
	v_mfma_f32_16x16x32_bf16 v[212:215], v[68:71], v[92:95], 0
	s_nop 7
	v_max_f32_e32 v212, 0, v212
	v_fmac_f32_e32 v211, v7, v212
	v_max_f32_e32 v212, 0, v213
	v_fmac_f32_e32 v226, v7, v212
	v_max_f32_e32 v218, 0, v214
	v_max_f32_e32 v219, 0, v215
	s_waitcnt lgkmcnt(3)
	v_mfma_f32_16x16x32_bf16 v[212:215], v[68:71], v[88:91], 0
	v_fma_f32 v216, v7, v218, v216
	v_fma_f32 v217, v7, v219, v217
	s_nop 5
	v_max_f32_e32 v212, 0, v212
	v_fmac_f32_e32 v211, v0, v212
	v_max_f32_e32 v212, 0, v213
	v_fmac_f32_e32 v226, v0, v212
	v_max_f32_e32 v220, 0, v214
	v_max_f32_e32 v221, 0, v215
	s_waitcnt lgkmcnt(2)
	v_mfma_f32_16x16x32_bf16 v[212:215], v[68:71], v[84:87], 0
	v_fma_f32 v216, v0, v220, v216
	v_fma_f32 v217, v0, v221, v217
	s_nop 5
	v_max_f32_e32 v212, 0, v212
	v_fmac_f32_e32 v211, v1, v212
	v_max_f32_e32 v212, 0, v213
	v_fmac_f32_e32 v226, v1, v212
	v_max_f32_e32 v222, 0, v214
	v_max_f32_e32 v223, 0, v215
	s_waitcnt lgkmcnt(1)
	v_mfma_f32_16x16x32_bf16 v[212:215], v[68:71], v[80:83], 0
	v_fma_f32 v216, v1, v222, v216
	v_fma_f32 v217, v1, v223, v217
	s_nop 5
	v_max_f32_e32 v212, 0, v212
	v_fmac_f32_e32 v211, v2, v212
	v_max_f32_e32 v212, 0, v213
	v_fmac_f32_e32 v226, v2, v212
	v_max_f32_e32 v224, 0, v214
	v_max_f32_e32 v225, 0, v215
	s_waitcnt lgkmcnt(0)
	v_mfma_f32_16x16x32_bf16 v[212:215], v[68:71], v[76:79], 0
	v_fma_f32 v216, v2, v224, v216
	v_fma_f32 v217, v2, v225, v217
	s_nop 5
	v_max_f32_e32 v212, 0, v212
	v_fmac_f32_e32 v211, v3, v212
	v_max_f32_e32 v212, 0, v213
	v_fmac_f32_e32 v226, v3, v212
	v_max_f32_e32 v214, 0, v214
	v_max_f32_e32 v215, 0, v215
	v_add_f32_e32 v211, 0, v211
	v_ashrrev_i32_e32 v212, 31, v211
	v_bitop3_b32 v211, v212, v211, s7 bitop3:0x36
	v_cndmask_b32_e32 v212, 0, v211, vcc
	v_add_f32_e32 v211, 0, v226
	v_ashrrev_i32_e32 v213, 31, v211
	v_pk_fma_f32 v[214:215], v[2:3], v[214:215], v[216:217] op_sel:[1,0,0]
	v_bitop3_b32 v211, v213, v211, s7 bitop3:0x36
	v_cmp_lt_i32_e32 vcc, 0, v227
	v_pk_add_f32 v[214:215], v[214:215], 0 op_sel_hi:[1,0]
	s_nop 0
	v_cndmask_b32_e32 v213, 0, v211, vcc
	v_ashrrev_i32_e32 v211, 31, v215
	v_ashrrev_i32_e32 v216, 31, v214
	v_or_b32_e32 v211, 0x80000000, v211
	v_or_b32_e32 v216, 0x80000000, v216
	v_xor_b32_e32 v211, v211, v215
	v_cmp_lt_i32_e32 vcc, 2, v227
	v_xor_b32_e32 v214, v216, v214
	s_nop 0
	v_cndmask_b32_e32 v215, 0, v211, vcc
	v_cmp_lt_i32_e32 vcc, 1, v227
	s_nop 1
	v_cndmask_b32_e32 v214, 0, v214, vcc
	ds_write_b128 v165, v[212:215] offset:8448
	s_cmp_ge_i32 s34, s91
	s_cbranch_scc0 .LBB0_1626

.LBB0_1612:
	s_waitcnt vmcnt(0) lgkmcnt(7)
	v_mfma_f32_16x16x32_bf16 v[212:215], v[16:19], v[104:107], 0
	v_sub_u32_e32 v227, v108, v145
	v_cmp_lt_i32_e32 vcc, -1, v227
	s_nop 5
	v_max_f32_e32 v211, 0, v212
	v_max_f32_e32 v212, 0, v213
	v_fma_f32 v226, v4, v212, 0
	v_max_f32_e32 v216, 0, v214
	v_max_f32_e32 v217, 0, v215
	s_waitcnt lgkmcnt(6)
	v_mfma_f32_16x16x32_bf16 v[212:215], v[16:19], v[100:103], 0
	s_nop 0
	v_fma_f32 v211, v4, v211, 0
	s_nop 5
	v_max_f32_e32 v212, 0, v212
	v_fmac_f32_e32 v211, v5, v212
	v_max_f32_e32 v212, 0, v213
	v_fmac_f32_e32 v226, v5, v212
	v_max_f32_e32 v218, 0, v214
	v_max_f32_e32 v219, 0, v215
	s_waitcnt lgkmcnt(5)
	v_mfma_f32_16x16x32_bf16 v[212:215], v[16:19], v[96:99], 0
	s_nop 7
	v_max_f32_e32 v212, 0, v212
	v_fmac_f32_e32 v211, v6, v212
	v_max_f32_e32 v212, 0, v213
	v_fmac_f32_e32 v226, v6, v212
	v_max_f32_e32 v212, 0, v214
	v_max_f32_e32 v213, 0, v215
	v_pk_fma_f32 v[214:215], v[4:5], v[216:217], 0 op_sel_hi:[0,1,0]
	v_pk_fma_f32 v[214:215], v[4:5], v[218:219], v[214:215] op_sel:[1,0,0]
	s_nop 0
	v_pk_fma_f32 v[216:217], v[6:7], v[212:213], v[214:215] op_sel_hi:[0,1,1]
	s_waitcnt lgkmcnt(4)
	v_mfma_f32_16x16x32_bf16 v[212:215], v[16:19], v[92:95], 0
	s_nop 7
	v_max_f32_e32 v212, 0, v212
	v_fmac_f32_e32 v211, v7, v212
	v_max_f32_e32 v212, 0, v213
	v_fmac_f32_e32 v226, v7, v212
	v_max_f32_e32 v218, 0, v214
	v_max_f32_e32 v219, 0, v215
	s_waitcnt lgkmcnt(3)
	v_mfma_f32_16x16x32_bf16 v[212:215], v[16:19], v[88:91], 0
	v_fma_f32 v216, v7, v218, v216
	v_fma_f32 v217, v7, v219, v217
	s_nop 5
	v_max_f32_e32 v212, 0, v212
	v_fmac_f32_e32 v211, v0, v212
	v_max_f32_e32 v212, 0, v213
	v_fmac_f32_e32 v226, v0, v212
	v_max_f32_e32 v220, 0, v214
	v_max_f32_e32 v221, 0, v215
	s_waitcnt lgkmcnt(2)
	v_mfma_f32_16x16x32_bf16 v[212:215], v[16:19], v[84:87], 0
	v_fma_f32 v216, v0, v220, v216
	v_fma_f32 v217, v0, v221, v217
	s_nop 5
	v_max_f32_e32 v212, 0, v212
	v_fmac_f32_e32 v211, v1, v212
	v_max_f32_e32 v212, 0, v213
	v_fmac_f32_e32 v226, v1, v212
	v_max_f32_e32 v222, 0, v214
	v_max_f32_e32 v223, 0, v215
	s_waitcnt lgkmcnt(1)
	v_mfma_f32_16x16x32_bf16 v[212:215], v[16:19], v[80:83], 0
	v_fma_f32 v216, v1, v222, v216
	v_fma_f32 v217, v1, v223, v217
	s_nop 5
	v_max_f32_e32 v212, 0, v212
	v_fmac_f32_e32 v211, v2, v212
	v_max_f32_e32 v212, 0, v213
	v_fmac_f32_e32 v226, v2, v212
	v_max_f32_e32 v224, 0, v214
	v_max_f32_e32 v225, 0, v215
	s_waitcnt lgkmcnt(0)
	v_mfma_f32_16x16x32_bf16 v[212:215], v[16:19], v[76:79], 0
	v_fma_f32 v216, v2, v224, v216
	v_fma_f32 v217, v2, v225, v217
	s_nop 5
	v_max_f32_e32 v212, 0, v212
	v_fmac_f32_e32 v211, v3, v212
	v_max_f32_e32 v212, 0, v213
	v_fmac_f32_e32 v226, v3, v212
	v_max_f32_e32 v214, 0, v214
	v_max_f32_e32 v215, 0, v215
	v_add_f32_e32 v211, 0, v211
	v_ashrrev_i32_e32 v212, 31, v211
	v_bitop3_b32 v211, v212, v211, s7 bitop3:0x36
	v_cndmask_b32_e32 v212, 0, v211, vcc
	v_add_f32_e32 v211, 0, v226
	v_ashrrev_i32_e32 v213, 31, v211
	v_pk_fma_f32 v[214:215], v[2:3], v[214:215], v[216:217] op_sel:[1,0,0]
	v_bitop3_b32 v211, v213, v211, s7 bitop3:0x36
	v_cmp_lt_i32_e32 vcc, 0, v227
	v_pk_add_f32 v[214:215], v[214:215], 0 op_sel_hi:[1,0]
	s_nop 0
	v_cndmask_b32_e32 v213, 0, v211, vcc
	v_ashrrev_i32_e32 v211, 31, v215
	v_ashrrev_i32_e32 v216, 31, v214
	v_or_b32_e32 v211, 0x80000000, v211
	v_or_b32_e32 v216, 0x80000000, v216
	v_xor_b32_e32 v211, v211, v215
	v_cmp_lt_i32_e32 vcc, 2, v227
	v_xor_b32_e32 v214, v216, v214
	s_nop 0
	v_cndmask_b32_e32 v215, 0, v211, vcc
	v_cmp_lt_i32_e32 vcc, 1, v227
	s_nop 1
	v_cndmask_b32_e32 v214, 0, v214, vcc
	ds_write_b128 v144, v[212:215] offset:8512
	s_cmp_gt_i32 s84, s91
	s_cbranch_scc0 .LBB0_1595

.LBB0_1614:
	s_waitcnt vmcnt(0) lgkmcnt(7)
	v_mfma_f32_16x16x32_bf16 v[212:215], v[24:27], v[104:107], 0
	v_sub_u32_e32 v227, v108, v148
	v_cmp_lt_i32_e32 vcc, -1, v227
	s_nop 5
	v_max_f32_e32 v211, 0, v212
	v_max_f32_e32 v212, 0, v213
	v_fma_f32 v226, v4, v212, 0
	v_max_f32_e32 v216, 0, v214
	v_max_f32_e32 v217, 0, v215
	s_waitcnt lgkmcnt(6)
	v_mfma_f32_16x16x32_bf16 v[212:215], v[24:27], v[100:103], 0
	s_nop 0
	v_fma_f32 v211, v4, v211, 0
	s_nop 5
	v_max_f32_e32 v212, 0, v212
	v_fmac_f32_e32 v211, v5, v212
	v_max_f32_e32 v212, 0, v213
	v_fmac_f32_e32 v226, v5, v212
	v_max_f32_e32 v218, 0, v214
	v_max_f32_e32 v219, 0, v215
	s_waitcnt lgkmcnt(5)
	v_mfma_f32_16x16x32_bf16 v[212:215], v[24:27], v[96:99], 0
	s_nop 7
	v_max_f32_e32 v212, 0, v212
	v_fmac_f32_e32 v211, v6, v212
	v_max_f32_e32 v212, 0, v213
	v_fmac_f32_e32 v226, v6, v212
	v_max_f32_e32 v212, 0, v214
	v_max_f32_e32 v213, 0, v215
	v_pk_fma_f32 v[214:215], v[4:5], v[216:217], 0 op_sel_hi:[0,1,0]
	v_pk_fma_f32 v[214:215], v[4:5], v[218:219], v[214:215] op_sel:[1,0,0]
	s_nop 0
	v_pk_fma_f32 v[216:217], v[6:7], v[212:213], v[214:215] op_sel_hi:[0,1,1]
	s_waitcnt lgkmcnt(4)
	v_mfma_f32_16x16x32_bf16 v[212:215], v[24:27], v[92:95], 0
	s_nop 7
	v_max_f32_e32 v212, 0, v212
	v_fmac_f32_e32 v211, v7, v212
	v_max_f32_e32 v212, 0, v213
	v_fmac_f32_e32 v226, v7, v212
	v_max_f32_e32 v218, 0, v214
	v_max_f32_e32 v219, 0, v215
	s_waitcnt lgkmcnt(3)
	v_mfma_f32_16x16x32_bf16 v[212:215], v[24:27], v[88:91], 0
	v_fma_f32 v216, v7, v218, v216
	v_fma_f32 v217, v7, v219, v217
	s_nop 5
	v_max_f32_e32 v212, 0, v212
	v_fmac_f32_e32 v211, v0, v212
	v_max_f32_e32 v212, 0, v213
	v_fmac_f32_e32 v226, v0, v212
	v_max_f32_e32 v220, 0, v214
	v_max_f32_e32 v221, 0, v215
	s_waitcnt lgkmcnt(2)
	v_mfma_f32_16x16x32_bf16 v[212:215], v[24:27], v[84:87], 0
	v_fma_f32 v216, v0, v220, v216
	v_fma_f32 v217, v0, v221, v217
	s_nop 5
	v_max_f32_e32 v212, 0, v212
	v_fmac_f32_e32 v211, v1, v212
	v_max_f32_e32 v212, 0, v213
	v_fmac_f32_e32 v226, v1, v212
	v_max_f32_e32 v222, 0, v214
	v_max_f32_e32 v223, 0, v215
	s_waitcnt lgkmcnt(1)
	v_mfma_f32_16x16x32_bf16 v[212:215], v[24:27], v[80:83], 0
	v_fma_f32 v216, v1, v222, v216
	v_fma_f32 v217, v1, v223, v217
	s_nop 5
	v_max_f32_e32 v212, 0, v212
	v_fmac_f32_e32 v211, v2, v212
	v_max_f32_e32 v212, 0, v213
	v_fmac_f32_e32 v226, v2, v212
	v_max_f32_e32 v224, 0, v214
	v_max_f32_e32 v225, 0, v215
	s_waitcnt lgkmcnt(0)
	v_mfma_f32_16x16x32_bf16 v[212:215], v[24:27], v[76:79], 0
	v_fma_f32 v216, v2, v224, v216
	v_fma_f32 v217, v2, v225, v217
	s_nop 5
	v_max_f32_e32 v212, 0, v212
	v_fmac_f32_e32 v211, v3, v212
	v_max_f32_e32 v212, 0, v213
	v_fmac_f32_e32 v226, v3, v212
	v_max_f32_e32 v214, 0, v214
	v_max_f32_e32 v215, 0, v215
	v_add_f32_e32 v211, 0, v211
	v_ashrrev_i32_e32 v212, 31, v211
	v_bitop3_b32 v211, v212, v211, s7 bitop3:0x36
	v_cndmask_b32_e32 v212, 0, v211, vcc
	v_add_f32_e32 v211, 0, v226
	v_ashrrev_i32_e32 v213, 31, v211
	v_pk_fma_f32 v[214:215], v[2:3], v[214:215], v[216:217] op_sel:[1,0,0]
	v_bitop3_b32 v211, v213, v211, s7 bitop3:0x36
	v_cmp_lt_i32_e32 vcc, 0, v227
	v_pk_add_f32 v[214:215], v[214:215], 0 op_sel_hi:[1,0]
	s_nop 0
	v_cndmask_b32_e32 v213, 0, v211, vcc
	v_ashrrev_i32_e32 v211, 31, v215
	v_ashrrev_i32_e32 v216, 31, v214
	v_or_b32_e32 v211, 0x80000000, v211
	v_or_b32_e32 v216, 0x80000000, v216
	v_xor_b32_e32 v211, v211, v215
	v_cmp_lt_i32_e32 vcc, 2, v227
	v_xor_b32_e32 v214, v216, v214
	s_nop 0
	v_cndmask_b32_e32 v215, 0, v211, vcc
	v_cmp_lt_i32_e32 vcc, 1, v227
	s_nop 1
	v_cndmask_b32_e32 v214, 0, v214, vcc
	ds_write_b128 v147, v[212:215] offset:8512
	s_cmp_gt_i32 s83, s91
	s_cbranch_scc0 .LBB0_1597

.LBB0_1616:
	s_waitcnt vmcnt(0) lgkmcnt(7)
	v_mfma_f32_16x16x32_bf16 v[212:215], v[32:35], v[104:107], 0
	v_sub_u32_e32 v227, v108, v151
	v_cmp_lt_i32_e32 vcc, -1, v227
	s_nop 5
	v_max_f32_e32 v211, 0, v212
	v_max_f32_e32 v212, 0, v213
	v_fma_f32 v226, v4, v212, 0
	v_max_f32_e32 v216, 0, v214
	v_max_f32_e32 v217, 0, v215
	s_waitcnt lgkmcnt(6)
	v_mfma_f32_16x16x32_bf16 v[212:215], v[32:35], v[100:103], 0
	s_nop 0
	v_fma_f32 v211, v4, v211, 0
	s_nop 5
	v_max_f32_e32 v212, 0, v212
	v_fmac_f32_e32 v211, v5, v212
	v_max_f32_e32 v212, 0, v213
	v_fmac_f32_e32 v226, v5, v212
	v_max_f32_e32 v218, 0, v214
	v_max_f32_e32 v219, 0, v215
	s_waitcnt lgkmcnt(5)
	v_mfma_f32_16x16x32_bf16 v[212:215], v[32:35], v[96:99], 0
	s_nop 7
	v_max_f32_e32 v212, 0, v212
	v_fmac_f32_e32 v211, v6, v212
	v_max_f32_e32 v212, 0, v213
	v_fmac_f32_e32 v226, v6, v212
	v_max_f32_e32 v212, 0, v214
	v_max_f32_e32 v213, 0, v215
	v_pk_fma_f32 v[214:215], v[4:5], v[216:217], 0 op_sel_hi:[0,1,0]
	v_pk_fma_f32 v[214:215], v[4:5], v[218:219], v[214:215] op_sel:[1,0,0]
	s_nop 0
	v_pk_fma_f32 v[216:217], v[6:7], v[212:213], v[214:215] op_sel_hi:[0,1,1]
	s_waitcnt lgkmcnt(4)
	v_mfma_f32_16x16x32_bf16 v[212:215], v[32:35], v[92:95], 0
	s_nop 7
	v_max_f32_e32 v212, 0, v212
	v_fmac_f32_e32 v211, v7, v212
	v_max_f32_e32 v212, 0, v213
	v_fmac_f32_e32 v226, v7, v212
	v_max_f32_e32 v218, 0, v214
	v_max_f32_e32 v219, 0, v215
	s_waitcnt lgkmcnt(3)
	v_mfma_f32_16x16x32_bf16 v[212:215], v[32:35], v[88:91], 0
	v_fma_f32 v216, v7, v218, v216
	v_fma_f32 v217, v7, v219, v217
	s_nop 5
	v_max_f32_e32 v212, 0, v212
	v_fmac_f32_e32 v211, v0, v212
	v_max_f32_e32 v212, 0, v213
	v_fmac_f32_e32 v226, v0, v212
	v_max_f32_e32 v220, 0, v214
	v_max_f32_e32 v221, 0, v215
	s_waitcnt lgkmcnt(2)
	v_mfma_f32_16x16x32_bf16 v[212:215], v[32:35], v[84:87], 0
	v_fma_f32 v216, v0, v220, v216
	v_fma_f32 v217, v0, v221, v217
	s_nop 5
	v_max_f32_e32 v212, 0, v212
	v_fmac_f32_e32 v211, v1, v212
	v_max_f32_e32 v212, 0, v213
	v_fmac_f32_e32 v226, v1, v212
	v_max_f32_e32 v222, 0, v214
	v_max_f32_e32 v223, 0, v215
	s_waitcnt lgkmcnt(1)
	v_mfma_f32_16x16x32_bf16 v[212:215], v[32:35], v[80:83], 0
	v_fma_f32 v216, v1, v222, v216
	v_fma_f32 v217, v1, v223, v217
	s_nop 5
	v_max_f32_e32 v212, 0, v212
	v_fmac_f32_e32 v211, v2, v212
	v_max_f32_e32 v212, 0, v213
	v_fmac_f32_e32 v226, v2, v212
	v_max_f32_e32 v224, 0, v214
	v_max_f32_e32 v225, 0, v215
	s_waitcnt lgkmcnt(0)
	v_mfma_f32_16x16x32_bf16 v[212:215], v[32:35], v[76:79], 0
	v_fma_f32 v216, v2, v224, v216
	v_fma_f32 v217, v2, v225, v217
	s_nop 5
	v_max_f32_e32 v212, 0, v212
	v_fmac_f32_e32 v211, v3, v212
	v_max_f32_e32 v212, 0, v213
	v_fmac_f32_e32 v226, v3, v212
	v_max_f32_e32 v214, 0, v214
	v_max_f32_e32 v215, 0, v215
	v_add_f32_e32 v211, 0, v211
	v_ashrrev_i32_e32 v212, 31, v211
	v_bitop3_b32 v211, v212, v211, s7 bitop3:0x36
	v_cndmask_b32_e32 v212, 0, v211, vcc
	v_add_f32_e32 v211, 0, v226
	v_ashrrev_i32_e32 v213, 31, v211
	v_pk_fma_f32 v[214:215], v[2:3], v[214:215], v[216:217] op_sel:[1,0,0]
	v_bitop3_b32 v211, v213, v211, s7 bitop3:0x36
	v_cmp_lt_i32_e32 vcc, 0, v227
	v_pk_add_f32 v[214:215], v[214:215], 0 op_sel_hi:[1,0]
	s_nop 0
	v_cndmask_b32_e32 v213, 0, v211, vcc
	v_ashrrev_i32_e32 v211, 31, v215
	v_ashrrev_i32_e32 v216, 31, v214
	v_or_b32_e32 v211, 0x80000000, v211
	v_or_b32_e32 v216, 0x80000000, v216
	v_xor_b32_e32 v211, v211, v215
	v_cmp_lt_i32_e32 vcc, 2, v227
	v_xor_b32_e32 v214, v216, v214
	s_nop 0
	v_cndmask_b32_e32 v215, 0, v211, vcc
	v_cmp_lt_i32_e32 vcc, 1, v227
	s_nop 1
	v_cndmask_b32_e32 v214, 0, v214, vcc
	ds_write_b128 v150, v[212:215] offset:8512
	s_cmp_gt_i32 s82, s91
	s_cbranch_scc0 .LBB0_1599

.LBB0_1618:
	s_waitcnt vmcnt(0) lgkmcnt(7)
	v_mfma_f32_16x16x32_bf16 v[212:215], v[40:43], v[104:107], 0
	v_sub_u32_e32 v227, v108, v154
	v_cmp_lt_i32_e32 vcc, -1, v227
	s_nop 5
	v_max_f32_e32 v211, 0, v212
	v_max_f32_e32 v212, 0, v213
	v_fma_f32 v226, v4, v212, 0
	v_max_f32_e32 v216, 0, v214
	v_max_f32_e32 v217, 0, v215
	s_waitcnt lgkmcnt(6)
	v_mfma_f32_16x16x32_bf16 v[212:215], v[40:43], v[100:103], 0
	s_nop 0
	v_fma_f32 v211, v4, v211, 0
	s_nop 5
	v_max_f32_e32 v212, 0, v212
	v_fmac_f32_e32 v211, v5, v212
	v_max_f32_e32 v212, 0, v213
	v_fmac_f32_e32 v226, v5, v212
	v_max_f32_e32 v218, 0, v214
	v_max_f32_e32 v219, 0, v215
	s_waitcnt lgkmcnt(5)
	v_mfma_f32_16x16x32_bf16 v[212:215], v[40:43], v[96:99], 0
	s_nop 7
	v_max_f32_e32 v212, 0, v212
	v_fmac_f32_e32 v211, v6, v212
	v_max_f32_e32 v212, 0, v213
	v_fmac_f32_e32 v226, v6, v212
	v_max_f32_e32 v212, 0, v214
	v_max_f32_e32 v213, 0, v215
	v_pk_fma_f32 v[214:215], v[4:5], v[216:217], 0 op_sel_hi:[0,1,0]
	v_pk_fma_f32 v[214:215], v[4:5], v[218:219], v[214:215] op_sel:[1,0,0]
	s_nop 0
	v_pk_fma_f32 v[216:217], v[6:7], v[212:213], v[214:215] op_sel_hi:[0,1,1]
	s_waitcnt lgkmcnt(4)
	v_mfma_f32_16x16x32_bf16 v[212:215], v[40:43], v[92:95], 0
	s_nop 7
	v_max_f32_e32 v212, 0, v212
	v_fmac_f32_e32 v211, v7, v212
	v_max_f32_e32 v212, 0, v213
	v_fmac_f32_e32 v226, v7, v212
	v_max_f32_e32 v218, 0, v214
	v_max_f32_e32 v219, 0, v215
	s_waitcnt lgkmcnt(3)
	v_mfma_f32_16x16x32_bf16 v[212:215], v[40:43], v[88:91], 0
	v_fma_f32 v216, v7, v218, v216
	v_fma_f32 v217, v7, v219, v217
	s_nop 5
	v_max_f32_e32 v212, 0, v212
	v_fmac_f32_e32 v211, v0, v212
	v_max_f32_e32 v212, 0, v213
	v_fmac_f32_e32 v226, v0, v212
	v_max_f32_e32 v220, 0, v214
	v_max_f32_e32 v221, 0, v215
	s_waitcnt lgkmcnt(2)
	v_mfma_f32_16x16x32_bf16 v[212:215], v[40:43], v[84:87], 0
	v_fma_f32 v216, v0, v220, v216
	v_fma_f32 v217, v0, v221, v217
	s_nop 5
	v_max_f32_e32 v212, 0, v212
	v_fmac_f32_e32 v211, v1, v212
	v_max_f32_e32 v212, 0, v213
	v_fmac_f32_e32 v226, v1, v212
	v_max_f32_e32 v222, 0, v214
	v_max_f32_e32 v223, 0, v215
	s_waitcnt lgkmcnt(1)
	v_mfma_f32_16x16x32_bf16 v[212:215], v[40:43], v[80:83], 0
	v_fma_f32 v216, v1, v222, v216
	v_fma_f32 v217, v1, v223, v217
	s_nop 5
	v_max_f32_e32 v212, 0, v212
	v_fmac_f32_e32 v211, v2, v212
	v_max_f32_e32 v212, 0, v213
	v_fmac_f32_e32 v226, v2, v212
	v_max_f32_e32 v224, 0, v214
	v_max_f32_e32 v225, 0, v215
	s_waitcnt lgkmcnt(0)
	v_mfma_f32_16x16x32_bf16 v[212:215], v[40:43], v[76:79], 0
	v_fma_f32 v216, v2, v224, v216
	v_fma_f32 v217, v2, v225, v217
	s_nop 5
	v_max_f32_e32 v212, 0, v212
	v_fmac_f32_e32 v211, v3, v212
	v_max_f32_e32 v212, 0, v213
	v_fmac_f32_e32 v226, v3, v212
	v_max_f32_e32 v214, 0, v214
	v_max_f32_e32 v215, 0, v215
	v_add_f32_e32 v211, 0, v211
	v_ashrrev_i32_e32 v212, 31, v211
	v_bitop3_b32 v211, v212, v211, s7 bitop3:0x36
	v_cndmask_b32_e32 v212, 0, v211, vcc
	v_add_f32_e32 v211, 0, v226
	v_ashrrev_i32_e32 v213, 31, v211
	v_pk_fma_f32 v[214:215], v[2:3], v[214:215], v[216:217] op_sel:[1,0,0]
	v_bitop3_b32 v211, v213, v211, s7 bitop3:0x36
	v_cmp_lt_i32_e32 vcc, 0, v227
	v_pk_add_f32 v[214:215], v[214:215], 0 op_sel_hi:[1,0]
	s_nop 0
	v_cndmask_b32_e32 v213, 0, v211, vcc
	v_ashrrev_i32_e32 v211, 31, v215
	v_ashrrev_i32_e32 v216, 31, v214
	v_or_b32_e32 v211, 0x80000000, v211
	v_or_b32_e32 v216, 0x80000000, v216
	v_xor_b32_e32 v211, v211, v215
	v_cmp_lt_i32_e32 vcc, 2, v227
	v_xor_b32_e32 v214, v216, v214
	s_nop 0
	v_cndmask_b32_e32 v215, 0, v211, vcc
	v_cmp_lt_i32_e32 vcc, 1, v227
	s_nop 1
	v_cndmask_b32_e32 v214, 0, v214, vcc
	ds_write_b128 v153, v[212:215] offset:8512
	s_cmp_gt_i32 s94, s91
	s_cbranch_scc0 .LBB0_1601

.LBB0_1620:
	s_waitcnt vmcnt(0) lgkmcnt(7)
	v_mfma_f32_16x16x32_bf16 v[212:215], v[48:51], v[104:107], 0
	v_sub_u32_e32 v227, v108, v157
	v_cmp_lt_i32_e32 vcc, -1, v227
	s_nop 5
	v_max_f32_e32 v211, 0, v212
	v_max_f32_e32 v212, 0, v213
	v_fma_f32 v226, v4, v212, 0
	v_max_f32_e32 v216, 0, v214
	v_max_f32_e32 v217, 0, v215
	s_waitcnt lgkmcnt(6)
	v_mfma_f32_16x16x32_bf16 v[212:215], v[48:51], v[100:103], 0
	s_nop 0
	v_fma_f32 v211, v4, v211, 0
	s_nop 5
	v_max_f32_e32 v212, 0, v212
	v_fmac_f32_e32 v211, v5, v212
	v_max_f32_e32 v212, 0, v213
	v_fmac_f32_e32 v226, v5, v212
	v_max_f32_e32 v218, 0, v214
	v_max_f32_e32 v219, 0, v215
	s_waitcnt lgkmcnt(5)
	v_mfma_f32_16x16x32_bf16 v[212:215], v[48:51], v[96:99], 0
	s_nop 7
	v_max_f32_e32 v212, 0, v212
	v_fmac_f32_e32 v211, v6, v212
	v_max_f32_e32 v212, 0, v213
	v_fmac_f32_e32 v226, v6, v212
	v_max_f32_e32 v212, 0, v214
	v_max_f32_e32 v213, 0, v215
	v_pk_fma_f32 v[214:215], v[4:5], v[216:217], 0 op_sel_hi:[0,1,0]
	v_pk_fma_f32 v[214:215], v[4:5], v[218:219], v[214:215] op_sel:[1,0,0]
	s_nop 0
	v_pk_fma_f32 v[216:217], v[6:7], v[212:213], v[214:215] op_sel_hi:[0,1,1]
	s_waitcnt lgkmcnt(4)
	v_mfma_f32_16x16x32_bf16 v[212:215], v[48:51], v[92:95], 0
	s_nop 7
	v_max_f32_e32 v212, 0, v212
	v_fmac_f32_e32 v211, v7, v212
	v_max_f32_e32 v212, 0, v213
	v_fmac_f32_e32 v226, v7, v212
	v_max_f32_e32 v218, 0, v214
	v_max_f32_e32 v219, 0, v215
	s_waitcnt lgkmcnt(3)
	v_mfma_f32_16x16x32_bf16 v[212:215], v[48:51], v[88:91], 0
	v_fma_f32 v216, v7, v218, v216
	v_fma_f32 v217, v7, v219, v217
	s_nop 5
	v_max_f32_e32 v212, 0, v212
	v_fmac_f32_e32 v211, v0, v212
	v_max_f32_e32 v212, 0, v213
	v_fmac_f32_e32 v226, v0, v212
	v_max_f32_e32 v220, 0, v214
	v_max_f32_e32 v221, 0, v215
	s_waitcnt lgkmcnt(2)
	v_mfma_f32_16x16x32_bf16 v[212:215], v[48:51], v[84:87], 0
	v_fma_f32 v216, v0, v220, v216
	v_fma_f32 v217, v0, v221, v217
	s_nop 5
	v_max_f32_e32 v212, 0, v212
	v_fmac_f32_e32 v211, v1, v212
	v_max_f32_e32 v212, 0, v213
	v_fmac_f32_e32 v226, v1, v212
	v_max_f32_e32 v222, 0, v214
	v_max_f32_e32 v223, 0, v215
	s_waitcnt lgkmcnt(1)
	v_mfma_f32_16x16x32_bf16 v[212:215], v[48:51], v[80:83], 0
	v_fma_f32 v216, v1, v222, v216
	v_fma_f32 v217, v1, v223, v217
	s_nop 5
	v_max_f32_e32 v212, 0, v212
	v_fmac_f32_e32 v211, v2, v212
	v_max_f32_e32 v212, 0, v213
	v_fmac_f32_e32 v226, v2, v212
	v_max_f32_e32 v224, 0, v214
	v_max_f32_e32 v225, 0, v215
	s_waitcnt lgkmcnt(0)
	v_mfma_f32_16x16x32_bf16 v[212:215], v[48:51], v[76:79], 0
	v_fma_f32 v216, v2, v224, v216
	v_fma_f32 v217, v2, v225, v217
	s_nop 5
	v_max_f32_e32 v212, 0, v212
	v_fmac_f32_e32 v211, v3, v212
	v_max_f32_e32 v212, 0, v213
	v_fmac_f32_e32 v226, v3, v212
	v_max_f32_e32 v214, 0, v214
	v_max_f32_e32 v215, 0, v215
	v_add_f32_e32 v211, 0, v211
	v_ashrrev_i32_e32 v212, 31, v211
	v_bitop3_b32 v211, v212, v211, s7 bitop3:0x36
	v_cndmask_b32_e32 v212, 0, v211, vcc
	v_add_f32_e32 v211, 0, v226
	v_ashrrev_i32_e32 v213, 31, v211
	v_pk_fma_f32 v[214:215], v[2:3], v[214:215], v[216:217] op_sel:[1,0,0]
	v_bitop3_b32 v211, v213, v211, s7 bitop3:0x36
	v_cmp_lt_i32_e32 vcc, 0, v227
	v_pk_add_f32 v[214:215], v[214:215], 0 op_sel_hi:[1,0]
	s_nop 0
	v_cndmask_b32_e32 v213, 0, v211, vcc
	v_ashrrev_i32_e32 v211, 31, v215
	v_ashrrev_i32_e32 v216, 31, v214
	v_or_b32_e32 v211, 0x80000000, v211
	v_or_b32_e32 v216, 0x80000000, v216
	v_xor_b32_e32 v211, v211, v215
	v_cmp_lt_i32_e32 vcc, 2, v227
	v_xor_b32_e32 v214, v216, v214
	s_nop 0
	v_cndmask_b32_e32 v215, 0, v211, vcc
	v_cmp_lt_i32_e32 vcc, 1, v227
	s_nop 1
	v_cndmask_b32_e32 v214, 0, v214, vcc
	ds_write_b128 v156, v[212:215] offset:8512
	s_cmp_gt_i32 s96, s91
	s_cbranch_scc0 .LBB0_1603

.LBB0_1622:
	s_waitcnt vmcnt(0) lgkmcnt(7)
	v_mfma_f32_16x16x32_bf16 v[212:215], v[56:59], v[104:107], 0
	v_sub_u32_e32 v227, v108, v160
	v_cmp_lt_i32_e32 vcc, -1, v227
	s_nop 5
	v_max_f32_e32 v211, 0, v212
	v_max_f32_e32 v212, 0, v213
	v_fma_f32 v226, v4, v212, 0
	v_max_f32_e32 v216, 0, v214
	v_max_f32_e32 v217, 0, v215
	s_waitcnt lgkmcnt(6)
	v_mfma_f32_16x16x32_bf16 v[212:215], v[56:59], v[100:103], 0
	s_nop 0
	v_fma_f32 v211, v4, v211, 0
	s_nop 5
	v_max_f32_e32 v212, 0, v212
	v_fmac_f32_e32 v211, v5, v212
	v_max_f32_e32 v212, 0, v213
	v_fmac_f32_e32 v226, v5, v212
	v_max_f32_e32 v218, 0, v214
	v_max_f32_e32 v219, 0, v215
	s_waitcnt lgkmcnt(5)
	v_mfma_f32_16x16x32_bf16 v[212:215], v[56:59], v[96:99], 0
	s_nop 7
	v_max_f32_e32 v212, 0, v212
	v_fmac_f32_e32 v211, v6, v212
	v_max_f32_e32 v212, 0, v213
	v_fmac_f32_e32 v226, v6, v212
	v_max_f32_e32 v212, 0, v214
	v_max_f32_e32 v213, 0, v215
	v_pk_fma_f32 v[214:215], v[4:5], v[216:217], 0 op_sel_hi:[0,1,0]
	v_pk_fma_f32 v[214:215], v[4:5], v[218:219], v[214:215] op_sel:[1,0,0]
	s_nop 0
	v_pk_fma_f32 v[216:217], v[6:7], v[212:213], v[214:215] op_sel_hi:[0,1,1]
	s_waitcnt lgkmcnt(4)
	v_mfma_f32_16x16x32_bf16 v[212:215], v[56:59], v[92:95], 0
	s_nop 7
	v_max_f32_e32 v212, 0, v212
	v_fmac_f32_e32 v211, v7, v212
	v_max_f32_e32 v212, 0, v213
	v_fmac_f32_e32 v226, v7, v212
	v_max_f32_e32 v218, 0, v214
	v_max_f32_e32 v219, 0, v215
	s_waitcnt lgkmcnt(3)
	v_mfma_f32_16x16x32_bf16 v[212:215], v[56:59], v[88:91], 0
	v_fma_f32 v216, v7, v218, v216
	v_fma_f32 v217, v7, v219, v217
	s_nop 5
	v_max_f32_e32 v212, 0, v212
	v_fmac_f32_e32 v211, v0, v212
	v_max_f32_e32 v212, 0, v213
	v_fmac_f32_e32 v226, v0, v212
	v_max_f32_e32 v220, 0, v214
	v_max_f32_e32 v221, 0, v215
	s_waitcnt lgkmcnt(2)
	v_mfma_f32_16x16x32_bf16 v[212:215], v[56:59], v[84:87], 0
	v_fma_f32 v216, v0, v220, v216
	v_fma_f32 v217, v0, v221, v217
	s_nop 5
	v_max_f32_e32 v212, 0, v212
	v_fmac_f32_e32 v211, v1, v212
	v_max_f32_e32 v212, 0, v213
	v_fmac_f32_e32 v226, v1, v212
	v_max_f32_e32 v222, 0, v214
	v_max_f32_e32 v223, 0, v215
	s_waitcnt lgkmcnt(1)
	v_mfma_f32_16x16x32_bf16 v[212:215], v[56:59], v[80:83], 0
	v_fma_f32 v216, v1, v222, v216
	v_fma_f32 v217, v1, v223, v217
	s_nop 5
	v_max_f32_e32 v212, 0, v212
	v_fmac_f32_e32 v211, v2, v212
	v_max_f32_e32 v212, 0, v213
	v_fmac_f32_e32 v226, v2, v212
	v_max_f32_e32 v224, 0, v214
	v_max_f32_e32 v225, 0, v215
	s_waitcnt lgkmcnt(0)
	v_mfma_f32_16x16x32_bf16 v[212:215], v[56:59], v[76:79], 0
	v_fma_f32 v216, v2, v224, v216
	v_fma_f32 v217, v2, v225, v217
	s_nop 5
	v_max_f32_e32 v212, 0, v212
	v_fmac_f32_e32 v211, v3, v212
	v_max_f32_e32 v212, 0, v213
	v_fmac_f32_e32 v226, v3, v212
	v_max_f32_e32 v214, 0, v214
	v_max_f32_e32 v215, 0, v215
	v_add_f32_e32 v211, 0, v211
	v_ashrrev_i32_e32 v212, 31, v211
	v_bitop3_b32 v211, v212, v211, s7 bitop3:0x36
	v_cndmask_b32_e32 v212, 0, v211, vcc
	v_add_f32_e32 v211, 0, v226
	v_ashrrev_i32_e32 v213, 31, v211
	v_pk_fma_f32 v[214:215], v[2:3], v[214:215], v[216:217] op_sel:[1,0,0]
	v_bitop3_b32 v211, v213, v211, s7 bitop3:0x36
	v_cmp_lt_i32_e32 vcc, 0, v227
	v_pk_add_f32 v[214:215], v[214:215], 0 op_sel_hi:[1,0]
	s_nop 0
	v_cndmask_b32_e32 v213, 0, v211, vcc
	v_ashrrev_i32_e32 v211, 31, v215
	v_ashrrev_i32_e32 v216, 31, v214
	v_or_b32_e32 v211, 0x80000000, v211
	v_or_b32_e32 v216, 0x80000000, v216
	v_xor_b32_e32 v211, v211, v215
	v_cmp_lt_i32_e32 vcc, 2, v227
	v_xor_b32_e32 v214, v216, v214
	s_nop 0
	v_cndmask_b32_e32 v215, 0, v211, vcc
	v_cmp_lt_i32_e32 vcc, 1, v227
	s_nop 1
	v_cndmask_b32_e32 v214, 0, v214, vcc
	ds_write_b128 v159, v[212:215] offset:8512
	s_cmp_gt_i32 s74, s91
	s_cbranch_scc0 .LBB0_1605

.LBB0_1624:
	s_waitcnt vmcnt(0) lgkmcnt(7)
	v_mfma_f32_16x16x32_bf16 v[212:215], v[64:67], v[104:107], 0
	v_sub_u32_e32 v227, v108, v163
	v_cmp_lt_i32_e32 vcc, -1, v227
	s_nop 5
	v_max_f32_e32 v211, 0, v212
	v_max_f32_e32 v212, 0, v213
	v_fma_f32 v226, v4, v212, 0
	v_max_f32_e32 v216, 0, v214
	v_max_f32_e32 v217, 0, v215
	s_waitcnt lgkmcnt(6)
	v_mfma_f32_16x16x32_bf16 v[212:215], v[64:67], v[100:103], 0
	s_nop 0
	v_fma_f32 v211, v4, v211, 0
	s_nop 5
	v_max_f32_e32 v212, 0, v212
	v_fmac_f32_e32 v211, v5, v212
	v_max_f32_e32 v212, 0, v213
	v_fmac_f32_e32 v226, v5, v212
	v_max_f32_e32 v218, 0, v214
	v_max_f32_e32 v219, 0, v215
	s_waitcnt lgkmcnt(5)
	v_mfma_f32_16x16x32_bf16 v[212:215], v[64:67], v[96:99], 0
	s_nop 7
	v_max_f32_e32 v212, 0, v212
	v_fmac_f32_e32 v211, v6, v212
	v_max_f32_e32 v212, 0, v213
	v_fmac_f32_e32 v226, v6, v212
	v_max_f32_e32 v212, 0, v214
	v_max_f32_e32 v213, 0, v215
	v_pk_fma_f32 v[214:215], v[4:5], v[216:217], 0 op_sel_hi:[0,1,0]
	v_pk_fma_f32 v[214:215], v[4:5], v[218:219], v[214:215] op_sel:[1,0,0]
	s_nop 0
	v_pk_fma_f32 v[216:217], v[6:7], v[212:213], v[214:215] op_sel_hi:[0,1,1]
	s_waitcnt lgkmcnt(4)
	v_mfma_f32_16x16x32_bf16 v[212:215], v[64:67], v[92:95], 0
	s_nop 7
	v_max_f32_e32 v212, 0, v212
	v_fmac_f32_e32 v211, v7, v212
	v_max_f32_e32 v212, 0, v213
	v_fmac_f32_e32 v226, v7, v212
	v_max_f32_e32 v218, 0, v214
	v_max_f32_e32 v219, 0, v215
	s_waitcnt lgkmcnt(3)
	v_mfma_f32_16x16x32_bf16 v[212:215], v[64:67], v[88:91], 0
	v_fma_f32 v216, v7, v218, v216
	v_fma_f32 v217, v7, v219, v217
	s_nop 5
	v_max_f32_e32 v212, 0, v212
	v_fmac_f32_e32 v211, v0, v212
	v_max_f32_e32 v212, 0, v213
	v_fmac_f32_e32 v226, v0, v212
	v_max_f32_e32 v220, 0, v214
	v_max_f32_e32 v221, 0, v215
	s_waitcnt lgkmcnt(2)
	v_mfma_f32_16x16x32_bf16 v[212:215], v[64:67], v[84:87], 0
	v_fma_f32 v216, v0, v220, v216
	v_fma_f32 v217, v0, v221, v217
	s_nop 5
	v_max_f32_e32 v212, 0, v212
	v_fmac_f32_e32 v211, v1, v212
	v_max_f32_e32 v212, 0, v213
	v_fmac_f32_e32 v226, v1, v212
	v_max_f32_e32 v222, 0, v214
	v_max_f32_e32 v223, 0, v215
	s_waitcnt lgkmcnt(1)
	v_mfma_f32_16x16x32_bf16 v[212:215], v[64:67], v[80:83], 0
	v_fma_f32 v216, v1, v222, v216
	v_fma_f32 v217, v1, v223, v217
	s_nop 5
	v_max_f32_e32 v212, 0, v212
	v_fmac_f32_e32 v211, v2, v212
	v_max_f32_e32 v212, 0, v213
	v_fmac_f32_e32 v226, v2, v212
	v_max_f32_e32 v224, 0, v214
	v_max_f32_e32 v225, 0, v215
	s_waitcnt lgkmcnt(0)
	v_mfma_f32_16x16x32_bf16 v[212:215], v[64:67], v[76:79], 0
	v_fma_f32 v216, v2, v224, v216
	v_fma_f32 v217, v2, v225, v217
	s_nop 5
	v_max_f32_e32 v212, 0, v212
	v_fmac_f32_e32 v211, v3, v212
	v_max_f32_e32 v212, 0, v213
	v_fmac_f32_e32 v226, v3, v212
	v_max_f32_e32 v214, 0, v214
	v_max_f32_e32 v215, 0, v215
	v_add_f32_e32 v211, 0, v211
	v_ashrrev_i32_e32 v212, 31, v211
	v_bitop3_b32 v211, v212, v211, s7 bitop3:0x36
	v_cndmask_b32_e32 v212, 0, v211, vcc
	v_add_f32_e32 v211, 0, v226
	v_ashrrev_i32_e32 v213, 31, v211
	v_pk_fma_f32 v[214:215], v[2:3], v[214:215], v[216:217] op_sel:[1,0,0]
	v_bitop3_b32 v211, v213, v211, s7 bitop3:0x36
	v_cmp_lt_i32_e32 vcc, 0, v227
	v_pk_add_f32 v[214:215], v[214:215], 0 op_sel_hi:[1,0]
	s_nop 0
	v_cndmask_b32_e32 v213, 0, v211, vcc
	v_ashrrev_i32_e32 v211, 31, v215
	v_ashrrev_i32_e32 v216, 31, v214
	v_or_b32_e32 v211, 0x80000000, v211
	v_or_b32_e32 v216, 0x80000000, v216
	v_xor_b32_e32 v211, v211, v215
	v_cmp_lt_i32_e32 vcc, 2, v227
	v_xor_b32_e32 v214, v216, v214
	s_nop 0
	v_cndmask_b32_e32 v215, 0, v211, vcc
	v_cmp_lt_i32_e32 vcc, 1, v227
	s_nop 1
	v_cndmask_b32_e32 v214, 0, v214, vcc
	ds_write_b128 v162, v[212:215] offset:8512
	s_cmp_gt_i32 s34, s91
	s_cbranch_scc0 .LBB0_1607

.LBB0_1626:
	s_waitcnt vmcnt(0) lgkmcnt(7)
	v_mfma_f32_16x16x32_bf16 v[104:107], v[72:75], v[104:107], 0
	s_waitcnt lgkmcnt(6)
	v_mfma_f32_16x16x32_bf16 v[100:103], v[72:75], v[100:103], 0
	s_waitcnt lgkmcnt(5)
	v_mfma_f32_16x16x32_bf16 v[96:99], v[72:75], v[96:99], 0
	s_nop 3
	v_max_f32_e32 v104, 0, v104
	s_nop 0
	v_max_f32_e32 v100, 0, v100
	s_waitcnt lgkmcnt(4)
	v_mfma_f32_16x16x32_bf16 v[92:95], v[72:75], v[92:95], 0
	v_max_f32_e32 v105, 0, v105
	v_fma_f32 v211, v4, v104, 0
	s_nop 0
	s_waitcnt lgkmcnt(3)
	v_mfma_f32_16x16x32_bf16 v[88:91], v[72:75], v[88:91], 0
	v_max_f32_e32 v96, 0, v96
	s_nop 0
	v_fmac_f32_e32 v211, v5, v100
	s_waitcnt lgkmcnt(2)
	v_mfma_f32_16x16x32_bf16 v[84:87], v[72:75], v[84:87], 0
	v_max_f32_e32 v100, 0, v101
	s_nop 0
	v_max_f32_e32 v92, 0, v92
	s_waitcnt lgkmcnt(1)
	v_mfma_f32_16x16x32_bf16 v[80:83], v[72:75], v[80:83], 0
	v_fma_f32 v212, v4, v105, 0
	s_nop 0
	v_fmac_f32_e32 v211, v6, v96
	s_waitcnt lgkmcnt(0)
	v_mfma_f32_16x16x32_bf16 v[76:79], v[72:75], v[76:79], 0
	v_max_f32_e32 v96, 0, v97
	s_nop 0
	v_max_f32_e32 v88, 0, v88
	v_fmac_f32_e32 v212, v5, v100
	s_nop 0
	v_fmac_f32_e32 v211, v7, v92
	v_max_f32_e32 v92, 0, v93
	s_nop 0
	v_max_f32_e32 v84, 0, v84
	v_fmac_f32_e32 v212, v6, v96
	s_nop 0
	v_fmac_f32_e32 v211, v0, v88
	v_max_f32_e32 v88, 0, v89
	s_nop 0
	v_max_f32_e32 v80, 0, v80
	v_fmac_f32_e32 v212, v7, v92
	s_nop 0
	v_fmac_f32_e32 v211, v1, v84
	v_max_f32_e32 v84, 0, v85
	s_nop 0
	v_max_f32_e32 v76, 0, v76
	v_fmac_f32_e32 v212, v0, v88
	v_fmac_f32_e32 v211, v2, v80
	v_max_f32_e32 v80, 0, v81
	v_fmac_f32_e32 v212, v1, v84
	v_fmac_f32_e32 v211, v3, v76
	v_max_f32_e32 v76, 0, v77
	v_fmac_f32_e32 v212, v2, v80
	v_fmac_f32_e32 v212, v3, v76
	v_max_f32_e32 v78, 0, v78
	v_max_f32_e32 v104, 0, v106
	v_max_f32_e32 v105, 0, v107
	v_max_f32_e32 v79, 0, v79
	v_max_f32_e32 v100, 0, v102
	v_max_f32_e32 v101, 0, v103
	v_add_f32_e32 v76, 0, v211
	v_max_f32_e32 v96, 0, v98
	v_max_f32_e32 v97, 0, v99
	v_pk_fma_f32 v[98:99], v[4:5], v[104:105], 0 op_sel_hi:[0,1,0]
	v_ashrrev_i32_e32 v77, 31, v76
	v_pk_fma_f32 v[98:99], v[4:5], v[100:101], v[98:99] op_sel:[1,0,0]
	v_max_f32_e32 v92, 0, v94
	v_max_f32_e32 v93, 0, v95
	v_bitop3_b32 v76, v77, v76, s7 bitop3:0x36
	v_add_f32_e32 v77, 0, v212
	v_pk_fma_f32 v[96:97], v[6:7], v[96:97], v[98:99] op_sel_hi:[0,1,1]
	v_max_f32_e32 v88, 0, v90
	v_max_f32_e32 v89, 0, v91
	v_max_f32_e32 v80, 0, v82
	v_ashrrev_i32_e32 v82, 31, v77
	v_max_f32_e32 v84, 0, v86
	v_max_f32_e32 v85, 0, v87
	v_max_f32_e32 v81, 0, v83
	v_bitop3_b32 v77, v82, v77, s7 bitop3:0x36
	v_pk_fma_f32 v[82:83], v[6:7], v[92:93], v[96:97] op_sel:[1,0,0]
	v_pk_fma_f32 v[82:83], v[0:1], v[88:89], v[82:83] op_sel_hi:[0,1,1]
	v_pk_fma_f32 v[82:83], v[0:1], v[84:85], v[82:83] op_sel:[1,0,0]
	v_sub_u32_e32 v86, v108, v166
	v_pk_fma_f32 v[80:81], v[2:3], v[80:81], v[82:83] op_sel_hi:[0,1,1]
	v_pk_fma_f32 v[78:79], v[2:3], v[78:79], v[80:81] op_sel:[1,0,0]
	v_cmp_lt_i32_e32 vcc, -1, v86
	v_pk_add_f32 v[78:79], v[78:79], 0 op_sel_hi:[1,0]
	s_nop 0
	v_ashrrev_i32_e32 v80, 31, v79
	v_cndmask_b32_e32 v76, 0, v76, vcc
	v_cmp_lt_i32_e32 vcc, 0, v86
	v_ashrrev_i32_e32 v81, 31, v78
	v_or_b32_e32 v80, 0x80000000, v80
	v_cndmask_b32_e32 v77, 0, v77, vcc
	v_or_b32_e32 v81, 0x80000000, v81
	v_xor_b32_e32 v79, v80, v79
	v_cmp_lt_i32_e32 vcc, 2, v86
	v_xor_b32_e32 v78, v81, v78
	s_nop 0
	v_cndmask_b32_e32 v79, 0, v79, vcc
	v_cmp_lt_i32_e32 vcc, 1, v86
	s_nop 1
	v_cndmask_b32_e32 v78, 0, v78, vcc
	ds_write_b128 v165, v[76:79] offset:8512
	s_add_i32 s90, s90, 1
	s_cmp_lt_i32 s90, s33
	s_cbranch_scc1 .LBB0_1609

.LBB0_1726:
	s_sub_u32 s2, s2, 1
	s_cselect_b64 s[20:21], -1, 0
	s_and_b64 s[22:23], s[14:15], s[16:17]
	s_or_b64 s[20:21], s[20:21], s[22:23]
	s_andn2_b64 vcc, exec, s[20:21]
	s_cbranch_vccz .LBB0_1742
.LBB0_1727:
	s_lshl_b32 s19, 1, s2
	s_or_b32 s20, s19, s1
	s_andn2_b64 vcc, exec, s[4:5]
	s_or_b32 s19, s19, s0
	s_cbranch_vccnz .LBB0_1738
	v_cmp_le_u32_e64 s[22:23], s20, v241
	v_cmp_le_u32_e64 s[24:25], s20, v240
	v_cmp_le_u32_e64 s[26:27], s20, v239
	v_cmp_le_u32_e64 s[28:29], s20, v238
	v_cndmask_b32_e64 v247, 0, 1, s[22:23]
	v_cndmask_b32_e64 v246, 0, 1, s[24:25]
	v_cndmask_b32_e64 v249, 0, 1, s[26:27]
	v_cndmask_b32_e64 v248, 0, 1, s[28:29]
	s_nop 0
	v_cmp_le_u32_e64 s[22:23], s19, v211
	v_cmp_le_u32_e64 s[24:25], s19, v108
	v_cmp_le_u32_e64 s[26:27], s19, v107
	v_cmp_le_u32_e64 s[28:29], s19, v106
	v_cndmask_b32_e64 v243, 0, 1, s[22:23]
	v_cndmask_b32_e64 v242, 0, 1, s[24:25]
	v_cndmask_b32_e64 v244, 0, 1, s[26:27]
	v_cndmask_b32_e64 v245, 0, 1, s[28:29]
	s_nop 0
	v_cmp_le_u32_e64 s[22:23], s20, v237
	v_cmp_le_u32_e64 s[24:25], s20, v236
	v_cmp_le_u32_e64 s[26:27], s20, v235
	v_cmp_le_u32_e64 s[28:29], s20, v234
	v_addc_co_u32_e64 v247, s[22:23], v247, 0, s[22:23]
	v_addc_co_u32_e64 v246, s[24:25], v246, 0, s[24:25]
	v_addc_co_u32_e64 v249, s[26:27], v249, 0, s[26:27]
	v_addc_co_u32_e64 v248, s[28:29], v248, 0, s[28:29]
	s_nop 0
	v_cmp_le_u32_e64 s[22:23], s19, v105
	v_cmp_le_u32_e64 s[24:25], s19, v104
	v_cmp_le_u32_e64 s[26:27], s19, v103
	v_cmp_le_u32_e64 s[28:29], s19, v102
	v_addc_co_u32_e64 v243, s[22:23], v243, 0, s[22:23]
	v_addc_co_u32_e64 v242, s[24:25], v242, 0, s[24:25]
	v_addc_co_u32_e64 v244, s[26:27], v244, 0, s[26:27]
	v_addc_co_u32_e64 v245, s[28:29], v245, 0, s[28:29]
	s_andn2_b64 vcc, exec, s[8:9]
	s_cbranch_vccnz .LBB0_1730

.LBB0_1734:
	v_add_u32_e32 v248, v249, v248
	v_add3_u32 v246, v248, v246, v247
	v_add_u32_e32 v242, v244, v242
	v_add3_u32 v242, v242, v245, v243
	v_lshl_add_u32 v246, v242, 16, v246
	s_nop 1
	v_add_u32_dpp v246, v246, v246 quad_perm:[1,0,3,2] row_mask:0xf bank_mask:0xf bound_ctrl:1
	s_nop 1
	v_add_u32_dpp v246, v246, v246 quad_perm:[2,3,0,1] row_mask:0xf bank_mask:0xf bound_ctrl:1
	s_nop 1
	v_add_u32_dpp v246, v246, v246 row_half_mirror row_mask:0xf bank_mask:0xf bound_ctrl:1
	s_nop 1
	v_add_u32_dpp v246, v246, v246 row_mirror row_mask:0xf bank_mask:0xf bound_ctrl:1
	v_mov_b32_e32 v247, v246
	s_nop 1
	v_permlane16_swap_b32_e32 v246, v247
	v_add_u32_e32 v246, v246, v247
	v_mov_b32_e32 v247, v246
	s_nop 1
	v_permlane32_swap_b32_e32 v246, v247
	v_add_u32_e32 v246, v246, v247
	s_nop 0
	v_readfirstlane_b32 s22, v246
	s_lshr_b32 s21, s22, 16
	s_and_b32 s22, s22, 0xffff
	s_cmpk_lt_i32 s22, 0x100
	s_cselect_b64 s[24:25], -1, 0
	s_or_b64 s[24:25], s[14:15], s[24:25]
	s_and_b64 vcc, exec, s[24:25]
	s_cbranch_vccnz .LBB0_1736
	s_cmpk_eq_i32 s22, 0x100
	s_cselect_b64 s[14:15], -1, 0
	s_mov_b32 s3, s22
	s_mov_b32 s1, s20
